# v47 + E/H/I epilogues: f32 tile stores lane-swizzled (permlane16/32 swap) so each store writes 64 contiguous bytes per row
# baseline (speedup 1.0000x reference)
.LBB0_838:
	v_lshl_add_u64 v[178:179], s[88:89], 0, v[196:197]
	s_add_i32 m0, s39, 0xc000
	ds_read_b128 v[146:149], v213
	ds_read_b128 v[150:153], v213 offset:1024
	ds_read_b128 v[154:157], v213 offset:2048
	ds_read_b128 v[158:161], v213 offset:3072
	ds_read_b128 v[162:165], v213 offset:4096
	ds_read_b128 v[166:169], v213 offset:5120
	ds_read_b128 v[170:173], v213 offset:6144
	ds_read_b128 v[174:177], v213 offset:7168
	global_load_lds_dwordx4 v[178:179], off
	s_add_i32 m0, s39, 0xe000
	v_lshl_add_u64 v[178:179], s[88:89], 0, v[198:199]
	global_load_lds_dwordx4 v[178:179], off
	s_waitcnt lgkmcnt(8)
	s_barrier
	s_waitcnt lgkmcnt(0)
	v_mfma_f32_16x16x32_bf16 v[126:129], v[130:133], v[146:149], v[126:129]
	v_mfma_f32_16x16x32_bf16 v[122:125], v[138:141], v[146:149], v[122:125]
	v_mfma_f32_16x16x32_bf16 v[110:113], v[130:133], v[154:157], v[110:113]
	v_mfma_f32_16x16x32_bf16 v[106:109], v[138:141], v[154:157], v[106:109]
	v_mfma_f32_16x16x32_bf16 v[94:97], v[130:133], v[162:165], v[94:97]
	v_mfma_f32_16x16x32_bf16 v[90:93], v[138:141], v[162:165], v[90:93]
	v_mfma_f32_16x16x32_bf16 v[78:81], v[130:133], v[170:173], v[78:81]
	v_mfma_f32_16x16x32_bf16 v[74:77], v[138:141], v[170:173], v[74:77]
	v_mfma_f32_16x16x32_bf16 v[126:129], v[134:137], v[150:153], v[126:129]
	v_mfma_f32_16x16x32_bf16 v[122:125], v[142:145], v[150:153], v[122:125]
	v_mfma_f32_16x16x32_bf16 v[110:113], v[134:137], v[158:161], v[110:113]
	v_mfma_f32_16x16x32_bf16 v[106:109], v[142:145], v[158:161], v[106:109]
	v_mfma_f32_16x16x32_bf16 v[94:97], v[134:137], v[166:169], v[94:97]
	v_mfma_f32_16x16x32_bf16 v[90:93], v[142:145], v[166:169], v[90:93]
	v_mfma_f32_16x16x32_bf16 v[78:81], v[134:137], v[174:177], v[78:81]
	v_mfma_f32_16x16x32_bf16 v[74:77], v[142:145], v[174:177], v[74:77]
	s_barrier
	s_add_i32 s87, 0, 0x14000
	v_add_u32_e32 v186, s87, v212
	s_add_i32 s79, s79, s38
	ds_read_b128 v[178:181], v186
	ds_read_b128 v[182:185], v186 offset:1024
	ds_read_b128 v[200:203], v186 offset:2048
	ds_read_b128 v[204:207], v186 offset:3072
	v_lshl_add_u64 v[186:187], s[90:91], 0, v[0:1]
	s_mov_b32 m0, s79
	v_lshl_add_u64 v[208:209], s[90:91], 0, v[194:195]
	global_load_lds_dwordx4 v[186:187], off
	s_add_i32 m0, s79, 0x2000
	s_nop 0
	global_load_lds_dwordx4 v[208:209], off
	s_barrier
	s_waitcnt lgkmcnt(0)
	v_mfma_f32_16x16x32_bf16 v[118:121], v[178:181], v[146:149], v[118:121]
	v_mfma_f32_16x16x32_bf16 v[114:117], v[200:203], v[146:149], v[114:117]
	v_mfma_f32_16x16x32_bf16 v[102:105], v[178:181], v[154:157], v[102:105]
	v_mfma_f32_16x16x32_bf16 v[98:101], v[200:203], v[154:157], v[98:101]
	v_mfma_f32_16x16x32_bf16 v[86:89], v[178:181], v[162:165], v[86:89]
	v_mfma_f32_16x16x32_bf16 v[82:85], v[200:203], v[162:165], v[82:85]
	v_mfma_f32_16x16x32_bf16 v[70:73], v[178:181], v[170:173], v[70:73]
	v_mfma_f32_16x16x32_bf16 v[66:69], v[200:203], v[170:173], v[66:69]
	v_mfma_f32_16x16x32_bf16 v[118:121], v[182:185], v[150:153], v[118:121]
	v_mfma_f32_16x16x32_bf16 v[114:117], v[204:207], v[150:153], v[114:117]
	v_mfma_f32_16x16x32_bf16 v[102:105], v[182:185], v[158:161], v[102:105]
	v_mfma_f32_16x16x32_bf16 v[98:101], v[204:207], v[158:161], v[98:101]
	v_mfma_f32_16x16x32_bf16 v[86:89], v[182:185], v[166:169], v[86:89]
	v_mfma_f32_16x16x32_bf16 v[82:85], v[204:207], v[166:169], v[82:85]
	v_mfma_f32_16x16x32_bf16 v[70:73], v[182:185], v[174:177], v[70:73]
	v_mfma_f32_16x16x32_bf16 v[66:69], v[204:207], v[174:177], v[66:69]
	s_mov_b32 m0, s39
	v_lshl_add_u64 v[210:211], s[92:93], 0, v[190:191]
	s_barrier
	ds_read_b128 v[146:149], v213 offset:16384
	ds_read_b128 v[150:153], v213 offset:17408
	ds_read_b128 v[154:157], v213 offset:18432
	ds_read_b128 v[158:161], v213 offset:19456
	ds_read_b128 v[162:165], v213 offset:20480
	ds_read_b128 v[166:169], v213 offset:21504
	ds_read_b128 v[170:173], v213 offset:22528
	ds_read_b128 v[174:177], v213 offset:23552
	global_load_lds_dwordx4 v[210:211], off
	s_mov_b32 m0, s42
	v_lshl_add_u64 v[214:215], s[92:93], 0, v[192:193]
	global_load_lds_dwordx4 v[214:215], off
	s_waitcnt vmcnt(10)
	s_barrier
	s_waitcnt lgkmcnt(0)
	v_mfma_f32_16x16x32_bf16 v[62:65], v[130:133], v[146:149], v[62:65]
	v_mfma_f32_16x16x32_bf16 v[58:61], v[138:141], v[146:149], v[58:61]
	v_mfma_f32_16x16x32_bf16 v[46:49], v[130:133], v[154:157], v[46:49]
	v_mfma_f32_16x16x32_bf16 v[42:45], v[138:141], v[154:157], v[42:45]
	v_mfma_f32_16x16x32_bf16 v[30:33], v[130:133], v[162:165], v[30:33]
	v_mfma_f32_16x16x32_bf16 v[26:29], v[138:141], v[162:165], v[26:29]
	v_mfma_f32_16x16x32_bf16 v[14:17], v[130:133], v[170:173], v[14:17]
	v_mfma_f32_16x16x32_bf16 v[10:13], v[138:141], v[170:173], v[10:13]
	v_mfma_f32_16x16x32_bf16 v[62:65], v[134:137], v[150:153], v[62:65]
	v_mfma_f32_16x16x32_bf16 v[58:61], v[142:145], v[150:153], v[58:61]
	v_mfma_f32_16x16x32_bf16 v[46:49], v[134:137], v[158:161], v[46:49]
	v_mfma_f32_16x16x32_bf16 v[42:45], v[142:145], v[158:161], v[42:45]
	v_mfma_f32_16x16x32_bf16 v[30:33], v[134:137], v[166:169], v[30:33]
	v_mfma_f32_16x16x32_bf16 v[26:29], v[142:145], v[166:169], v[26:29]
	v_mfma_f32_16x16x32_bf16 v[14:17], v[134:137], v[174:177], v[14:17]
	v_mfma_f32_16x16x32_bf16 v[10:13], v[142:145], v[174:177], v[10:13]
	s_barrier
	s_add_u32 s88, s90, 0x40000
	s_addc_u32 s89, s91, 0
	s_add_i32 s79, s87, s38
	s_mov_b32 m0, s79
	v_lshl_add_u64 v[130:131], s[88:89], 0, v[0:1]
	global_load_lds_dwordx4 v[130:131], off
	s_add_i32 m0, s79, 0x2000
	v_lshl_add_u64 v[130:131], s[88:89], 0, v[194:195]
	global_load_lds_dwordx4 v[130:131], off
	s_add_i32 s79, 0, 0x18000
	v_add_u32_e32 v142, s79, v212
	ds_read_b128 v[130:133], v142
	ds_read_b128 v[134:137], v142 offset:1024
	ds_read_b128 v[138:141], v142 offset:2048
	ds_read_b128 v[142:145], v142 offset:3072
	s_waitcnt vmcnt(6)
	s_barrier
	v_mfma_f32_16x16x32_bf16 v[54:57], v[178:181], v[146:149], v[54:57]
	v_mfma_f32_16x16x32_bf16 v[50:53], v[200:203], v[146:149], v[50:53]
	v_mfma_f32_16x16x32_bf16 v[38:41], v[178:181], v[154:157], v[38:41]
	v_mfma_f32_16x16x32_bf16 v[34:37], v[200:203], v[154:157], v[34:37]
	v_mfma_f32_16x16x32_bf16 v[22:25], v[178:181], v[162:165], v[22:25]
	v_mfma_f32_16x16x32_bf16 v[18:21], v[200:203], v[162:165], v[18:21]
	v_mfma_f32_16x16x32_bf16 v[6:9], v[178:181], v[170:173], v[6:9]
	v_mfma_f32_16x16x32_bf16 v[2:5], v[200:203], v[170:173], v[2:5]
	v_mfma_f32_16x16x32_bf16 v[54:57], v[182:185], v[150:153], v[54:57]
	v_mfma_f32_16x16x32_bf16 v[50:53], v[204:207], v[150:153], v[50:53]
	v_mfma_f32_16x16x32_bf16 v[38:41], v[182:185], v[158:161], v[38:41]
	v_mfma_f32_16x16x32_bf16 v[34:37], v[204:207], v[158:161], v[34:37]
	v_mfma_f32_16x16x32_bf16 v[22:25], v[182:185], v[166:169], v[22:25]
	v_mfma_f32_16x16x32_bf16 v[18:21], v[204:207], v[166:169], v[18:21]
	v_mfma_f32_16x16x32_bf16 v[6:9], v[182:185], v[174:177], v[6:9]
	v_mfma_f32_16x16x32_bf16 v[2:5], v[204:207], v[174:177], v[2:5]
	s_barrier
	s_add_u32 s88, s92, 0xc0000
	s_addc_u32 s89, s93, 0
	s_mov_b32 m0, s43
	v_lshl_add_u64 v[178:179], s[88:89], 0, v[190:191]
	ds_read_b128 v[146:149], v213 offset:32768
	ds_read_b128 v[150:153], v213 offset:33792
	ds_read_b128 v[154:157], v213 offset:34816
	ds_read_b128 v[158:161], v213 offset:35840
	ds_read_b128 v[162:165], v213 offset:36864
	ds_read_b128 v[166:169], v213 offset:37888
	ds_read_b128 v[170:173], v213 offset:38912
	ds_read_b128 v[174:177], v213 offset:39936
	global_load_lds_dwordx4 v[178:179], off
	s_mov_b32 m0, s44
	v_lshl_add_u64 v[178:179], s[88:89], 0, v[192:193]
	global_load_lds_dwordx4 v[178:179], off
	s_waitcnt lgkmcnt(8)
	s_barrier
	s_waitcnt lgkmcnt(0)
	v_mfma_f32_16x16x32_bf16 v[126:129], v[130:133], v[146:149], v[126:129]
	v_mfma_f32_16x16x32_bf16 v[122:125], v[138:141], v[146:149], v[122:125]
	v_mfma_f32_16x16x32_bf16 v[110:113], v[130:133], v[154:157], v[110:113]
	v_mfma_f32_16x16x32_bf16 v[106:109], v[138:141], v[154:157], v[106:109]
	v_mfma_f32_16x16x32_bf16 v[94:97], v[130:133], v[162:165], v[94:97]
	v_mfma_f32_16x16x32_bf16 v[90:93], v[138:141], v[162:165], v[90:93]
	v_mfma_f32_16x16x32_bf16 v[78:81], v[130:133], v[170:173], v[78:81]
	v_mfma_f32_16x16x32_bf16 v[74:77], v[138:141], v[170:173], v[74:77]
	v_mfma_f32_16x16x32_bf16 v[126:129], v[134:137], v[150:153], v[126:129]
	v_mfma_f32_16x16x32_bf16 v[122:125], v[142:145], v[150:153], v[122:125]
	v_mfma_f32_16x16x32_bf16 v[110:113], v[134:137], v[158:161], v[110:113]
	v_mfma_f32_16x16x32_bf16 v[106:109], v[142:145], v[158:161], v[106:109]
	v_mfma_f32_16x16x32_bf16 v[94:97], v[134:137], v[166:169], v[94:97]
	v_mfma_f32_16x16x32_bf16 v[90:93], v[142:145], v[166:169], v[90:93]
	v_mfma_f32_16x16x32_bf16 v[78:81], v[134:137], v[174:177], v[78:81]
	v_mfma_f32_16x16x32_bf16 v[74:77], v[142:145], v[174:177], v[74:77]
	s_barrier
	s_add_i32 s87, 0, 0x1c000
	s_add_i32 s79, s79, s38
	v_add_u32_e32 v204, s87, v212
	v_lshl_add_u64 v[186:187], v[186:187], 0, s[40:41]
	s_mov_b32 m0, s79
	ds_read_b128 v[178:181], v204
	ds_read_b128 v[182:185], v204 offset:1024
	ds_read_b128 v[200:203], v204 offset:2048
	ds_read_b128 v[204:207], v204 offset:3072
	global_load_lds_dwordx4 v[186:187], off
	s_add_i32 m0, s79, 0x2000
	v_lshl_add_u64 v[186:187], v[208:209], 0, s[40:41]
	global_load_lds_dwordx4 v[186:187], off
	s_barrier
	s_waitcnt lgkmcnt(0)
	v_mfma_f32_16x16x32_bf16 v[118:121], v[178:181], v[146:149], v[118:121]
	v_mfma_f32_16x16x32_bf16 v[114:117], v[200:203], v[146:149], v[114:117]
	v_mfma_f32_16x16x32_bf16 v[102:105], v[178:181], v[154:157], v[102:105]
	v_mfma_f32_16x16x32_bf16 v[98:101], v[200:203], v[154:157], v[98:101]
	v_mfma_f32_16x16x32_bf16 v[86:89], v[178:181], v[162:165], v[86:89]
	v_mfma_f32_16x16x32_bf16 v[82:85], v[200:203], v[162:165], v[82:85]
	v_mfma_f32_16x16x32_bf16 v[70:73], v[178:181], v[170:173], v[70:73]
	v_mfma_f32_16x16x32_bf16 v[66:69], v[200:203], v[170:173], v[66:69]
	v_mfma_f32_16x16x32_bf16 v[118:121], v[182:185], v[150:153], v[118:121]
	v_mfma_f32_16x16x32_bf16 v[114:117], v[204:207], v[150:153], v[114:117]
	v_mfma_f32_16x16x32_bf16 v[102:105], v[182:185], v[158:161], v[102:105]
	v_mfma_f32_16x16x32_bf16 v[98:101], v[204:207], v[158:161], v[98:101]
	v_mfma_f32_16x16x32_bf16 v[86:89], v[182:185], v[166:169], v[86:89]
	v_mfma_f32_16x16x32_bf16 v[82:85], v[204:207], v[166:169], v[82:85]
	v_mfma_f32_16x16x32_bf16 v[70:73], v[182:185], v[174:177], v[70:73]
	v_mfma_f32_16x16x32_bf16 v[66:69], v[204:207], v[174:177], v[66:69]
	s_mov_b32 m0, s60
	v_lshl_add_u64 v[186:187], v[210:211], 0, s[40:41]
	s_barrier
	ds_read_b128 v[146:149], v213 offset:49152
	ds_read_b128 v[150:153], v213 offset:50176
	ds_read_b128 v[154:157], v213 offset:51200
	ds_read_b128 v[158:161], v213 offset:52224
	ds_read_b128 v[162:165], v213 offset:53248
	ds_read_b128 v[166:169], v213 offset:54272
	ds_read_b128 v[170:173], v213 offset:55296
	ds_read_b128 v[174:177], v213 offset:56320
	global_load_lds_dwordx4 v[186:187], off
	s_mov_b32 m0, s61
	v_lshl_add_u64 v[186:187], v[214:215], 0, s[40:41]
	global_load_lds_dwordx4 v[186:187], off
	s_waitcnt vmcnt(10)
	s_barrier
	s_waitcnt lgkmcnt(0)
	v_mfma_f32_16x16x32_bf16 v[62:65], v[130:133], v[146:149], v[62:65]
	v_mfma_f32_16x16x32_bf16 v[58:61], v[138:141], v[146:149], v[58:61]
	v_mfma_f32_16x16x32_bf16 v[46:49], v[130:133], v[154:157], v[46:49]
	v_mfma_f32_16x16x32_bf16 v[42:45], v[138:141], v[154:157], v[42:45]
	v_mfma_f32_16x16x32_bf16 v[30:33], v[130:133], v[162:165], v[30:33]
	v_mfma_f32_16x16x32_bf16 v[26:29], v[138:141], v[162:165], v[26:29]
	v_mfma_f32_16x16x32_bf16 v[14:17], v[130:133], v[170:173], v[14:17]
	v_mfma_f32_16x16x32_bf16 v[10:13], v[138:141], v[170:173], v[10:13]
	v_mfma_f32_16x16x32_bf16 v[62:65], v[134:137], v[150:153], v[62:65]
	v_mfma_f32_16x16x32_bf16 v[58:61], v[142:145], v[150:153], v[58:61]
	v_mfma_f32_16x16x32_bf16 v[46:49], v[134:137], v[158:161], v[46:49]
	v_mfma_f32_16x16x32_bf16 v[42:45], v[142:145], v[158:161], v[42:45]
	v_mfma_f32_16x16x32_bf16 v[30:33], v[134:137], v[166:169], v[30:33]
	v_mfma_f32_16x16x32_bf16 v[26:29], v[142:145], v[166:169], v[26:29]
	v_mfma_f32_16x16x32_bf16 v[14:17], v[134:137], v[174:177], v[14:17]
	v_mfma_f32_16x16x32_bf16 v[10:13], v[142:145], v[174:177], v[10:13]
	s_barrier
	s_add_u32 s88, s90, 0x40080
	s_addc_u32 s89, s91, 0
	s_add_i32 s79, s87, s38
	s_mov_b32 m0, s79
	v_lshl_add_u64 v[130:131], s[88:89], 0, v[0:1]
	global_load_lds_dwordx4 v[130:131], off
	s_add_i32 m0, s79, 0x2000
	v_lshl_add_u64 v[130:131], s[88:89], 0, v[194:195]
	global_load_lds_dwordx4 v[130:131], off
	s_add_i32 s79, 0, 0x10000
	v_add_u32_e32 v142, s79, v212
	ds_read_b128 v[130:133], v142
	ds_read_b128 v[134:137], v142 offset:1024
	ds_read_b128 v[138:141], v142 offset:2048
	ds_read_b128 v[142:145], v142 offset:3072
	s_waitcnt vmcnt(6)
	s_barrier
	v_mfma_f32_16x16x32_bf16 v[54:57], v[178:181], v[146:149], v[54:57]
	v_mfma_f32_16x16x32_bf16 v[50:53], v[200:203], v[146:149], v[50:53]
	v_mfma_f32_16x16x32_bf16 v[38:41], v[178:181], v[154:157], v[38:41]
	v_mfma_f32_16x16x32_bf16 v[34:37], v[200:203], v[154:157], v[34:37]
	v_mfma_f32_16x16x32_bf16 v[22:25], v[178:181], v[162:165], v[22:25]
	v_mfma_f32_16x16x32_bf16 v[18:21], v[200:203], v[162:165], v[18:21]
	v_mfma_f32_16x16x32_bf16 v[6:9], v[178:181], v[170:173], v[6:9]
	v_mfma_f32_16x16x32_bf16 v[2:5], v[200:203], v[170:173], v[2:5]
	v_mfma_f32_16x16x32_bf16 v[54:57], v[182:185], v[150:153], v[54:57]
	v_mfma_f32_16x16x32_bf16 v[50:53], v[204:207], v[150:153], v[50:53]
	v_mfma_f32_16x16x32_bf16 v[38:41], v[182:185], v[158:161], v[38:41]
	v_mfma_f32_16x16x32_bf16 v[34:37], v[204:207], v[158:161], v[34:37]
	v_mfma_f32_16x16x32_bf16 v[22:25], v[182:185], v[166:169], v[22:25]
	v_mfma_f32_16x16x32_bf16 v[18:21], v[204:207], v[166:169], v[18:21]
	v_mfma_f32_16x16x32_bf16 v[6:9], v[182:185], v[174:177], v[6:9]
	v_mfma_f32_16x16x32_bf16 v[2:5], v[204:207], v[174:177], v[2:5]
	s_add_i32 s78, s78, 2
	s_add_u32 s34, s34, 0x100
	s_addc_u32 s75, s75, 0
	s_mov_b64 s[88:89], s[4:5]
	s_add_u32 s4, s88, 0x100
	s_addc_u32 s5, s89, 0
	s_cmp_eq_u32 s78, 12
	s_cselect_b32 s93, s17, s5
	s_cselect_b32 s92, s16, s4
	s_cselect_b32 s91, s15, s75
	s_cselect_b32 s90, s23, s34
	s_cmp_gt_u32 s78, 13
	s_barrier
	s_cbranch_scc0 .LBB0_838
	v_bfe_u32 v189, v252, 4, 2
	v_lshlrev_b32_e32 v189, 4, v189
	s_waitcnt lgkmcnt(0)
	s_lshl_b32 s4, s22, 8
	v_mov_b32_e32 v186, v252
	s_add_i32 s4, s4, s47
	s_nop 0
	v_and_or_b32 v202, v186, 15, s4
	s_lshl_b32 s4, s86, 8
	s_or_b32 s4, s4, s55
	v_lshrrev_b32_e32 v130, 1, v186
	v_and_or_b32 v200, v130, 24, s4
	v_ashrrev_i32_e32 v201, 31, v200
	v_ashrrev_i32_e32 v203, 31, v202
	v_lshl_add_u64 v[204:205], v[200:201], 2, s[6:7]
	v_lshlrev_b64 v[130:131], 12, v[202:203]
	v_lshl_add_u64 v[130:131], v[204:205], 0, v[130:131]
	global_load_dwordx4 v[216:219], v[130:131], off offset:16
	global_load_dwordx4 v[220:223], v[130:131], off
	global_load_dwordx4 v[178:181], v[130:131], off offset:528
	global_load_dwordx4 v[182:185], v[130:131], off offset:512
	v_or_b32_e32 v210, 16, v202
	v_ashrrev_i32_e32 v211, 31, v210
	v_lshlrev_b64 v[130:131], 12, v[210:211]
	v_or_b32_e32 v208, 32, v202
	v_lshl_add_u64 v[130:131], v[204:205], 0, v[130:131]
	v_ashrrev_i32_e32 v209, 31, v208
	global_load_dwordx4 v[170:173], v[130:131], off offset:16
	global_load_dwordx4 v[174:177], v[130:131], off
	global_load_dwordx4 v[162:165], v[130:131], off offset:528
	global_load_dwordx4 v[166:169], v[130:131], off offset:512
	v_lshlrev_b64 v[130:131], 12, v[208:209]
	v_or_b32_e32 v206, 48, v202
	v_lshl_add_u64 v[130:131], v[204:205], 0, v[130:131]
	v_ashrrev_i32_e32 v207, 31, v206
	global_load_dwordx4 v[154:157], v[130:131], off offset:16
	global_load_dwordx4 v[158:161], v[130:131], off
	global_load_dwordx4 v[138:141], v[130:131], off offset:528
	global_load_dwordx4 v[142:145], v[130:131], off offset:512
	v_lshlrev_b64 v[130:131], 12, v[206:207]
	v_lshl_add_u64 v[134:135], v[204:205], 0, v[130:131]
	global_load_dwordx4 v[146:149], v[134:135], off offset:16
	global_load_dwordx4 v[150:153], v[134:135], off
	global_load_dwordx4 v[130:133], v[134:135], off offset:528
	s_nop 0
	global_load_dwordx4 v[134:137], v[134:135], off offset:512
	v_and_b32_e32 v186, 63, v186
	v_lshlrev_b32_e32 v187, 2, v186
	v_xor_b32_e32 v215, 64, v187
	v_xor_b32_e32 v214, 0x80, v187
	v_cmp_gt_u32_e32 vcc, 16, v186
	v_lshlrev_b64 v[186:187], 10, v[202:203]
	v_lshl_add_u64 v[186:187], v[186:187], 0, v[200:201]
	s_lshl_b32 s4, s86, 2
	s_ashr_i32 s5, s4, 31
	s_waitcnt vmcnt(0)
	v_pk_add_f32 v[124:125], v[124:125], v[218:219]
	v_pk_add_f32 v[128:129], v[128:129], v[222:223]
	v_pk_add_f32 v[126:127], v[126:127], v[220:221]
	v_pk_mul_f32 v[218:219], v[128:129], v[128:129]
	v_pk_mul_f32 v[220:221], v[126:127], v[126:127]
	v_pk_add_f32 v[122:123], v[122:123], v[216:217]
	v_lshl_add_u64 v[216:217], v[186:187], 2, s[12:13]
	v_add_f32_e32 v220, v220, v221
	v_add_f32_e32 v218, v218, v219
	s_nop 1
	v_permlane16_swap_b32_e32 v126, v122
	v_permlane16_swap_b32_e32 v127, v123
	v_permlane16_swap_b32_e32 v128, v124
	v_permlane16_swap_b32_e32 v129, v125
	v_permlane32_swap_b32_e32 v126, v122
	v_permlane32_swap_b32_e32 v127, v123
	v_permlane32_swap_b32_e32 v128, v124
	v_permlane32_swap_b32_e32 v129, v125
	v_sub_co_u32_e64 v232, s[98:99], v216, v189
	v_subbrev_co_u32_e64 v233, s[98:99], 0, v217, s[98:99]
	global_store_dwordx4 v[232:233], v[126:129], off
	global_store_dwordx4 v[232:233], v[122:125], off offset:64
	s_nop 1
	v_permlane32_swap_b32_e32 v126, v122
	v_permlane32_swap_b32_e32 v127, v123
	v_permlane32_swap_b32_e32 v128, v124
	v_permlane32_swap_b32_e32 v129, v125
	v_permlane16_swap_b32_e32 v126, v122
	v_permlane16_swap_b32_e32 v127, v123
	v_permlane16_swap_b32_e32 v128, v124
	v_permlane16_swap_b32_e32 v129, v125
	v_add_f32_e32 v222, v220, v218
	v_pk_mul_f32 v[220:221], v[122:123], v[122:123]
	v_cvt_pk_bf16_f32 v126, v126, v127
	v_cvt_pk_bf16_f32 v127, v128, v129
	v_cvt_pk_bf16_f32 v128, v122, v123
	v_cvt_pk_bf16_f32 v129, v124, v125
	v_lshl_add_u64 v[122:123], v[186:187], 1, s[8:9]
	v_pk_add_f32 v[120:121], v[120:121], v[184:185]
	v_pk_add_f32 v[118:119], v[118:119], v[182:183]
	v_pk_mul_f32 v[218:219], v[124:125], v[124:125]
	global_store_dwordx4 v[122:123], v[126:129], off
	v_pk_mul_f32 v[124:125], v[120:121], v[120:121]
	v_pk_add_f32 v[116:117], v[116:117], v[180:181]
	v_pk_mul_f32 v[126:127], v[118:119], v[118:119]
	v_pk_add_f32 v[114:115], v[114:115], v[178:179]
	v_add_f32_e32 v126, v126, v127
	v_add_f32_e32 v124, v124, v125
	v_add_f32_e32 v128, v126, v124
	v_pk_mul_f32 v[124:125], v[116:117], v[116:117]
	v_pk_mul_f32 v[126:127], v[114:115], v[114:115]
	v_add_f32_e32 v220, v220, v221
	v_add_f32_e32 v218, v218, v219
	v_add_f32_e32 v126, v126, v127
	v_add_f32_e32 v124, v124, v125
	v_add_f32_e32 v218, v220, v218
	v_add_f32_e32 v124, v126, v124
	v_add_f32_e32 v218, v222, v218
	v_add_f32_e32 v124, v128, v124
	v_add_f32_e32 v124, v218, v124
	s_nop 1
	v_permlane16_swap_b32_e32 v118, v114
	v_permlane16_swap_b32_e32 v119, v115
	v_permlane16_swap_b32_e32 v120, v116
	v_permlane16_swap_b32_e32 v121, v117
	v_permlane32_swap_b32_e32 v118, v114
	v_permlane32_swap_b32_e32 v119, v115
	v_permlane32_swap_b32_e32 v120, v116
	v_permlane32_swap_b32_e32 v121, v117
	v_sub_co_u32_e64 v232, s[98:99], v216, v189
	v_subbrev_co_u32_e64 v233, s[98:99], 0, v217, s[98:99]
	global_store_dwordx4 v[232:233], v[118:121], off offset:512
	global_store_dwordx4 v[232:233], v[114:117], off offset:576
	s_nop 1
	v_permlane32_swap_b32_e32 v118, v114
	v_permlane32_swap_b32_e32 v119, v115
	v_permlane32_swap_b32_e32 v120, v116
	v_permlane32_swap_b32_e32 v121, v117
	v_permlane16_swap_b32_e32 v118, v114
	v_permlane16_swap_b32_e32 v119, v115
	v_permlane16_swap_b32_e32 v120, v116
	v_permlane16_swap_b32_e32 v121, v117
	s_nop 0
	v_cvt_pk_bf16_f32 v118, v118, v119
	v_cvt_pk_bf16_f32 v119, v120, v121
	v_cvt_pk_bf16_f32 v120, v114, v115
	ds_bpermute_b32 v114, v215, v124
	v_cvt_pk_bf16_f32 v121, v116, v117
	global_store_dwordx4 v[122:123], v[118:121], off offset:256
	s_waitcnt lgkmcnt(0)
	v_add_f32_e32 v114, v124, v114
	ds_bpermute_b32 v115, v214, v114
	s_and_saveexec_b64 s[22:23], vcc
	s_cbranch_execz .LBB0_841
	v_lshlrev_b64 v[116:117], 6, v[202:203]
	v_lshl_add_u64 v[116:117], s[10:11], 0, v[116:117]
	v_lshl_add_u64 v[116:117], s[4:5], 2, v[116:117]
	s_lshl_b32 s34, s45, 2
	v_lshl_add_u64 v[116:117], v[116:117], 0, s[34:35]
	s_waitcnt lgkmcnt(0)
	v_add_f32_e32 v114, v114, v115
	global_store_dword v[116:117], v114, off
.LBB0_841:
	s_or_b64 exec, exec, s[22:23]
	s_waitcnt lgkmcnt(0)
	v_lshlrev_b64 v[114:115], 10, v[210:211]
	v_pk_add_f32 v[112:113], v[112:113], v[176:177]
	v_pk_add_f32 v[110:111], v[110:111], v[174:175]
	v_lshl_add_u64 v[114:115], v[114:115], 0, v[200:201]
	v_pk_mul_f32 v[118:119], v[112:113], v[112:113]
	v_pk_mul_f32 v[120:121], v[110:111], v[110:111]
	v_pk_add_f32 v[108:109], v[108:109], v[172:173]
	v_pk_add_f32 v[106:107], v[106:107], v[170:171]
	v_lshl_add_u64 v[116:117], v[114:115], 2, s[12:13]
	v_add_f32_e32 v120, v120, v121
	v_add_f32_e32 v118, v118, v119
	v_pk_add_f32 v[104:105], v[104:105], v[168:169]
	v_pk_add_f32 v[102:103], v[102:103], v[166:167]
	s_nop 1
	v_permlane16_swap_b32_e32 v110, v106
	v_permlane16_swap_b32_e32 v111, v107
	v_permlane16_swap_b32_e32 v112, v108
	v_permlane16_swap_b32_e32 v113, v109
	v_permlane32_swap_b32_e32 v110, v106
	v_permlane32_swap_b32_e32 v111, v107
	v_permlane32_swap_b32_e32 v112, v108
	v_permlane32_swap_b32_e32 v113, v109
	v_sub_co_u32_e64 v232, s[98:99], v116, v189
	v_subbrev_co_u32_e64 v233, s[98:99], 0, v117, s[98:99]
	global_store_dwordx4 v[232:233], v[110:113], off
	global_store_dwordx4 v[232:233], v[106:109], off offset:64
	s_nop 1
	v_permlane32_swap_b32_e32 v110, v106
	v_permlane32_swap_b32_e32 v111, v107
	v_permlane32_swap_b32_e32 v112, v108
	v_permlane32_swap_b32_e32 v113, v109
	v_permlane16_swap_b32_e32 v110, v106
	v_permlane16_swap_b32_e32 v111, v107
	v_permlane16_swap_b32_e32 v112, v108
	v_permlane16_swap_b32_e32 v113, v109
	v_add_f32_e32 v122, v120, v118
	v_pk_mul_f32 v[118:119], v[108:109], v[108:109]
	v_pk_mul_f32 v[120:121], v[106:107], v[106:107]
	v_cvt_pk_bf16_f32 v110, v110, v111
	v_cvt_pk_bf16_f32 v111, v112, v113
	v_cvt_pk_bf16_f32 v112, v106, v107
	v_cvt_pk_bf16_f32 v113, v108, v109
	v_pk_add_f32 v[108:109], v[100:101], v[164:165]
	v_pk_add_f32 v[106:107], v[98:99], v[162:163]
	v_pk_mul_f32 v[98:99], v[104:105], v[104:105]
	v_pk_mul_f32 v[100:101], v[102:103], v[102:103]
	v_add_f32_e32 v98, v98, v99
	v_add_f32_e32 v100, v100, v101
	v_add_f32_e32 v118, v118, v119
	v_add_f32_e32 v119, v100, v98
	v_pk_mul_f32 v[98:99], v[108:109], v[108:109]
	v_pk_mul_f32 v[100:101], v[106:107], v[106:107]
	v_add_f32_e32 v120, v120, v121
	v_add_f32_e32 v100, v100, v101
	v_add_f32_e32 v98, v98, v99
	v_add_f32_e32 v118, v120, v118
	v_add_f32_e32 v98, v100, v98
	v_add_f32_e32 v118, v122, v118
	v_add_f32_e32 v98, v119, v98
	v_add_f32_e32 v98, v118, v98
	ds_bpermute_b32 v99, v215, v98
	v_lshl_add_u64 v[114:115], v[114:115], 1, s[8:9]
	global_store_dwordx4 v[114:115], v[110:113], off
	s_nop 1
	v_permlane16_swap_b32_e32 v102, v106
	v_permlane16_swap_b32_e32 v103, v107
	v_permlane16_swap_b32_e32 v104, v108
	v_permlane16_swap_b32_e32 v105, v109
	v_permlane32_swap_b32_e32 v102, v106
	v_permlane32_swap_b32_e32 v103, v107
	v_permlane32_swap_b32_e32 v104, v108
	v_permlane32_swap_b32_e32 v105, v109
	v_sub_co_u32_e64 v232, s[98:99], v116, v189
	v_subbrev_co_u32_e64 v233, s[98:99], 0, v117, s[98:99]
	global_store_dwordx4 v[232:233], v[102:105], off offset:512
	global_store_dwordx4 v[232:233], v[106:109], off offset:576
	s_nop 1
	v_permlane32_swap_b32_e32 v102, v106
	v_permlane32_swap_b32_e32 v103, v107
	v_permlane32_swap_b32_e32 v104, v108
	v_permlane32_swap_b32_e32 v105, v109
	v_permlane16_swap_b32_e32 v102, v106
	v_permlane16_swap_b32_e32 v103, v107
	v_permlane16_swap_b32_e32 v104, v108
	v_permlane16_swap_b32_e32 v105, v109
	v_cvt_pk_bf16_f32 v100, v102, v103
	v_cvt_pk_bf16_f32 v101, v104, v105
	s_waitcnt lgkmcnt(0)
	v_add_f32_e32 v98, v98, v99
	ds_bpermute_b32 v99, v214, v98
	v_cvt_pk_bf16_f32 v102, v106, v107
	v_cvt_pk_bf16_f32 v103, v108, v109
	global_store_dwordx4 v[114:115], v[100:103], off offset:256
	s_and_saveexec_b64 s[22:23], vcc
	s_cbranch_execz .LBB0_843
	v_lshlrev_b64 v[100:101], 6, v[210:211]
	v_lshl_add_u64 v[100:101], s[10:11], 0, v[100:101]
	v_lshl_add_u64 v[100:101], s[4:5], 2, v[100:101]
	s_lshl_b32 s34, s45, 2
	v_lshl_add_u64 v[100:101], v[100:101], 0, s[34:35]
	s_waitcnt lgkmcnt(0)
	v_add_f32_e32 v98, v98, v99
	global_store_dword v[100:101], v98, off
.LBB0_843:
	s_or_b64 exec, exec, s[22:23]
	v_add_u32_e32 v164, 0x80, v202
	v_ashrrev_i32_e32 v165, 31, v164
	s_waitcnt lgkmcnt(0)
	v_lshlrev_b64 v[98:99], 12, v[164:165]
	v_add_u32_e32 v162, 0x90, v202
	v_lshl_add_u64 v[98:99], v[204:205], 0, v[98:99]
	v_ashrrev_i32_e32 v163, 31, v162
	global_load_dwordx4 v[122:125], v[98:99], off offset:16
	global_load_dwordx4 v[126:129], v[98:99], off
	global_load_dwordx4 v[114:117], v[98:99], off offset:528
	global_load_dwordx4 v[118:121], v[98:99], off offset:512
	v_lshlrev_b64 v[98:99], 12, v[162:163]
	v_lshl_add_u64 v[102:103], v[204:205], 0, v[98:99]
	global_load_dwordx4 v[106:109], v[102:103], off offset:16
	global_load_dwordx4 v[110:113], v[102:103], off
	global_load_dwordx4 v[98:101], v[102:103], off offset:528
	s_nop 0
	global_load_dwordx4 v[102:105], v[102:103], off offset:512
	v_lshlrev_b64 v[166:167], 10, v[208:209]
	v_pk_add_f32 v[96:97], v[96:97], v[160:161]
	v_pk_add_f32 v[94:95], v[94:95], v[158:159]
	v_lshl_add_u64 v[166:167], v[166:167], 0, v[200:201]
	v_pk_add_f32 v[92:93], v[92:93], v[156:157]
	v_pk_mul_f32 v[156:157], v[96:97], v[96:97]
	v_pk_mul_f32 v[158:159], v[94:95], v[94:95]
	v_pk_add_f32 v[90:91], v[90:91], v[154:155]
	v_lshl_add_u64 v[154:155], v[166:167], 2, s[12:13]
	v_add_f32_e32 v158, v158, v159
	v_add_f32_e32 v156, v156, v157
	v_pk_add_f32 v[88:89], v[88:89], v[144:145]
	v_pk_add_f32 v[86:87], v[86:87], v[142:143]
	s_nop 1
	v_permlane16_swap_b32_e32 v94, v90
	v_permlane16_swap_b32_e32 v95, v91
	v_permlane16_swap_b32_e32 v96, v92
	v_permlane16_swap_b32_e32 v97, v93
	v_permlane32_swap_b32_e32 v94, v90
	v_permlane32_swap_b32_e32 v95, v91
	v_permlane32_swap_b32_e32 v96, v92
	v_permlane32_swap_b32_e32 v97, v93
	v_sub_co_u32_e64 v232, s[98:99], v154, v189
	v_subbrev_co_u32_e64 v233, s[98:99], 0, v155, s[98:99]
	global_store_dwordx4 v[232:233], v[94:97], off
	global_store_dwordx4 v[232:233], v[90:93], off offset:64
	s_nop 1
	v_permlane32_swap_b32_e32 v94, v90
	v_permlane32_swap_b32_e32 v95, v91
	v_permlane32_swap_b32_e32 v96, v92
	v_permlane32_swap_b32_e32 v97, v93
	v_permlane16_swap_b32_e32 v94, v90
	v_permlane16_swap_b32_e32 v95, v91
	v_permlane16_swap_b32_e32 v96, v92
	v_permlane16_swap_b32_e32 v97, v93
	v_add_f32_e32 v160, v158, v156
	v_pk_mul_f32 v[156:157], v[92:93], v[92:93]
	v_pk_mul_f32 v[158:159], v[90:91], v[90:91]
	v_cvt_pk_bf16_f32 v94, v94, v95
	v_cvt_pk_bf16_f32 v95, v96, v97
	v_cvt_pk_bf16_f32 v96, v90, v91
	v_cvt_pk_bf16_f32 v97, v92, v93
	v_pk_add_f32 v[92:93], v[84:85], v[140:141]
	v_pk_add_f32 v[90:91], v[82:83], v[138:139]
	v_pk_mul_f32 v[82:83], v[88:89], v[88:89]
	v_pk_mul_f32 v[84:85], v[86:87], v[86:87]
	v_add_f32_e32 v82, v82, v83
	v_add_f32_e32 v84, v84, v85
	v_add_f32_e32 v138, v84, v82
	v_pk_mul_f32 v[82:83], v[92:93], v[92:93]
	v_pk_mul_f32 v[84:85], v[90:91], v[90:91]
	v_add_f32_e32 v158, v158, v159
	v_add_f32_e32 v156, v156, v157
	v_add_f32_e32 v84, v84, v85
	v_add_f32_e32 v82, v82, v83
	v_add_f32_e32 v156, v158, v156
	v_add_f32_e32 v82, v84, v82
	v_add_f32_e32 v158, v160, v156
	v_add_f32_e32 v82, v138, v82
	v_add_f32_e32 v82, v158, v82
	ds_bpermute_b32 v83, v215, v82
	v_lshl_add_u64 v[156:157], v[166:167], 1, s[8:9]
	global_store_dwordx4 v[156:157], v[94:97], off
	s_nop 1
	v_permlane16_swap_b32_e32 v86, v90
	v_permlane16_swap_b32_e32 v87, v91
	v_permlane16_swap_b32_e32 v88, v92
	v_permlane16_swap_b32_e32 v89, v93
	v_permlane32_swap_b32_e32 v86, v90
	v_permlane32_swap_b32_e32 v87, v91
	v_permlane32_swap_b32_e32 v88, v92
	v_permlane32_swap_b32_e32 v89, v93
	v_sub_co_u32_e64 v232, s[98:99], v154, v189
	v_subbrev_co_u32_e64 v233, s[98:99], 0, v155, s[98:99]
	global_store_dwordx4 v[232:233], v[86:89], off offset:512
	global_store_dwordx4 v[232:233], v[90:93], off offset:576
	s_nop 1
	v_permlane32_swap_b32_e32 v86, v90
	v_permlane32_swap_b32_e32 v87, v91
	v_permlane32_swap_b32_e32 v88, v92
	v_permlane32_swap_b32_e32 v89, v93
	v_permlane16_swap_b32_e32 v86, v90
	v_permlane16_swap_b32_e32 v87, v91
	v_permlane16_swap_b32_e32 v88, v92
	v_permlane16_swap_b32_e32 v89, v93
	v_cvt_pk_bf16_f32 v84, v86, v87
	v_cvt_pk_bf16_f32 v85, v88, v89
	s_waitcnt lgkmcnt(0)
	v_add_f32_e32 v82, v82, v83
	ds_bpermute_b32 v83, v214, v82
	v_cvt_pk_bf16_f32 v86, v90, v91
	v_cvt_pk_bf16_f32 v87, v92, v93
	global_store_dwordx4 v[156:157], v[84:87], off offset:256
	s_and_saveexec_b64 s[22:23], vcc
	s_cbranch_execz .LBB0_845
	v_lshlrev_b64 v[84:85], 6, v[208:209]
	v_lshl_add_u64 v[84:85], s[10:11], 0, v[84:85]
	v_lshl_add_u64 v[84:85], s[4:5], 2, v[84:85]
	s_lshl_b32 s34, s45, 2
	v_lshl_add_u64 v[84:85], v[84:85], 0, s[34:35]
	s_waitcnt lgkmcnt(0)
	v_add_f32_e32 v82, v82, v83
	global_store_dword v[84:85], v82, off
.LBB0_845:
	s_or_b64 exec, exec, s[22:23]
	s_waitcnt lgkmcnt(0)
	v_lshlrev_b64 v[82:83], 10, v[206:207]
	v_pk_add_f32 v[80:81], v[80:81], v[152:153]
	v_pk_add_f32 v[78:79], v[78:79], v[150:151]
	v_lshl_add_u64 v[82:83], v[82:83], 0, v[200:201]
	v_pk_mul_f32 v[86:87], v[80:81], v[80:81]
	v_pk_mul_f32 v[88:89], v[78:79], v[78:79]
	v_pk_add_f32 v[76:77], v[76:77], v[148:149]
	v_pk_add_f32 v[74:75], v[74:75], v[146:147]
	v_lshl_add_u64 v[84:85], v[82:83], 2, s[12:13]
	v_add_f32_e32 v88, v88, v89
	v_add_f32_e32 v86, v86, v87
	v_pk_add_f32 v[72:73], v[72:73], v[136:137]
	v_pk_add_f32 v[70:71], v[70:71], v[134:135]
	s_nop 1
	v_permlane16_swap_b32_e32 v78, v74
	v_permlane16_swap_b32_e32 v79, v75
	v_permlane16_swap_b32_e32 v80, v76
	v_permlane16_swap_b32_e32 v81, v77
	v_permlane32_swap_b32_e32 v78, v74
	v_permlane32_swap_b32_e32 v79, v75
	v_permlane32_swap_b32_e32 v80, v76
	v_permlane32_swap_b32_e32 v81, v77
	v_sub_co_u32_e64 v232, s[98:99], v84, v189
	v_subbrev_co_u32_e64 v233, s[98:99], 0, v85, s[98:99]
	global_store_dwordx4 v[232:233], v[78:81], off
	global_store_dwordx4 v[232:233], v[74:77], off offset:64
	s_nop 1
	v_permlane32_swap_b32_e32 v78, v74
	v_permlane32_swap_b32_e32 v79, v75
	v_permlane32_swap_b32_e32 v80, v76
	v_permlane32_swap_b32_e32 v81, v77
	v_permlane16_swap_b32_e32 v78, v74
	v_permlane16_swap_b32_e32 v79, v75
	v_permlane16_swap_b32_e32 v80, v76
	v_permlane16_swap_b32_e32 v81, v77
	v_add_f32_e32 v90, v88, v86
	v_pk_mul_f32 v[86:87], v[76:77], v[76:77]
	v_pk_mul_f32 v[88:89], v[74:75], v[74:75]
	v_cvt_pk_bf16_f32 v78, v78, v79
	v_cvt_pk_bf16_f32 v79, v80, v81
	v_cvt_pk_bf16_f32 v80, v74, v75
	v_cvt_pk_bf16_f32 v81, v76, v77
	v_pk_add_f32 v[76:77], v[68:69], v[132:133]
	v_pk_add_f32 v[74:75], v[66:67], v[130:131]
	v_pk_mul_f32 v[66:67], v[72:73], v[72:73]
	v_pk_mul_f32 v[68:69], v[70:71], v[70:71]
	v_add_f32_e32 v66, v66, v67
	v_add_f32_e32 v68, v68, v69
	v_add_f32_e32 v86, v86, v87
	v_add_f32_e32 v87, v68, v66
	v_pk_mul_f32 v[66:67], v[76:77], v[76:77]
	v_pk_mul_f32 v[68:69], v[74:75], v[74:75]
	v_add_f32_e32 v88, v88, v89
	v_add_f32_e32 v68, v68, v69
	v_add_f32_e32 v66, v66, v67
	v_add_f32_e32 v86, v88, v86
	v_add_f32_e32 v66, v68, v66
	v_add_f32_e32 v86, v90, v86
	v_add_f32_e32 v66, v87, v66
	v_add_f32_e32 v66, v86, v66
	ds_bpermute_b32 v67, v215, v66
	v_lshl_add_u64 v[82:83], v[82:83], 1, s[8:9]
	global_store_dwordx4 v[82:83], v[78:81], off
	s_nop 1
	v_permlane16_swap_b32_e32 v70, v74
	v_permlane16_swap_b32_e32 v71, v75
	v_permlane16_swap_b32_e32 v72, v76
	v_permlane16_swap_b32_e32 v73, v77
	v_permlane32_swap_b32_e32 v70, v74
	v_permlane32_swap_b32_e32 v71, v75
	v_permlane32_swap_b32_e32 v72, v76
	v_permlane32_swap_b32_e32 v73, v77
	v_sub_co_u32_e64 v232, s[98:99], v84, v189
	v_subbrev_co_u32_e64 v233, s[98:99], 0, v85, s[98:99]
	global_store_dwordx4 v[232:233], v[70:73], off offset:512
	global_store_dwordx4 v[232:233], v[74:77], off offset:576
	s_nop 1
	v_permlane32_swap_b32_e32 v70, v74
	v_permlane32_swap_b32_e32 v71, v75
	v_permlane32_swap_b32_e32 v72, v76
	v_permlane32_swap_b32_e32 v73, v77
	v_permlane16_swap_b32_e32 v70, v74
	v_permlane16_swap_b32_e32 v71, v75
	v_permlane16_swap_b32_e32 v72, v76
	v_permlane16_swap_b32_e32 v73, v77
	v_cvt_pk_bf16_f32 v68, v70, v71
	v_cvt_pk_bf16_f32 v69, v72, v73
	s_waitcnt lgkmcnt(0)
	v_add_f32_e32 v66, v66, v67
	ds_bpermute_b32 v67, v214, v66
	v_cvt_pk_bf16_f32 v70, v74, v75
	v_cvt_pk_bf16_f32 v71, v76, v77
	global_store_dwordx4 v[82:83], v[68:71], off offset:256
	s_and_saveexec_b64 s[22:23], vcc
	s_cbranch_execz .LBB0_847
	v_lshlrev_b64 v[68:69], 6, v[206:207]
	v_lshl_add_u64 v[68:69], s[10:11], 0, v[68:69]
	v_lshl_add_u64 v[68:69], s[4:5], 2, v[68:69]
	s_lshl_b32 s34, s45, 2
	v_lshl_add_u64 v[68:69], v[68:69], 0, s[34:35]
	s_waitcnt lgkmcnt(0)
	v_add_f32_e32 v66, v66, v67
	global_store_dword v[68:69], v66, off
.LBB0_847:
	s_or_b64 exec, exec, s[22:23]
	v_add_u32_e32 v132, 0xa0, v202
	v_ashrrev_i32_e32 v133, 31, v132
	s_waitcnt lgkmcnt(0)
	v_lshlrev_b64 v[66:67], 12, v[132:133]
	v_add_u32_e32 v130, 0xb0, v202
	v_lshl_add_u64 v[66:67], v[204:205], 0, v[66:67]
	v_ashrrev_i32_e32 v131, 31, v130
	global_load_dwordx4 v[90:93], v[66:67], off offset:16
	global_load_dwordx4 v[94:97], v[66:67], off
	global_load_dwordx4 v[82:85], v[66:67], off offset:528
	global_load_dwordx4 v[86:89], v[66:67], off offset:512
	v_lshlrev_b64 v[66:67], 12, v[130:131]
	v_lshl_add_u64 v[70:71], v[204:205], 0, v[66:67]
	global_load_dwordx4 v[74:77], v[70:71], off offset:16
	global_load_dwordx4 v[78:81], v[70:71], off
	global_load_dwordx4 v[66:69], v[70:71], off offset:528
	s_nop 0
	global_load_dwordx4 v[70:73], v[70:71], off offset:512
	v_lshlrev_b64 v[134:135], 10, v[164:165]
	s_waitcnt vmcnt(26)
	v_pk_add_f32 v[64:65], v[64:65], v[128:129]
	v_pk_add_f32 v[62:63], v[62:63], v[126:127]
	v_lshl_add_u64 v[134:135], v[134:135], 0, v[200:201]
	v_pk_add_f32 v[60:61], v[60:61], v[124:125]
	v_pk_mul_f32 v[124:125], v[64:65], v[64:65]
	v_pk_mul_f32 v[126:127], v[62:63], v[62:63]
	v_pk_add_f32 v[58:59], v[58:59], v[122:123]
	v_lshl_add_u64 v[122:123], v[134:135], 2, s[12:13]
	v_add_f32_e32 v126, v126, v127
	v_add_f32_e32 v124, v124, v125
	s_waitcnt vmcnt(24)
	v_pk_add_f32 v[56:57], v[56:57], v[120:121]
	v_pk_add_f32 v[54:55], v[54:55], v[118:119]
	s_nop 1
	v_permlane16_swap_b32_e32 v62, v58
	v_permlane16_swap_b32_e32 v63, v59
	v_permlane16_swap_b32_e32 v64, v60
	v_permlane16_swap_b32_e32 v65, v61
	v_permlane32_swap_b32_e32 v62, v58
	v_permlane32_swap_b32_e32 v63, v59
	v_permlane32_swap_b32_e32 v64, v60
	v_permlane32_swap_b32_e32 v65, v61
	v_sub_co_u32_e64 v232, s[98:99], v122, v189
	v_subbrev_co_u32_e64 v233, s[98:99], 0, v123, s[98:99]
	global_store_dwordx4 v[232:233], v[62:65], off
	global_store_dwordx4 v[232:233], v[58:61], off offset:64
	s_nop 1
	v_permlane32_swap_b32_e32 v62, v58
	v_permlane32_swap_b32_e32 v63, v59
	v_permlane32_swap_b32_e32 v64, v60
	v_permlane32_swap_b32_e32 v65, v61
	v_permlane16_swap_b32_e32 v62, v58
	v_permlane16_swap_b32_e32 v63, v59
	v_permlane16_swap_b32_e32 v64, v60
	v_permlane16_swap_b32_e32 v65, v61
	v_add_f32_e32 v128, v126, v124
	v_pk_mul_f32 v[124:125], v[60:61], v[60:61]
	v_pk_mul_f32 v[126:127], v[58:59], v[58:59]
	v_cvt_pk_bf16_f32 v62, v62, v63
	v_cvt_pk_bf16_f32 v63, v64, v65
	v_cvt_pk_bf16_f32 v64, v58, v59
	v_cvt_pk_bf16_f32 v65, v60, v61
	v_pk_add_f32 v[60:61], v[52:53], v[116:117]
	v_pk_add_f32 v[58:59], v[50:51], v[114:115]
	v_pk_mul_f32 v[50:51], v[56:57], v[56:57]
	v_pk_mul_f32 v[52:53], v[54:55], v[54:55]
	v_add_f32_e32 v50, v50, v51
	v_add_f32_e32 v52, v52, v53
	v_add_f32_e32 v114, v52, v50
	v_pk_mul_f32 v[50:51], v[60:61], v[60:61]
	v_pk_mul_f32 v[52:53], v[58:59], v[58:59]
	v_add_f32_e32 v126, v126, v127
	v_add_f32_e32 v124, v124, v125
	v_add_f32_e32 v52, v52, v53
	v_add_f32_e32 v50, v50, v51
	v_add_f32_e32 v124, v126, v124
	v_add_f32_e32 v50, v52, v50
	v_add_f32_e32 v126, v128, v124
	v_add_f32_e32 v50, v114, v50
	v_add_f32_e32 v50, v126, v50
	ds_bpermute_b32 v51, v215, v50
	v_lshl_add_u64 v[124:125], v[134:135], 1, s[8:9]
	global_store_dwordx4 v[124:125], v[62:65], off
	s_nop 1
	v_permlane16_swap_b32_e32 v54, v58
	v_permlane16_swap_b32_e32 v55, v59
	v_permlane16_swap_b32_e32 v56, v60
	v_permlane16_swap_b32_e32 v57, v61
	v_permlane32_swap_b32_e32 v54, v58
	v_permlane32_swap_b32_e32 v55, v59
	v_permlane32_swap_b32_e32 v56, v60
	v_permlane32_swap_b32_e32 v57, v61
	v_sub_co_u32_e64 v232, s[98:99], v122, v189
	v_subbrev_co_u32_e64 v233, s[98:99], 0, v123, s[98:99]
	global_store_dwordx4 v[232:233], v[54:57], off offset:512
	global_store_dwordx4 v[232:233], v[58:61], off offset:576
	s_nop 1
	v_permlane32_swap_b32_e32 v54, v58
	v_permlane32_swap_b32_e32 v55, v59
	v_permlane32_swap_b32_e32 v56, v60
	v_permlane32_swap_b32_e32 v57, v61
	v_permlane16_swap_b32_e32 v54, v58
	v_permlane16_swap_b32_e32 v55, v59
	v_permlane16_swap_b32_e32 v56, v60
	v_permlane16_swap_b32_e32 v57, v61
	v_cvt_pk_bf16_f32 v52, v54, v55
	v_cvt_pk_bf16_f32 v53, v56, v57
	s_waitcnt lgkmcnt(0)
	v_add_f32_e32 v50, v50, v51
	ds_bpermute_b32 v51, v214, v50
	v_cvt_pk_bf16_f32 v54, v58, v59
	v_cvt_pk_bf16_f32 v55, v60, v61
	global_store_dwordx4 v[124:125], v[52:55], off offset:256
	s_and_saveexec_b64 s[22:23], vcc
	s_cbranch_execz .LBB0_849
	v_lshlrev_b64 v[52:53], 6, v[164:165]
	v_lshl_add_u64 v[52:53], s[10:11], 0, v[52:53]
	v_lshl_add_u64 v[52:53], s[4:5], 2, v[52:53]
	s_lshl_b32 s34, s45, 2
	v_lshl_add_u64 v[52:53], v[52:53], 0, s[34:35]
	s_waitcnt lgkmcnt(0)
	v_add_f32_e32 v50, v50, v51
	global_store_dword v[52:53], v50, off
.LBB0_849:
	s_or_b64 exec, exec, s[22:23]
	s_waitcnt lgkmcnt(0)
	v_lshlrev_b64 v[50:51], 10, v[162:163]
	s_waitcnt vmcnt(28)
	v_pk_add_f32 v[48:49], v[48:49], v[112:113]
	v_pk_add_f32 v[46:47], v[46:47], v[110:111]
	v_lshl_add_u64 v[50:51], v[50:51], 0, v[200:201]
	v_pk_mul_f32 v[54:55], v[48:49], v[48:49]
	v_pk_mul_f32 v[56:57], v[46:47], v[46:47]
	v_pk_add_f32 v[44:45], v[44:45], v[108:109]
	v_pk_add_f32 v[42:43], v[42:43], v[106:107]
	v_lshl_add_u64 v[52:53], v[50:51], 2, s[12:13]
	v_add_f32_e32 v56, v56, v57
	v_add_f32_e32 v54, v54, v55
	s_waitcnt vmcnt(26)
	v_pk_add_f32 v[40:41], v[40:41], v[104:105]
	v_pk_add_f32 v[38:39], v[38:39], v[102:103]
	s_nop 1
	v_permlane16_swap_b32_e32 v46, v42
	v_permlane16_swap_b32_e32 v47, v43
	v_permlane16_swap_b32_e32 v48, v44
	v_permlane16_swap_b32_e32 v49, v45
	v_permlane32_swap_b32_e32 v46, v42
	v_permlane32_swap_b32_e32 v47, v43
	v_permlane32_swap_b32_e32 v48, v44
	v_permlane32_swap_b32_e32 v49, v45
	v_sub_co_u32_e64 v232, s[98:99], v52, v189
	v_subbrev_co_u32_e64 v233, s[98:99], 0, v53, s[98:99]
	global_store_dwordx4 v[232:233], v[46:49], off
	global_store_dwordx4 v[232:233], v[42:45], off offset:64
	s_nop 1
	v_permlane32_swap_b32_e32 v46, v42
	v_permlane32_swap_b32_e32 v47, v43
	v_permlane32_swap_b32_e32 v48, v44
	v_permlane32_swap_b32_e32 v49, v45
	v_permlane16_swap_b32_e32 v46, v42
	v_permlane16_swap_b32_e32 v47, v43
	v_permlane16_swap_b32_e32 v48, v44
	v_permlane16_swap_b32_e32 v49, v45
	v_add_f32_e32 v58, v56, v54
	v_pk_mul_f32 v[54:55], v[44:45], v[44:45]
	v_pk_mul_f32 v[56:57], v[42:43], v[42:43]
	v_cvt_pk_bf16_f32 v46, v46, v47
	v_cvt_pk_bf16_f32 v47, v48, v49
	v_cvt_pk_bf16_f32 v48, v42, v43
	v_cvt_pk_bf16_f32 v49, v44, v45
	v_pk_add_f32 v[44:45], v[36:37], v[100:101]
	v_pk_add_f32 v[42:43], v[34:35], v[98:99]
	v_pk_mul_f32 v[34:35], v[40:41], v[40:41]
	v_pk_mul_f32 v[36:37], v[38:39], v[38:39]
	v_add_f32_e32 v34, v34, v35
	v_add_f32_e32 v36, v36, v37
	v_add_f32_e32 v54, v54, v55
	v_add_f32_e32 v55, v36, v34
	v_pk_mul_f32 v[34:35], v[44:45], v[44:45]
	v_pk_mul_f32 v[36:37], v[42:43], v[42:43]
	v_add_f32_e32 v56, v56, v57
	v_add_f32_e32 v36, v36, v37
	v_add_f32_e32 v34, v34, v35
	v_add_f32_e32 v54, v56, v54
	v_add_f32_e32 v34, v36, v34
	v_add_f32_e32 v54, v58, v54
	v_add_f32_e32 v34, v55, v34
	v_add_f32_e32 v34, v54, v34
	ds_bpermute_b32 v35, v215, v34
	v_lshl_add_u64 v[50:51], v[50:51], 1, s[8:9]
	global_store_dwordx4 v[50:51], v[46:49], off
	s_nop 1
	v_permlane16_swap_b32_e32 v38, v42
	v_permlane16_swap_b32_e32 v39, v43
	v_permlane16_swap_b32_e32 v40, v44
	v_permlane16_swap_b32_e32 v41, v45
	v_permlane32_swap_b32_e32 v38, v42
	v_permlane32_swap_b32_e32 v39, v43
	v_permlane32_swap_b32_e32 v40, v44
	v_permlane32_swap_b32_e32 v41, v45
	v_sub_co_u32_e64 v232, s[98:99], v52, v189
	v_subbrev_co_u32_e64 v233, s[98:99], 0, v53, s[98:99]
	global_store_dwordx4 v[232:233], v[38:41], off offset:512
	global_store_dwordx4 v[232:233], v[42:45], off offset:576
	s_nop 1
	v_permlane32_swap_b32_e32 v38, v42
	v_permlane32_swap_b32_e32 v39, v43
	v_permlane32_swap_b32_e32 v40, v44
	v_permlane32_swap_b32_e32 v41, v45
	v_permlane16_swap_b32_e32 v38, v42
	v_permlane16_swap_b32_e32 v39, v43
	v_permlane16_swap_b32_e32 v40, v44
	v_permlane16_swap_b32_e32 v41, v45
	v_cvt_pk_bf16_f32 v36, v38, v39
	v_cvt_pk_bf16_f32 v37, v40, v41
	s_waitcnt lgkmcnt(0)
	v_add_f32_e32 v34, v34, v35
	ds_bpermute_b32 v35, v214, v34
	v_cvt_pk_bf16_f32 v38, v42, v43
	v_cvt_pk_bf16_f32 v39, v44, v45
	global_store_dwordx4 v[50:51], v[36:39], off offset:256
	s_and_saveexec_b64 s[22:23], vcc
	s_cbranch_execz .LBB0_851
	v_lshlrev_b64 v[36:37], 6, v[162:163]
	v_lshl_add_u64 v[36:37], s[10:11], 0, v[36:37]
	v_lshl_add_u64 v[36:37], s[4:5], 2, v[36:37]
	s_lshl_b32 s34, s45, 2
	v_lshl_add_u64 v[36:37], v[36:37], 0, s[34:35]
	s_waitcnt lgkmcnt(0)
	v_add_f32_e32 v34, v34, v35
	global_store_dword v[36:37], v34, off
.LBB0_851:
	s_or_b64 exec, exec, s[22:23]
	s_waitcnt lgkmcnt(0)
	v_lshlrev_b64 v[34:35], 10, v[132:133]
	s_waitcnt vmcnt(18)
	v_pk_add_f32 v[32:33], v[32:33], v[96:97]
	v_pk_add_f32 v[30:31], v[30:31], v[94:95]
	v_lshl_add_u64 v[34:35], v[34:35], 0, v[200:201]
	v_pk_mul_f32 v[38:39], v[32:33], v[32:33]
	v_pk_mul_f32 v[40:41], v[30:31], v[30:31]
	v_pk_add_f32 v[28:29], v[28:29], v[92:93]
	v_pk_add_f32 v[26:27], v[26:27], v[90:91]
	v_lshl_add_u64 v[36:37], v[34:35], 2, s[12:13]
	v_add_f32_e32 v40, v40, v41
	v_add_f32_e32 v38, v38, v39
	s_waitcnt vmcnt(16)
	v_pk_add_f32 v[24:25], v[24:25], v[88:89]
	v_pk_add_f32 v[22:23], v[22:23], v[86:87]
	s_nop 1
	v_permlane16_swap_b32_e32 v30, v26
	v_permlane16_swap_b32_e32 v31, v27
	v_permlane16_swap_b32_e32 v32, v28
	v_permlane16_swap_b32_e32 v33, v29
	v_permlane32_swap_b32_e32 v30, v26
	v_permlane32_swap_b32_e32 v31, v27
	v_permlane32_swap_b32_e32 v32, v28
	v_permlane32_swap_b32_e32 v33, v29
	v_sub_co_u32_e64 v232, s[98:99], v36, v189
	v_subbrev_co_u32_e64 v233, s[98:99], 0, v37, s[98:99]
	global_store_dwordx4 v[232:233], v[30:33], off
	global_store_dwordx4 v[232:233], v[26:29], off offset:64
	s_nop 1
	v_permlane32_swap_b32_e32 v30, v26
	v_permlane32_swap_b32_e32 v31, v27
	v_permlane32_swap_b32_e32 v32, v28
	v_permlane32_swap_b32_e32 v33, v29
	v_permlane16_swap_b32_e32 v30, v26
	v_permlane16_swap_b32_e32 v31, v27
	v_permlane16_swap_b32_e32 v32, v28
	v_permlane16_swap_b32_e32 v33, v29
	v_add_f32_e32 v42, v40, v38
	v_pk_mul_f32 v[38:39], v[28:29], v[28:29]
	v_pk_mul_f32 v[40:41], v[26:27], v[26:27]
	v_cvt_pk_bf16_f32 v30, v30, v31
	v_cvt_pk_bf16_f32 v31, v32, v33
	v_cvt_pk_bf16_f32 v32, v26, v27
	v_cvt_pk_bf16_f32 v33, v28, v29
	v_pk_add_f32 v[28:29], v[20:21], v[84:85]
	v_pk_add_f32 v[26:27], v[18:19], v[82:83]
	v_pk_mul_f32 v[18:19], v[24:25], v[24:25]
	v_pk_mul_f32 v[20:21], v[22:23], v[22:23]
	v_add_f32_e32 v18, v18, v19
	v_add_f32_e32 v20, v20, v21
	v_add_f32_e32 v38, v38, v39
	v_add_f32_e32 v39, v20, v18
	v_pk_mul_f32 v[18:19], v[28:29], v[28:29]
	v_pk_mul_f32 v[20:21], v[26:27], v[26:27]
	v_add_f32_e32 v40, v40, v41
	v_add_f32_e32 v20, v20, v21
	v_add_f32_e32 v18, v18, v19
	v_add_f32_e32 v38, v40, v38
	v_add_f32_e32 v18, v20, v18
	v_add_f32_e32 v38, v42, v38
	v_add_f32_e32 v18, v39, v18
	v_add_f32_e32 v18, v38, v18
	ds_bpermute_b32 v19, v215, v18
	v_lshl_add_u64 v[34:35], v[34:35], 1, s[8:9]
	global_store_dwordx4 v[34:35], v[30:33], off
	s_nop 1
	v_permlane16_swap_b32_e32 v22, v26
	v_permlane16_swap_b32_e32 v23, v27
	v_permlane16_swap_b32_e32 v24, v28
	v_permlane16_swap_b32_e32 v25, v29
	v_permlane32_swap_b32_e32 v22, v26
	v_permlane32_swap_b32_e32 v23, v27
	v_permlane32_swap_b32_e32 v24, v28
	v_permlane32_swap_b32_e32 v25, v29
	v_sub_co_u32_e64 v232, s[98:99], v36, v189
	v_subbrev_co_u32_e64 v233, s[98:99], 0, v37, s[98:99]
	global_store_dwordx4 v[232:233], v[22:25], off offset:512
	global_store_dwordx4 v[232:233], v[26:29], off offset:576
	s_nop 1
	v_permlane32_swap_b32_e32 v22, v26
	v_permlane32_swap_b32_e32 v23, v27
	v_permlane32_swap_b32_e32 v24, v28
	v_permlane32_swap_b32_e32 v25, v29
	v_permlane16_swap_b32_e32 v22, v26
	v_permlane16_swap_b32_e32 v23, v27
	v_permlane16_swap_b32_e32 v24, v28
	v_permlane16_swap_b32_e32 v25, v29
	v_cvt_pk_bf16_f32 v20, v22, v23
	v_cvt_pk_bf16_f32 v21, v24, v25
	s_waitcnt lgkmcnt(0)
	v_add_f32_e32 v18, v18, v19
	ds_bpermute_b32 v19, v214, v18
	v_cvt_pk_bf16_f32 v22, v26, v27
	v_cvt_pk_bf16_f32 v23, v28, v29
	global_store_dwordx4 v[34:35], v[20:23], off offset:256
	s_and_saveexec_b64 s[22:23], vcc
	s_cbranch_execz .LBB0_853
	v_lshlrev_b64 v[20:21], 6, v[132:133]
	v_lshl_add_u64 v[20:21], s[10:11], 0, v[20:21]
	v_lshl_add_u64 v[20:21], s[4:5], 2, v[20:21]
	s_lshl_b32 s34, s45, 2
	v_lshl_add_u64 v[20:21], v[20:21], 0, s[34:35]
	s_waitcnt lgkmcnt(0)
	v_add_f32_e32 v18, v18, v19
	global_store_dword v[20:21], v18, off
.LBB0_853:
	s_or_b64 exec, exec, s[22:23]
	s_waitcnt lgkmcnt(0)
	v_lshlrev_b64 v[18:19], 10, v[130:131]
	s_waitcnt vmcnt(20)
	v_pk_add_f32 v[16:17], v[16:17], v[80:81]
	v_pk_add_f32 v[14:15], v[14:15], v[78:79]
	v_lshl_add_u64 v[18:19], v[18:19], 0, v[200:201]
	v_pk_mul_f32 v[22:23], v[16:17], v[16:17]
	v_pk_mul_f32 v[24:25], v[14:15], v[14:15]
	v_pk_add_f32 v[12:13], v[12:13], v[76:77]
	v_pk_add_f32 v[10:11], v[10:11], v[74:75]
	v_lshl_add_u64 v[20:21], v[18:19], 2, s[12:13]
	v_add_f32_e32 v24, v24, v25
	v_add_f32_e32 v22, v22, v23
	s_waitcnt vmcnt(18)
	v_pk_add_f32 v[8:9], v[8:9], v[72:73]
	v_pk_add_f32 v[6:7], v[6:7], v[70:71]
	s_nop 1
	v_permlane16_swap_b32_e32 v14, v10
	v_permlane16_swap_b32_e32 v15, v11
	v_permlane16_swap_b32_e32 v16, v12
	v_permlane16_swap_b32_e32 v17, v13
	v_permlane32_swap_b32_e32 v14, v10
	v_permlane32_swap_b32_e32 v15, v11
	v_permlane32_swap_b32_e32 v16, v12
	v_permlane32_swap_b32_e32 v17, v13
	v_sub_co_u32_e64 v232, s[98:99], v20, v189
	v_subbrev_co_u32_e64 v233, s[98:99], 0, v21, s[98:99]
	global_store_dwordx4 v[232:233], v[14:17], off
	global_store_dwordx4 v[232:233], v[10:13], off offset:64
	s_nop 1
	v_permlane32_swap_b32_e32 v14, v10
	v_permlane32_swap_b32_e32 v15, v11
	v_permlane32_swap_b32_e32 v16, v12
	v_permlane32_swap_b32_e32 v17, v13
	v_permlane16_swap_b32_e32 v14, v10
	v_permlane16_swap_b32_e32 v15, v11
	v_permlane16_swap_b32_e32 v16, v12
	v_permlane16_swap_b32_e32 v17, v13
	v_add_f32_e32 v26, v24, v22
	v_pk_mul_f32 v[22:23], v[12:13], v[12:13]
	v_pk_mul_f32 v[24:25], v[10:11], v[10:11]
	v_cvt_pk_bf16_f32 v14, v14, v15
	v_cvt_pk_bf16_f32 v15, v16, v17
	v_cvt_pk_bf16_f32 v16, v10, v11
	v_cvt_pk_bf16_f32 v17, v12, v13
	v_pk_add_f32 v[12:13], v[4:5], v[68:69]
	v_pk_add_f32 v[10:11], v[2:3], v[66:67]
	v_pk_mul_f32 v[2:3], v[8:9], v[8:9]
	v_pk_mul_f32 v[4:5], v[6:7], v[6:7]
	v_add_f32_e32 v2, v2, v3
	v_add_f32_e32 v4, v4, v5
	v_add_f32_e32 v22, v22, v23
	v_add_f32_e32 v23, v4, v2
	v_pk_mul_f32 v[2:3], v[12:13], v[12:13]
	v_pk_mul_f32 v[4:5], v[10:11], v[10:11]
	v_add_f32_e32 v24, v24, v25
	v_add_f32_e32 v4, v4, v5
	v_add_f32_e32 v2, v2, v3
	v_add_f32_e32 v22, v24, v22
	v_add_f32_e32 v2, v4, v2
	v_add_f32_e32 v22, v26, v22
	v_add_f32_e32 v2, v23, v2
	v_add_f32_e32 v2, v22, v2
	ds_bpermute_b32 v3, v215, v2
	v_lshl_add_u64 v[18:19], v[18:19], 1, s[8:9]
	global_store_dwordx4 v[18:19], v[14:17], off
	s_nop 1
	v_permlane16_swap_b32_e32 v6, v10
	v_permlane16_swap_b32_e32 v7, v11
	v_permlane16_swap_b32_e32 v8, v12
	v_permlane16_swap_b32_e32 v9, v13
	v_permlane32_swap_b32_e32 v6, v10
	v_permlane32_swap_b32_e32 v7, v11
	v_permlane32_swap_b32_e32 v8, v12
	v_permlane32_swap_b32_e32 v9, v13
	v_sub_co_u32_e64 v232, s[98:99], v20, v189
	v_subbrev_co_u32_e64 v233, s[98:99], 0, v21, s[98:99]
	global_store_dwordx4 v[232:233], v[6:9], off offset:512
	global_store_dwordx4 v[232:233], v[10:13], off offset:576
	s_nop 1
	v_permlane32_swap_b32_e32 v6, v10
	v_permlane32_swap_b32_e32 v7, v11
	v_permlane32_swap_b32_e32 v8, v12
	v_permlane32_swap_b32_e32 v9, v13
	v_permlane16_swap_b32_e32 v6, v10
	v_permlane16_swap_b32_e32 v7, v11
	v_permlane16_swap_b32_e32 v8, v12
	v_permlane16_swap_b32_e32 v9, v13
	v_cvt_pk_bf16_f32 v4, v6, v7
	v_cvt_pk_bf16_f32 v5, v8, v9
	s_waitcnt lgkmcnt(0)
	v_add_f32_e32 v2, v2, v3
	ds_bpermute_b32 v3, v214, v2
	v_cvt_pk_bf16_f32 v6, v10, v11
	v_cvt_pk_bf16_f32 v7, v12, v13
	global_store_dwordx4 v[18:19], v[4:7], off offset:256
	s_and_saveexec_b64 s[22:23], vcc
	s_cbranch_execz .LBB0_828
	s_waitcnt lgkmcnt(0)
	v_add_f32_e32 v4, v2, v3
	v_lshlrev_b64 v[2:3], 6, v[130:131]
	v_lshl_add_u64 v[2:3], s[10:11], 0, v[2:3]
	v_lshl_add_u64 v[2:3], s[4:5], 2, v[2:3]
	s_lshl_b32 s34, s45, 2
	v_lshl_add_u64 v[2:3], v[2:3], 0, s[34:35]
	global_store_dword v[2:3], v4, off
	s_branch .LBB0_828

.LBB0_1090:
	v_lshl_add_u64 v[178:179], s[16:17], 0, v[196:197]
	s_add_i32 m0, s39, 0xc000
	ds_read_b128 v[146:149], v213
	ds_read_b128 v[150:153], v213 offset:1024
	ds_read_b128 v[154:157], v213 offset:2048
	ds_read_b128 v[158:161], v213 offset:3072
	ds_read_b128 v[162:165], v213 offset:4096
	ds_read_b128 v[166:169], v213 offset:5120
	ds_read_b128 v[170:173], v213 offset:6144
	ds_read_b128 v[174:177], v213 offset:7168
	global_load_lds_dwordx4 v[178:179], off
	s_add_i32 m0, s39, 0xe000
	v_lshl_add_u64 v[178:179], s[16:17], 0, v[198:199]
	global_load_lds_dwordx4 v[178:179], off
	s_waitcnt lgkmcnt(8)
	s_barrier
	s_waitcnt lgkmcnt(0)
	v_mfma_f32_16x16x32_bf16 v[126:129], v[130:133], v[146:149], v[126:129]
	v_mfma_f32_16x16x32_bf16 v[122:125], v[138:141], v[146:149], v[122:125]
	v_mfma_f32_16x16x32_bf16 v[110:113], v[130:133], v[154:157], v[110:113]
	v_mfma_f32_16x16x32_bf16 v[106:109], v[138:141], v[154:157], v[106:109]
	v_mfma_f32_16x16x32_bf16 v[94:97], v[130:133], v[162:165], v[94:97]
	v_mfma_f32_16x16x32_bf16 v[90:93], v[138:141], v[162:165], v[90:93]
	v_mfma_f32_16x16x32_bf16 v[78:81], v[130:133], v[170:173], v[78:81]
	v_mfma_f32_16x16x32_bf16 v[74:77], v[138:141], v[170:173], v[74:77]
	v_mfma_f32_16x16x32_bf16 v[126:129], v[134:137], v[150:153], v[126:129]
	v_mfma_f32_16x16x32_bf16 v[122:125], v[142:145], v[150:153], v[122:125]
	v_mfma_f32_16x16x32_bf16 v[110:113], v[134:137], v[158:161], v[110:113]
	v_mfma_f32_16x16x32_bf16 v[106:109], v[142:145], v[158:161], v[106:109]
	v_mfma_f32_16x16x32_bf16 v[94:97], v[134:137], v[166:169], v[94:97]
	v_mfma_f32_16x16x32_bf16 v[90:93], v[142:145], v[166:169], v[90:93]
	v_mfma_f32_16x16x32_bf16 v[78:81], v[134:137], v[174:177], v[78:81]
	v_mfma_f32_16x16x32_bf16 v[74:77], v[142:145], v[174:177], v[74:77]
	s_barrier
	s_add_i32 s91, 0, 0x14000
	v_add_u32_e32 v186, s91, v212
	s_add_i32 s16, s90, s38
	ds_read_b128 v[178:181], v186
	ds_read_b128 v[182:185], v186 offset:1024
	ds_read_b128 v[200:203], v186 offset:2048
	ds_read_b128 v[204:207], v186 offset:3072
	v_lshl_add_u64 v[186:187], s[86:87], 0, v[0:1]
	s_mov_b32 m0, s16
	v_lshl_add_u64 v[208:209], s[86:87], 0, v[194:195]
	global_load_lds_dwordx4 v[186:187], off
	s_add_i32 m0, s16, 0x2000
	s_nop 0
	global_load_lds_dwordx4 v[208:209], off
	s_barrier
	s_waitcnt lgkmcnt(0)
	v_mfma_f32_16x16x32_bf16 v[118:121], v[178:181], v[146:149], v[118:121]
	v_mfma_f32_16x16x32_bf16 v[114:117], v[200:203], v[146:149], v[114:117]
	v_mfma_f32_16x16x32_bf16 v[102:105], v[178:181], v[154:157], v[102:105]
	v_mfma_f32_16x16x32_bf16 v[98:101], v[200:203], v[154:157], v[98:101]
	v_mfma_f32_16x16x32_bf16 v[86:89], v[178:181], v[162:165], v[86:89]
	v_mfma_f32_16x16x32_bf16 v[82:85], v[200:203], v[162:165], v[82:85]
	v_mfma_f32_16x16x32_bf16 v[70:73], v[178:181], v[170:173], v[70:73]
	v_mfma_f32_16x16x32_bf16 v[66:69], v[200:203], v[170:173], v[66:69]
	v_mfma_f32_16x16x32_bf16 v[118:121], v[182:185], v[150:153], v[118:121]
	v_mfma_f32_16x16x32_bf16 v[114:117], v[204:207], v[150:153], v[114:117]
	v_mfma_f32_16x16x32_bf16 v[102:105], v[182:185], v[158:161], v[102:105]
	v_mfma_f32_16x16x32_bf16 v[98:101], v[204:207], v[158:161], v[98:101]
	v_mfma_f32_16x16x32_bf16 v[86:89], v[182:185], v[166:169], v[86:89]
	v_mfma_f32_16x16x32_bf16 v[82:85], v[204:207], v[166:169], v[82:85]
	v_mfma_f32_16x16x32_bf16 v[70:73], v[182:185], v[174:177], v[70:73]
	v_mfma_f32_16x16x32_bf16 v[66:69], v[204:207], v[174:177], v[66:69]
	s_mov_b32 m0, s39
	v_lshl_add_u64 v[210:211], s[88:89], 0, v[190:191]
	s_barrier
	ds_read_b128 v[146:149], v213 offset:16384
	ds_read_b128 v[150:153], v213 offset:17408
	ds_read_b128 v[154:157], v213 offset:18432
	ds_read_b128 v[158:161], v213 offset:19456
	ds_read_b128 v[162:165], v213 offset:20480
	ds_read_b128 v[166:169], v213 offset:21504
	ds_read_b128 v[170:173], v213 offset:22528
	ds_read_b128 v[174:177], v213 offset:23552
	global_load_lds_dwordx4 v[210:211], off
	s_mov_b32 m0, s42
	v_lshl_add_u64 v[214:215], s[88:89], 0, v[192:193]
	global_load_lds_dwordx4 v[214:215], off
	s_waitcnt vmcnt(10)
	s_barrier
	s_waitcnt lgkmcnt(0)
	v_mfma_f32_16x16x32_bf16 v[62:65], v[130:133], v[146:149], v[62:65]
	v_mfma_f32_16x16x32_bf16 v[58:61], v[138:141], v[146:149], v[58:61]
	v_mfma_f32_16x16x32_bf16 v[46:49], v[130:133], v[154:157], v[46:49]
	v_mfma_f32_16x16x32_bf16 v[42:45], v[138:141], v[154:157], v[42:45]
	v_mfma_f32_16x16x32_bf16 v[30:33], v[130:133], v[162:165], v[30:33]
	v_mfma_f32_16x16x32_bf16 v[26:29], v[138:141], v[162:165], v[26:29]
	v_mfma_f32_16x16x32_bf16 v[14:17], v[130:133], v[170:173], v[14:17]
	v_mfma_f32_16x16x32_bf16 v[10:13], v[138:141], v[170:173], v[10:13]
	v_mfma_f32_16x16x32_bf16 v[62:65], v[134:137], v[150:153], v[62:65]
	v_mfma_f32_16x16x32_bf16 v[58:61], v[142:145], v[150:153], v[58:61]
	v_mfma_f32_16x16x32_bf16 v[46:49], v[134:137], v[158:161], v[46:49]
	v_mfma_f32_16x16x32_bf16 v[42:45], v[142:145], v[158:161], v[42:45]
	v_mfma_f32_16x16x32_bf16 v[30:33], v[134:137], v[166:169], v[30:33]
	v_mfma_f32_16x16x32_bf16 v[26:29], v[142:145], v[166:169], v[26:29]
	v_mfma_f32_16x16x32_bf16 v[14:17], v[134:137], v[174:177], v[14:17]
	v_mfma_f32_16x16x32_bf16 v[10:13], v[142:145], v[174:177], v[10:13]
	s_barrier
	s_add_u32 s16, s86, 0xb0000
	s_addc_u32 s17, s87, 0
	s_add_i32 s90, s91, s38
	s_mov_b32 m0, s90
	v_lshl_add_u64 v[130:131], s[16:17], 0, v[0:1]
	global_load_lds_dwordx4 v[130:131], off
	s_add_i32 m0, s90, 0x2000
	v_lshl_add_u64 v[130:131], s[16:17], 0, v[194:195]
	global_load_lds_dwordx4 v[130:131], off
	s_add_i32 s90, 0, 0x18000
	v_add_u32_e32 v142, s90, v212
	ds_read_b128 v[130:133], v142
	ds_read_b128 v[134:137], v142 offset:1024
	ds_read_b128 v[138:141], v142 offset:2048
	ds_read_b128 v[142:145], v142 offset:3072
	s_waitcnt vmcnt(6)
	s_barrier
	v_mfma_f32_16x16x32_bf16 v[54:57], v[178:181], v[146:149], v[54:57]
	v_mfma_f32_16x16x32_bf16 v[50:53], v[200:203], v[146:149], v[50:53]
	v_mfma_f32_16x16x32_bf16 v[38:41], v[178:181], v[154:157], v[38:41]
	v_mfma_f32_16x16x32_bf16 v[34:37], v[200:203], v[154:157], v[34:37]
	v_mfma_f32_16x16x32_bf16 v[22:25], v[178:181], v[162:165], v[22:25]
	v_mfma_f32_16x16x32_bf16 v[18:21], v[200:203], v[162:165], v[18:21]
	v_mfma_f32_16x16x32_bf16 v[6:9], v[178:181], v[170:173], v[6:9]
	v_mfma_f32_16x16x32_bf16 v[2:5], v[200:203], v[170:173], v[2:5]
	v_mfma_f32_16x16x32_bf16 v[54:57], v[182:185], v[150:153], v[54:57]
	v_mfma_f32_16x16x32_bf16 v[50:53], v[204:207], v[150:153], v[50:53]
	v_mfma_f32_16x16x32_bf16 v[38:41], v[182:185], v[158:161], v[38:41]
	v_mfma_f32_16x16x32_bf16 v[34:37], v[204:207], v[158:161], v[34:37]
	v_mfma_f32_16x16x32_bf16 v[22:25], v[182:185], v[166:169], v[22:25]
	v_mfma_f32_16x16x32_bf16 v[18:21], v[204:207], v[166:169], v[18:21]
	v_mfma_f32_16x16x32_bf16 v[6:9], v[182:185], v[174:177], v[6:9]
	v_mfma_f32_16x16x32_bf16 v[2:5], v[204:207], v[174:177], v[2:5]
	s_barrier
	s_add_u32 s16, s88, 0xb0000
	s_addc_u32 s17, s89, 0
	s_mov_b32 m0, s43
	v_lshl_add_u64 v[178:179], s[16:17], 0, v[190:191]
	ds_read_b128 v[146:149], v213 offset:32768
	ds_read_b128 v[150:153], v213 offset:33792
	ds_read_b128 v[154:157], v213 offset:34816
	ds_read_b128 v[158:161], v213 offset:35840
	ds_read_b128 v[162:165], v213 offset:36864
	ds_read_b128 v[166:169], v213 offset:37888
	ds_read_b128 v[170:173], v213 offset:38912
	ds_read_b128 v[174:177], v213 offset:39936
	global_load_lds_dwordx4 v[178:179], off
	s_mov_b32 m0, s44
	v_lshl_add_u64 v[178:179], s[16:17], 0, v[192:193]
	global_load_lds_dwordx4 v[178:179], off
	s_waitcnt lgkmcnt(8)
	s_barrier
	s_waitcnt lgkmcnt(0)
	v_mfma_f32_16x16x32_bf16 v[126:129], v[130:133], v[146:149], v[126:129]
	v_mfma_f32_16x16x32_bf16 v[122:125], v[138:141], v[146:149], v[122:125]
	v_mfma_f32_16x16x32_bf16 v[110:113], v[130:133], v[154:157], v[110:113]
	v_mfma_f32_16x16x32_bf16 v[106:109], v[138:141], v[154:157], v[106:109]
	v_mfma_f32_16x16x32_bf16 v[94:97], v[130:133], v[162:165], v[94:97]
	v_mfma_f32_16x16x32_bf16 v[90:93], v[138:141], v[162:165], v[90:93]
	v_mfma_f32_16x16x32_bf16 v[78:81], v[130:133], v[170:173], v[78:81]
	v_mfma_f32_16x16x32_bf16 v[74:77], v[138:141], v[170:173], v[74:77]
	v_mfma_f32_16x16x32_bf16 v[126:129], v[134:137], v[150:153], v[126:129]
	v_mfma_f32_16x16x32_bf16 v[122:125], v[142:145], v[150:153], v[122:125]
	v_mfma_f32_16x16x32_bf16 v[110:113], v[134:137], v[158:161], v[110:113]
	v_mfma_f32_16x16x32_bf16 v[106:109], v[142:145], v[158:161], v[106:109]
	v_mfma_f32_16x16x32_bf16 v[94:97], v[134:137], v[166:169], v[94:97]
	v_mfma_f32_16x16x32_bf16 v[90:93], v[142:145], v[166:169], v[90:93]
	v_mfma_f32_16x16x32_bf16 v[78:81], v[134:137], v[174:177], v[78:81]
	v_mfma_f32_16x16x32_bf16 v[74:77], v[142:145], v[174:177], v[74:77]
	s_barrier
	s_add_i32 s88, 0, 0x1c000
	s_add_i32 s16, s90, s38
	v_add_u32_e32 v204, s88, v212
	v_lshl_add_u64 v[186:187], v[186:187], 0, s[40:41]
	s_mov_b32 m0, s16
	ds_read_b128 v[178:181], v204
	ds_read_b128 v[182:185], v204 offset:1024
	ds_read_b128 v[200:203], v204 offset:2048
	ds_read_b128 v[204:207], v204 offset:3072
	global_load_lds_dwordx4 v[186:187], off
	s_add_i32 m0, s16, 0x2000
	v_lshl_add_u64 v[186:187], v[208:209], 0, s[40:41]
	global_load_lds_dwordx4 v[186:187], off
	s_barrier
	s_waitcnt lgkmcnt(0)
	v_mfma_f32_16x16x32_bf16 v[118:121], v[178:181], v[146:149], v[118:121]
	v_mfma_f32_16x16x32_bf16 v[114:117], v[200:203], v[146:149], v[114:117]
	v_mfma_f32_16x16x32_bf16 v[102:105], v[178:181], v[154:157], v[102:105]
	v_mfma_f32_16x16x32_bf16 v[98:101], v[200:203], v[154:157], v[98:101]
	v_mfma_f32_16x16x32_bf16 v[86:89], v[178:181], v[162:165], v[86:89]
	v_mfma_f32_16x16x32_bf16 v[82:85], v[200:203], v[162:165], v[82:85]
	v_mfma_f32_16x16x32_bf16 v[70:73], v[178:181], v[170:173], v[70:73]
	v_mfma_f32_16x16x32_bf16 v[66:69], v[200:203], v[170:173], v[66:69]
	v_mfma_f32_16x16x32_bf16 v[118:121], v[182:185], v[150:153], v[118:121]
	v_mfma_f32_16x16x32_bf16 v[114:117], v[204:207], v[150:153], v[114:117]
	v_mfma_f32_16x16x32_bf16 v[102:105], v[182:185], v[158:161], v[102:105]
	v_mfma_f32_16x16x32_bf16 v[98:101], v[204:207], v[158:161], v[98:101]
	v_mfma_f32_16x16x32_bf16 v[86:89], v[182:185], v[166:169], v[86:89]
	v_mfma_f32_16x16x32_bf16 v[82:85], v[204:207], v[166:169], v[82:85]
	v_mfma_f32_16x16x32_bf16 v[70:73], v[182:185], v[174:177], v[70:73]
	v_mfma_f32_16x16x32_bf16 v[66:69], v[204:207], v[174:177], v[66:69]
	s_mov_b32 m0, s60
	v_lshl_add_u64 v[186:187], v[210:211], 0, s[40:41]
	s_barrier
	ds_read_b128 v[146:149], v213 offset:49152
	ds_read_b128 v[150:153], v213 offset:50176
	ds_read_b128 v[154:157], v213 offset:51200
	ds_read_b128 v[158:161], v213 offset:52224
	ds_read_b128 v[162:165], v213 offset:53248
	ds_read_b128 v[166:169], v213 offset:54272
	ds_read_b128 v[170:173], v213 offset:55296
	ds_read_b128 v[174:177], v213 offset:56320
	global_load_lds_dwordx4 v[186:187], off
	s_mov_b32 m0, s61
	v_lshl_add_u64 v[186:187], v[214:215], 0, s[40:41]
	global_load_lds_dwordx4 v[186:187], off
	s_waitcnt vmcnt(10)
	s_barrier
	s_waitcnt lgkmcnt(0)
	v_mfma_f32_16x16x32_bf16 v[62:65], v[130:133], v[146:149], v[62:65]
	v_mfma_f32_16x16x32_bf16 v[58:61], v[138:141], v[146:149], v[58:61]
	v_mfma_f32_16x16x32_bf16 v[46:49], v[130:133], v[154:157], v[46:49]
	v_mfma_f32_16x16x32_bf16 v[42:45], v[138:141], v[154:157], v[42:45]
	v_mfma_f32_16x16x32_bf16 v[30:33], v[130:133], v[162:165], v[30:33]
	v_mfma_f32_16x16x32_bf16 v[26:29], v[138:141], v[162:165], v[26:29]
	v_mfma_f32_16x16x32_bf16 v[14:17], v[130:133], v[170:173], v[14:17]
	v_mfma_f32_16x16x32_bf16 v[10:13], v[138:141], v[170:173], v[10:13]
	v_mfma_f32_16x16x32_bf16 v[62:65], v[134:137], v[150:153], v[62:65]
	v_mfma_f32_16x16x32_bf16 v[58:61], v[142:145], v[150:153], v[58:61]
	v_mfma_f32_16x16x32_bf16 v[46:49], v[134:137], v[158:161], v[46:49]
	v_mfma_f32_16x16x32_bf16 v[42:45], v[142:145], v[158:161], v[42:45]
	v_mfma_f32_16x16x32_bf16 v[30:33], v[134:137], v[166:169], v[30:33]
	v_mfma_f32_16x16x32_bf16 v[26:29], v[142:145], v[166:169], v[26:29]
	v_mfma_f32_16x16x32_bf16 v[14:17], v[134:137], v[174:177], v[14:17]
	v_mfma_f32_16x16x32_bf16 v[10:13], v[142:145], v[174:177], v[10:13]
	s_barrier
	s_add_u32 s16, s86, 0xb0080
	s_addc_u32 s17, s87, 0
	s_add_i32 s86, s88, s38
	s_mov_b32 m0, s86
	v_lshl_add_u64 v[130:131], s[16:17], 0, v[0:1]
	global_load_lds_dwordx4 v[130:131], off
	s_add_i32 m0, s86, 0x2000
	v_lshl_add_u64 v[130:131], s[16:17], 0, v[194:195]
	global_load_lds_dwordx4 v[130:131], off
	s_add_i32 s90, 0, 0x10000
	v_add_u32_e32 v142, s90, v212
	ds_read_b128 v[130:133], v142
	ds_read_b128 v[134:137], v142 offset:1024
	ds_read_b128 v[138:141], v142 offset:2048
	ds_read_b128 v[142:145], v142 offset:3072
	s_waitcnt vmcnt(6)
	s_barrier
	v_mfma_f32_16x16x32_bf16 v[54:57], v[178:181], v[146:149], v[54:57]
	v_mfma_f32_16x16x32_bf16 v[50:53], v[200:203], v[146:149], v[50:53]
	v_mfma_f32_16x16x32_bf16 v[38:41], v[178:181], v[154:157], v[38:41]
	v_mfma_f32_16x16x32_bf16 v[34:37], v[200:203], v[154:157], v[34:37]
	v_mfma_f32_16x16x32_bf16 v[22:25], v[178:181], v[162:165], v[22:25]
	v_mfma_f32_16x16x32_bf16 v[18:21], v[200:203], v[162:165], v[18:21]
	v_mfma_f32_16x16x32_bf16 v[6:9], v[178:181], v[170:173], v[6:9]
	v_mfma_f32_16x16x32_bf16 v[2:5], v[200:203], v[170:173], v[2:5]
	v_mfma_f32_16x16x32_bf16 v[54:57], v[182:185], v[150:153], v[54:57]
	v_mfma_f32_16x16x32_bf16 v[50:53], v[204:207], v[150:153], v[50:53]
	v_mfma_f32_16x16x32_bf16 v[38:41], v[182:185], v[158:161], v[38:41]
	v_mfma_f32_16x16x32_bf16 v[34:37], v[204:207], v[158:161], v[34:37]
	v_mfma_f32_16x16x32_bf16 v[22:25], v[182:185], v[166:169], v[22:25]
	v_mfma_f32_16x16x32_bf16 v[18:21], v[204:207], v[166:169], v[18:21]
	v_mfma_f32_16x16x32_bf16 v[6:9], v[182:185], v[174:177], v[6:9]
	v_mfma_f32_16x16x32_bf16 v[2:5], v[204:207], v[174:177], v[2:5]
	s_add_i32 s79, s79, 2
	s_add_u32 s34, s34, 0x100
	s_addc_u32 s78, s78, 0
	s_mov_b64 s[16:17], s[84:85]
	s_add_u32 s84, s16, 0x100
	s_addc_u32 s85, s17, 0
	s_cmp_eq_u32 s79, 40
	s_cselect_b32 s89, s5, s85
	s_cselect_b32 s88, s4, s84
	s_cselect_b32 s87, s7, s78
	s_cselect_b32 s86, s6, s34
	s_cmp_gt_u32 s79, 41
	s_barrier
	s_cbranch_scc0 .LBB0_1090
	v_bfe_u32 v189, v252, 4, 2
	v_lshlrev_b32_e32 v189, 4, v189
	s_waitcnt lgkmcnt(0)
	s_lshl_b32 s16, s23, 8
	v_mov_b32_e32 v186, v252
	s_add_i32 s16, s16, s47
	s_nop 0
	v_and_or_b32 v202, v186, 15, s16
	s_lshl_b32 s16, s22, 8
	s_or_b32 s16, s16, s55
	v_lshrrev_b32_e32 v130, 1, v186
	v_and_or_b32 v200, v130, 24, s16
	v_ashrrev_i32_e32 v201, 31, v200
	v_ashrrev_i32_e32 v203, 31, v202
	v_lshl_add_u64 v[204:205], v[200:201], 2, s[12:13]
	v_lshlrev_b64 v[130:131], 12, v[202:203]
	v_lshl_add_u64 v[130:131], v[204:205], 0, v[130:131]
	global_load_dwordx4 v[216:219], v[130:131], off offset:16
	global_load_dwordx4 v[220:223], v[130:131], off
	global_load_dwordx4 v[178:181], v[130:131], off offset:528
	global_load_dwordx4 v[182:185], v[130:131], off offset:512
	v_or_b32_e32 v210, 16, v202
	v_ashrrev_i32_e32 v211, 31, v210
	v_lshlrev_b64 v[130:131], 12, v[210:211]
	v_or_b32_e32 v208, 32, v202
	v_lshl_add_u64 v[130:131], v[204:205], 0, v[130:131]
	v_ashrrev_i32_e32 v209, 31, v208
	global_load_dwordx4 v[170:173], v[130:131], off offset:16
	global_load_dwordx4 v[174:177], v[130:131], off
	global_load_dwordx4 v[162:165], v[130:131], off offset:528
	global_load_dwordx4 v[166:169], v[130:131], off offset:512
	v_lshlrev_b64 v[130:131], 12, v[208:209]
	v_or_b32_e32 v206, 48, v202
	v_lshl_add_u64 v[130:131], v[204:205], 0, v[130:131]
	v_ashrrev_i32_e32 v207, 31, v206
	global_load_dwordx4 v[154:157], v[130:131], off offset:16
	global_load_dwordx4 v[158:161], v[130:131], off
	global_load_dwordx4 v[138:141], v[130:131], off offset:528
	global_load_dwordx4 v[142:145], v[130:131], off offset:512
	v_lshlrev_b64 v[130:131], 12, v[206:207]
	v_lshl_add_u64 v[134:135], v[204:205], 0, v[130:131]
	global_load_dwordx4 v[146:149], v[134:135], off offset:16
	global_load_dwordx4 v[150:153], v[134:135], off
	global_load_dwordx4 v[130:133], v[134:135], off offset:528
	s_nop 0
	global_load_dwordx4 v[134:137], v[134:135], off offset:512
	v_and_b32_e32 v186, 63, v186
	v_lshlrev_b32_e32 v187, 2, v186
	v_xor_b32_e32 v215, 64, v187
	v_xor_b32_e32 v214, 0x80, v187
	v_cmp_gt_u32_e32 vcc, 16, v186
	v_lshlrev_b64 v[186:187], 10, v[202:203]
	v_lshl_add_u64 v[186:187], v[186:187], 0, v[200:201]
	s_lshl_b32 s16, s22, 2
	s_ashr_i32 s17, s16, 31
	s_waitcnt vmcnt(0)
	v_pk_add_f32 v[124:125], v[124:125], v[218:219]
	v_pk_add_f32 v[128:129], v[128:129], v[222:223]
	v_pk_add_f32 v[126:127], v[126:127], v[220:221]
	v_pk_mul_f32 v[218:219], v[128:129], v[128:129]
	v_pk_mul_f32 v[220:221], v[126:127], v[126:127]
	v_pk_add_f32 v[122:123], v[122:123], v[216:217]
	v_lshl_add_u64 v[216:217], v[186:187], 2, s[14:15]
	v_add_f32_e32 v220, v220, v221
	v_add_f32_e32 v218, v218, v219
	s_nop 1
	v_permlane16_swap_b32_e32 v126, v122
	v_permlane16_swap_b32_e32 v127, v123
	v_permlane16_swap_b32_e32 v128, v124
	v_permlane16_swap_b32_e32 v129, v125
	v_permlane32_swap_b32_e32 v126, v122
	v_permlane32_swap_b32_e32 v127, v123
	v_permlane32_swap_b32_e32 v128, v124
	v_permlane32_swap_b32_e32 v129, v125
	v_sub_co_u32_e64 v232, s[98:99], v216, v189
	v_subbrev_co_u32_e64 v233, s[98:99], 0, v217, s[98:99]
	global_store_dwordx4 v[232:233], v[126:129], off
	global_store_dwordx4 v[232:233], v[122:125], off offset:64
	s_nop 1
	v_permlane32_swap_b32_e32 v126, v122
	v_permlane32_swap_b32_e32 v127, v123
	v_permlane32_swap_b32_e32 v128, v124
	v_permlane32_swap_b32_e32 v129, v125
	v_permlane16_swap_b32_e32 v126, v122
	v_permlane16_swap_b32_e32 v127, v123
	v_permlane16_swap_b32_e32 v128, v124
	v_permlane16_swap_b32_e32 v129, v125
	v_add_f32_e32 v222, v220, v218
	v_pk_mul_f32 v[220:221], v[122:123], v[122:123]
	v_cvt_pk_bf16_f32 v126, v126, v127
	v_cvt_pk_bf16_f32 v127, v128, v129
	v_cvt_pk_bf16_f32 v128, v122, v123
	v_cvt_pk_bf16_f32 v129, v124, v125
	v_lshl_add_u64 v[122:123], v[186:187], 1, s[80:81]
	v_pk_add_f32 v[120:121], v[120:121], v[184:185]
	v_pk_add_f32 v[118:119], v[118:119], v[182:183]
	v_pk_mul_f32 v[218:219], v[124:125], v[124:125]
	global_store_dwordx4 v[122:123], v[126:129], off
	v_pk_mul_f32 v[124:125], v[120:121], v[120:121]
	v_pk_add_f32 v[116:117], v[116:117], v[180:181]
	v_pk_mul_f32 v[126:127], v[118:119], v[118:119]
	v_pk_add_f32 v[114:115], v[114:115], v[178:179]
	v_add_f32_e32 v126, v126, v127
	v_add_f32_e32 v124, v124, v125
	v_add_f32_e32 v128, v126, v124
	v_pk_mul_f32 v[124:125], v[116:117], v[116:117]
	v_pk_mul_f32 v[126:127], v[114:115], v[114:115]
	v_add_f32_e32 v220, v220, v221
	v_add_f32_e32 v218, v218, v219
	v_add_f32_e32 v126, v126, v127
	v_add_f32_e32 v124, v124, v125
	v_add_f32_e32 v218, v220, v218
	v_add_f32_e32 v124, v126, v124
	v_add_f32_e32 v218, v222, v218
	v_add_f32_e32 v124, v128, v124
	v_add_f32_e32 v124, v218, v124
	s_nop 1
	v_permlane16_swap_b32_e32 v118, v114
	v_permlane16_swap_b32_e32 v119, v115
	v_permlane16_swap_b32_e32 v120, v116
	v_permlane16_swap_b32_e32 v121, v117
	v_permlane32_swap_b32_e32 v118, v114
	v_permlane32_swap_b32_e32 v119, v115
	v_permlane32_swap_b32_e32 v120, v116
	v_permlane32_swap_b32_e32 v121, v117
	v_sub_co_u32_e64 v232, s[98:99], v216, v189
	v_subbrev_co_u32_e64 v233, s[98:99], 0, v217, s[98:99]
	global_store_dwordx4 v[232:233], v[118:121], off offset:512
	global_store_dwordx4 v[232:233], v[114:117], off offset:576
	s_nop 1
	v_permlane32_swap_b32_e32 v118, v114
	v_permlane32_swap_b32_e32 v119, v115
	v_permlane32_swap_b32_e32 v120, v116
	v_permlane32_swap_b32_e32 v121, v117
	v_permlane16_swap_b32_e32 v118, v114
	v_permlane16_swap_b32_e32 v119, v115
	v_permlane16_swap_b32_e32 v120, v116
	v_permlane16_swap_b32_e32 v121, v117
	s_nop 0
	v_cvt_pk_bf16_f32 v118, v118, v119
	v_cvt_pk_bf16_f32 v119, v120, v121
	v_cvt_pk_bf16_f32 v120, v114, v115
	ds_bpermute_b32 v114, v215, v124
	v_cvt_pk_bf16_f32 v121, v116, v117
	global_store_dwordx4 v[122:123], v[118:121], off offset:256
	s_waitcnt lgkmcnt(0)
	v_add_f32_e32 v114, v124, v114
	ds_bpermute_b32 v115, v214, v114
	s_and_saveexec_b64 s[22:23], vcc
	s_cbranch_execz .LBB0_1093
	v_lshlrev_b64 v[116:117], 6, v[202:203]
	v_lshl_add_u64 v[116:117], s[82:83], 0, v[116:117]
	v_lshl_add_u64 v[116:117], s[16:17], 2, v[116:117]
	s_lshl_b32 s34, s45, 2
	v_lshl_add_u64 v[116:117], v[116:117], 0, s[34:35]
	s_waitcnt lgkmcnt(0)
	v_add_f32_e32 v114, v114, v115
	global_store_dword v[116:117], v114, off
.LBB0_1093:
	s_or_b64 exec, exec, s[22:23]
	s_waitcnt lgkmcnt(0)
	v_lshlrev_b64 v[114:115], 10, v[210:211]
	v_pk_add_f32 v[112:113], v[112:113], v[176:177]
	v_pk_add_f32 v[110:111], v[110:111], v[174:175]
	v_lshl_add_u64 v[114:115], v[114:115], 0, v[200:201]
	v_pk_mul_f32 v[118:119], v[112:113], v[112:113]
	v_pk_mul_f32 v[120:121], v[110:111], v[110:111]
	v_pk_add_f32 v[108:109], v[108:109], v[172:173]
	v_pk_add_f32 v[106:107], v[106:107], v[170:171]
	v_lshl_add_u64 v[116:117], v[114:115], 2, s[14:15]
	v_add_f32_e32 v120, v120, v121
	v_add_f32_e32 v118, v118, v119
	v_pk_add_f32 v[104:105], v[104:105], v[168:169]
	v_pk_add_f32 v[102:103], v[102:103], v[166:167]
	s_nop 1
	v_permlane16_swap_b32_e32 v110, v106
	v_permlane16_swap_b32_e32 v111, v107
	v_permlane16_swap_b32_e32 v112, v108
	v_permlane16_swap_b32_e32 v113, v109
	v_permlane32_swap_b32_e32 v110, v106
	v_permlane32_swap_b32_e32 v111, v107
	v_permlane32_swap_b32_e32 v112, v108
	v_permlane32_swap_b32_e32 v113, v109
	v_sub_co_u32_e64 v232, s[98:99], v116, v189
	v_subbrev_co_u32_e64 v233, s[98:99], 0, v117, s[98:99]
	global_store_dwordx4 v[232:233], v[110:113], off
	global_store_dwordx4 v[232:233], v[106:109], off offset:64
	s_nop 1
	v_permlane32_swap_b32_e32 v110, v106
	v_permlane32_swap_b32_e32 v111, v107
	v_permlane32_swap_b32_e32 v112, v108
	v_permlane32_swap_b32_e32 v113, v109
	v_permlane16_swap_b32_e32 v110, v106
	v_permlane16_swap_b32_e32 v111, v107
	v_permlane16_swap_b32_e32 v112, v108
	v_permlane16_swap_b32_e32 v113, v109
	v_add_f32_e32 v122, v120, v118
	v_pk_mul_f32 v[118:119], v[108:109], v[108:109]
	v_pk_mul_f32 v[120:121], v[106:107], v[106:107]
	v_cvt_pk_bf16_f32 v110, v110, v111
	v_cvt_pk_bf16_f32 v111, v112, v113
	v_cvt_pk_bf16_f32 v112, v106, v107
	v_cvt_pk_bf16_f32 v113, v108, v109
	v_pk_add_f32 v[108:109], v[100:101], v[164:165]
	v_pk_add_f32 v[106:107], v[98:99], v[162:163]
	v_pk_mul_f32 v[98:99], v[104:105], v[104:105]
	v_pk_mul_f32 v[100:101], v[102:103], v[102:103]
	v_add_f32_e32 v98, v98, v99
	v_add_f32_e32 v100, v100, v101
	v_add_f32_e32 v118, v118, v119
	v_add_f32_e32 v119, v100, v98
	v_pk_mul_f32 v[98:99], v[108:109], v[108:109]
	v_pk_mul_f32 v[100:101], v[106:107], v[106:107]
	v_add_f32_e32 v120, v120, v121
	v_add_f32_e32 v100, v100, v101
	v_add_f32_e32 v98, v98, v99
	v_add_f32_e32 v118, v120, v118
	v_add_f32_e32 v98, v100, v98
	v_add_f32_e32 v118, v122, v118
	v_add_f32_e32 v98, v119, v98
	v_add_f32_e32 v98, v118, v98
	ds_bpermute_b32 v99, v215, v98
	v_lshl_add_u64 v[114:115], v[114:115], 1, s[80:81]
	global_store_dwordx4 v[114:115], v[110:113], off
	s_nop 1
	v_permlane16_swap_b32_e32 v102, v106
	v_permlane16_swap_b32_e32 v103, v107
	v_permlane16_swap_b32_e32 v104, v108
	v_permlane16_swap_b32_e32 v105, v109
	v_permlane32_swap_b32_e32 v102, v106
	v_permlane32_swap_b32_e32 v103, v107
	v_permlane32_swap_b32_e32 v104, v108
	v_permlane32_swap_b32_e32 v105, v109
	v_sub_co_u32_e64 v232, s[98:99], v116, v189
	v_subbrev_co_u32_e64 v233, s[98:99], 0, v117, s[98:99]
	global_store_dwordx4 v[232:233], v[102:105], off offset:512
	global_store_dwordx4 v[232:233], v[106:109], off offset:576
	s_nop 1
	v_permlane32_swap_b32_e32 v102, v106
	v_permlane32_swap_b32_e32 v103, v107
	v_permlane32_swap_b32_e32 v104, v108
	v_permlane32_swap_b32_e32 v105, v109
	v_permlane16_swap_b32_e32 v102, v106
	v_permlane16_swap_b32_e32 v103, v107
	v_permlane16_swap_b32_e32 v104, v108
	v_permlane16_swap_b32_e32 v105, v109
	v_cvt_pk_bf16_f32 v100, v102, v103
	v_cvt_pk_bf16_f32 v101, v104, v105
	s_waitcnt lgkmcnt(0)
	v_add_f32_e32 v98, v98, v99
	ds_bpermute_b32 v99, v214, v98
	v_cvt_pk_bf16_f32 v102, v106, v107
	v_cvt_pk_bf16_f32 v103, v108, v109
	global_store_dwordx4 v[114:115], v[100:103], off offset:256
	s_and_saveexec_b64 s[22:23], vcc
	s_cbranch_execz .LBB0_1095
	v_lshlrev_b64 v[100:101], 6, v[210:211]
	v_lshl_add_u64 v[100:101], s[82:83], 0, v[100:101]
	v_lshl_add_u64 v[100:101], s[16:17], 2, v[100:101]
	s_lshl_b32 s34, s45, 2
	v_lshl_add_u64 v[100:101], v[100:101], 0, s[34:35]
	s_waitcnt lgkmcnt(0)
	v_add_f32_e32 v98, v98, v99
	global_store_dword v[100:101], v98, off
.LBB0_1095:
	s_or_b64 exec, exec, s[22:23]
	v_add_u32_e32 v164, 0x80, v202
	v_ashrrev_i32_e32 v165, 31, v164
	s_waitcnt lgkmcnt(0)
	v_lshlrev_b64 v[98:99], 12, v[164:165]
	v_add_u32_e32 v162, 0x90, v202
	v_lshl_add_u64 v[98:99], v[204:205], 0, v[98:99]
	v_ashrrev_i32_e32 v163, 31, v162
	global_load_dwordx4 v[122:125], v[98:99], off offset:16
	global_load_dwordx4 v[126:129], v[98:99], off
	global_load_dwordx4 v[114:117], v[98:99], off offset:528
	global_load_dwordx4 v[118:121], v[98:99], off offset:512
	v_lshlrev_b64 v[98:99], 12, v[162:163]
	v_lshl_add_u64 v[102:103], v[204:205], 0, v[98:99]
	global_load_dwordx4 v[106:109], v[102:103], off offset:16
	global_load_dwordx4 v[110:113], v[102:103], off
	global_load_dwordx4 v[98:101], v[102:103], off offset:528
	s_nop 0
	global_load_dwordx4 v[102:105], v[102:103], off offset:512
	v_lshlrev_b64 v[166:167], 10, v[208:209]
	v_pk_add_f32 v[96:97], v[96:97], v[160:161]
	v_pk_add_f32 v[94:95], v[94:95], v[158:159]
	v_lshl_add_u64 v[166:167], v[166:167], 0, v[200:201]
	v_pk_add_f32 v[92:93], v[92:93], v[156:157]
	v_pk_mul_f32 v[156:157], v[96:97], v[96:97]
	v_pk_mul_f32 v[158:159], v[94:95], v[94:95]
	v_pk_add_f32 v[90:91], v[90:91], v[154:155]
	v_lshl_add_u64 v[154:155], v[166:167], 2, s[14:15]
	v_add_f32_e32 v158, v158, v159
	v_add_f32_e32 v156, v156, v157
	v_pk_add_f32 v[88:89], v[88:89], v[144:145]
	v_pk_add_f32 v[86:87], v[86:87], v[142:143]
	s_nop 1
	v_permlane16_swap_b32_e32 v94, v90
	v_permlane16_swap_b32_e32 v95, v91
	v_permlane16_swap_b32_e32 v96, v92
	v_permlane16_swap_b32_e32 v97, v93
	v_permlane32_swap_b32_e32 v94, v90
	v_permlane32_swap_b32_e32 v95, v91
	v_permlane32_swap_b32_e32 v96, v92
	v_permlane32_swap_b32_e32 v97, v93
	v_sub_co_u32_e64 v232, s[98:99], v154, v189
	v_subbrev_co_u32_e64 v233, s[98:99], 0, v155, s[98:99]
	global_store_dwordx4 v[232:233], v[94:97], off
	global_store_dwordx4 v[232:233], v[90:93], off offset:64
	s_nop 1
	v_permlane32_swap_b32_e32 v94, v90
	v_permlane32_swap_b32_e32 v95, v91
	v_permlane32_swap_b32_e32 v96, v92
	v_permlane32_swap_b32_e32 v97, v93
	v_permlane16_swap_b32_e32 v94, v90
	v_permlane16_swap_b32_e32 v95, v91
	v_permlane16_swap_b32_e32 v96, v92
	v_permlane16_swap_b32_e32 v97, v93
	v_add_f32_e32 v160, v158, v156
	v_pk_mul_f32 v[156:157], v[92:93], v[92:93]
	v_pk_mul_f32 v[158:159], v[90:91], v[90:91]
	v_cvt_pk_bf16_f32 v94, v94, v95
	v_cvt_pk_bf16_f32 v95, v96, v97
	v_cvt_pk_bf16_f32 v96, v90, v91
	v_cvt_pk_bf16_f32 v97, v92, v93
	v_pk_add_f32 v[92:93], v[84:85], v[140:141]
	v_pk_add_f32 v[90:91], v[82:83], v[138:139]
	v_pk_mul_f32 v[82:83], v[88:89], v[88:89]
	v_pk_mul_f32 v[84:85], v[86:87], v[86:87]
	v_add_f32_e32 v82, v82, v83
	v_add_f32_e32 v84, v84, v85
	v_add_f32_e32 v138, v84, v82
	v_pk_mul_f32 v[82:83], v[92:93], v[92:93]
	v_pk_mul_f32 v[84:85], v[90:91], v[90:91]
	v_add_f32_e32 v158, v158, v159
	v_add_f32_e32 v156, v156, v157
	v_add_f32_e32 v84, v84, v85
	v_add_f32_e32 v82, v82, v83
	v_add_f32_e32 v156, v158, v156
	v_add_f32_e32 v82, v84, v82
	v_add_f32_e32 v158, v160, v156
	v_add_f32_e32 v82, v138, v82
	v_add_f32_e32 v82, v158, v82
	ds_bpermute_b32 v83, v215, v82
	v_lshl_add_u64 v[156:157], v[166:167], 1, s[80:81]
	global_store_dwordx4 v[156:157], v[94:97], off
	s_nop 1
	v_permlane16_swap_b32_e32 v86, v90
	v_permlane16_swap_b32_e32 v87, v91
	v_permlane16_swap_b32_e32 v88, v92
	v_permlane16_swap_b32_e32 v89, v93
	v_permlane32_swap_b32_e32 v86, v90
	v_permlane32_swap_b32_e32 v87, v91
	v_permlane32_swap_b32_e32 v88, v92
	v_permlane32_swap_b32_e32 v89, v93
	v_sub_co_u32_e64 v232, s[98:99], v154, v189
	v_subbrev_co_u32_e64 v233, s[98:99], 0, v155, s[98:99]
	global_store_dwordx4 v[232:233], v[86:89], off offset:512
	global_store_dwordx4 v[232:233], v[90:93], off offset:576
	s_nop 1
	v_permlane32_swap_b32_e32 v86, v90
	v_permlane32_swap_b32_e32 v87, v91
	v_permlane32_swap_b32_e32 v88, v92
	v_permlane32_swap_b32_e32 v89, v93
	v_permlane16_swap_b32_e32 v86, v90
	v_permlane16_swap_b32_e32 v87, v91
	v_permlane16_swap_b32_e32 v88, v92
	v_permlane16_swap_b32_e32 v89, v93
	v_cvt_pk_bf16_f32 v84, v86, v87
	v_cvt_pk_bf16_f32 v85, v88, v89
	s_waitcnt lgkmcnt(0)
	v_add_f32_e32 v82, v82, v83
	ds_bpermute_b32 v83, v214, v82
	v_cvt_pk_bf16_f32 v86, v90, v91
	v_cvt_pk_bf16_f32 v87, v92, v93
	global_store_dwordx4 v[156:157], v[84:87], off offset:256
	s_and_saveexec_b64 s[22:23], vcc
	s_cbranch_execz .LBB0_1097
	v_lshlrev_b64 v[84:85], 6, v[208:209]
	v_lshl_add_u64 v[84:85], s[82:83], 0, v[84:85]
	v_lshl_add_u64 v[84:85], s[16:17], 2, v[84:85]
	s_lshl_b32 s34, s45, 2
	v_lshl_add_u64 v[84:85], v[84:85], 0, s[34:35]
	s_waitcnt lgkmcnt(0)
	v_add_f32_e32 v82, v82, v83
	global_store_dword v[84:85], v82, off
.LBB0_1097:
	s_or_b64 exec, exec, s[22:23]
	s_waitcnt lgkmcnt(0)
	v_lshlrev_b64 v[82:83], 10, v[206:207]
	v_pk_add_f32 v[80:81], v[80:81], v[152:153]
	v_pk_add_f32 v[78:79], v[78:79], v[150:151]
	v_lshl_add_u64 v[82:83], v[82:83], 0, v[200:201]
	v_pk_mul_f32 v[86:87], v[80:81], v[80:81]
	v_pk_mul_f32 v[88:89], v[78:79], v[78:79]
	v_pk_add_f32 v[76:77], v[76:77], v[148:149]
	v_pk_add_f32 v[74:75], v[74:75], v[146:147]
	v_lshl_add_u64 v[84:85], v[82:83], 2, s[14:15]
	v_add_f32_e32 v88, v88, v89
	v_add_f32_e32 v86, v86, v87
	v_pk_add_f32 v[72:73], v[72:73], v[136:137]
	v_pk_add_f32 v[70:71], v[70:71], v[134:135]
	s_nop 1
	v_permlane16_swap_b32_e32 v78, v74
	v_permlane16_swap_b32_e32 v79, v75
	v_permlane16_swap_b32_e32 v80, v76
	v_permlane16_swap_b32_e32 v81, v77
	v_permlane32_swap_b32_e32 v78, v74
	v_permlane32_swap_b32_e32 v79, v75
	v_permlane32_swap_b32_e32 v80, v76
	v_permlane32_swap_b32_e32 v81, v77
	v_sub_co_u32_e64 v232, s[98:99], v84, v189
	v_subbrev_co_u32_e64 v233, s[98:99], 0, v85, s[98:99]
	global_store_dwordx4 v[232:233], v[78:81], off
	global_store_dwordx4 v[232:233], v[74:77], off offset:64
	s_nop 1
	v_permlane32_swap_b32_e32 v78, v74
	v_permlane32_swap_b32_e32 v79, v75
	v_permlane32_swap_b32_e32 v80, v76
	v_permlane32_swap_b32_e32 v81, v77
	v_permlane16_swap_b32_e32 v78, v74
	v_permlane16_swap_b32_e32 v79, v75
	v_permlane16_swap_b32_e32 v80, v76
	v_permlane16_swap_b32_e32 v81, v77
	v_add_f32_e32 v90, v88, v86
	v_pk_mul_f32 v[86:87], v[76:77], v[76:77]
	v_pk_mul_f32 v[88:89], v[74:75], v[74:75]
	v_cvt_pk_bf16_f32 v78, v78, v79
	v_cvt_pk_bf16_f32 v79, v80, v81
	v_cvt_pk_bf16_f32 v80, v74, v75
	v_cvt_pk_bf16_f32 v81, v76, v77
	v_pk_add_f32 v[76:77], v[68:69], v[132:133]
	v_pk_add_f32 v[74:75], v[66:67], v[130:131]
	v_pk_mul_f32 v[66:67], v[72:73], v[72:73]
	v_pk_mul_f32 v[68:69], v[70:71], v[70:71]
	v_add_f32_e32 v66, v66, v67
	v_add_f32_e32 v68, v68, v69
	v_add_f32_e32 v86, v86, v87
	v_add_f32_e32 v87, v68, v66
	v_pk_mul_f32 v[66:67], v[76:77], v[76:77]
	v_pk_mul_f32 v[68:69], v[74:75], v[74:75]
	v_add_f32_e32 v88, v88, v89
	v_add_f32_e32 v68, v68, v69
	v_add_f32_e32 v66, v66, v67
	v_add_f32_e32 v86, v88, v86
	v_add_f32_e32 v66, v68, v66
	v_add_f32_e32 v86, v90, v86
	v_add_f32_e32 v66, v87, v66
	v_add_f32_e32 v66, v86, v66
	ds_bpermute_b32 v67, v215, v66
	v_lshl_add_u64 v[82:83], v[82:83], 1, s[80:81]
	global_store_dwordx4 v[82:83], v[78:81], off
	s_nop 1
	v_permlane16_swap_b32_e32 v70, v74
	v_permlane16_swap_b32_e32 v71, v75
	v_permlane16_swap_b32_e32 v72, v76
	v_permlane16_swap_b32_e32 v73, v77
	v_permlane32_swap_b32_e32 v70, v74
	v_permlane32_swap_b32_e32 v71, v75
	v_permlane32_swap_b32_e32 v72, v76
	v_permlane32_swap_b32_e32 v73, v77
	v_sub_co_u32_e64 v232, s[98:99], v84, v189
	v_subbrev_co_u32_e64 v233, s[98:99], 0, v85, s[98:99]
	global_store_dwordx4 v[232:233], v[70:73], off offset:512
	global_store_dwordx4 v[232:233], v[74:77], off offset:576
	s_nop 1
	v_permlane32_swap_b32_e32 v70, v74
	v_permlane32_swap_b32_e32 v71, v75
	v_permlane32_swap_b32_e32 v72, v76
	v_permlane32_swap_b32_e32 v73, v77
	v_permlane16_swap_b32_e32 v70, v74
	v_permlane16_swap_b32_e32 v71, v75
	v_permlane16_swap_b32_e32 v72, v76
	v_permlane16_swap_b32_e32 v73, v77
	v_cvt_pk_bf16_f32 v68, v70, v71
	v_cvt_pk_bf16_f32 v69, v72, v73
	s_waitcnt lgkmcnt(0)
	v_add_f32_e32 v66, v66, v67
	ds_bpermute_b32 v67, v214, v66
	v_cvt_pk_bf16_f32 v70, v74, v75
	v_cvt_pk_bf16_f32 v71, v76, v77
	global_store_dwordx4 v[82:83], v[68:71], off offset:256
	s_and_saveexec_b64 s[22:23], vcc
	s_cbranch_execz .LBB0_1099
	v_lshlrev_b64 v[68:69], 6, v[206:207]
	v_lshl_add_u64 v[68:69], s[82:83], 0, v[68:69]
	v_lshl_add_u64 v[68:69], s[16:17], 2, v[68:69]
	s_lshl_b32 s34, s45, 2
	v_lshl_add_u64 v[68:69], v[68:69], 0, s[34:35]
	s_waitcnt lgkmcnt(0)
	v_add_f32_e32 v66, v66, v67
	global_store_dword v[68:69], v66, off
.LBB0_1099:
	s_or_b64 exec, exec, s[22:23]
	v_add_u32_e32 v132, 0xa0, v202
	v_ashrrev_i32_e32 v133, 31, v132
	s_waitcnt lgkmcnt(0)
	v_lshlrev_b64 v[66:67], 12, v[132:133]
	v_add_u32_e32 v130, 0xb0, v202
	v_lshl_add_u64 v[66:67], v[204:205], 0, v[66:67]
	v_ashrrev_i32_e32 v131, 31, v130
	global_load_dwordx4 v[90:93], v[66:67], off offset:16
	global_load_dwordx4 v[94:97], v[66:67], off
	global_load_dwordx4 v[82:85], v[66:67], off offset:528
	global_load_dwordx4 v[86:89], v[66:67], off offset:512
	v_lshlrev_b64 v[66:67], 12, v[130:131]
	v_lshl_add_u64 v[70:71], v[204:205], 0, v[66:67]
	global_load_dwordx4 v[74:77], v[70:71], off offset:16
	global_load_dwordx4 v[78:81], v[70:71], off
	global_load_dwordx4 v[66:69], v[70:71], off offset:528
	s_nop 0
	global_load_dwordx4 v[70:73], v[70:71], off offset:512
	v_lshlrev_b64 v[134:135], 10, v[164:165]
	s_waitcnt vmcnt(26)
	v_pk_add_f32 v[64:65], v[64:65], v[128:129]
	v_pk_add_f32 v[62:63], v[62:63], v[126:127]
	v_lshl_add_u64 v[134:135], v[134:135], 0, v[200:201]
	v_pk_add_f32 v[60:61], v[60:61], v[124:125]
	v_pk_mul_f32 v[124:125], v[64:65], v[64:65]
	v_pk_mul_f32 v[126:127], v[62:63], v[62:63]
	v_pk_add_f32 v[58:59], v[58:59], v[122:123]
	v_lshl_add_u64 v[122:123], v[134:135], 2, s[14:15]
	v_add_f32_e32 v126, v126, v127
	v_add_f32_e32 v124, v124, v125
	s_waitcnt vmcnt(24)
	v_pk_add_f32 v[56:57], v[56:57], v[120:121]
	v_pk_add_f32 v[54:55], v[54:55], v[118:119]
	s_nop 1
	v_permlane16_swap_b32_e32 v62, v58
	v_permlane16_swap_b32_e32 v63, v59
	v_permlane16_swap_b32_e32 v64, v60
	v_permlane16_swap_b32_e32 v65, v61
	v_permlane32_swap_b32_e32 v62, v58
	v_permlane32_swap_b32_e32 v63, v59
	v_permlane32_swap_b32_e32 v64, v60
	v_permlane32_swap_b32_e32 v65, v61
	v_sub_co_u32_e64 v232, s[98:99], v122, v189
	v_subbrev_co_u32_e64 v233, s[98:99], 0, v123, s[98:99]
	global_store_dwordx4 v[232:233], v[62:65], off
	global_store_dwordx4 v[232:233], v[58:61], off offset:64
	s_nop 1
	v_permlane32_swap_b32_e32 v62, v58
	v_permlane32_swap_b32_e32 v63, v59
	v_permlane32_swap_b32_e32 v64, v60
	v_permlane32_swap_b32_e32 v65, v61
	v_permlane16_swap_b32_e32 v62, v58
	v_permlane16_swap_b32_e32 v63, v59
	v_permlane16_swap_b32_e32 v64, v60
	v_permlane16_swap_b32_e32 v65, v61
	v_add_f32_e32 v128, v126, v124
	v_pk_mul_f32 v[124:125], v[60:61], v[60:61]
	v_pk_mul_f32 v[126:127], v[58:59], v[58:59]
	v_cvt_pk_bf16_f32 v62, v62, v63
	v_cvt_pk_bf16_f32 v63, v64, v65
	v_cvt_pk_bf16_f32 v64, v58, v59
	v_cvt_pk_bf16_f32 v65, v60, v61
	v_pk_add_f32 v[60:61], v[52:53], v[116:117]
	v_pk_add_f32 v[58:59], v[50:51], v[114:115]
	v_pk_mul_f32 v[50:51], v[56:57], v[56:57]
	v_pk_mul_f32 v[52:53], v[54:55], v[54:55]
	v_add_f32_e32 v50, v50, v51
	v_add_f32_e32 v52, v52, v53
	v_add_f32_e32 v114, v52, v50
	v_pk_mul_f32 v[50:51], v[60:61], v[60:61]
	v_pk_mul_f32 v[52:53], v[58:59], v[58:59]
	v_add_f32_e32 v126, v126, v127
	v_add_f32_e32 v124, v124, v125
	v_add_f32_e32 v52, v52, v53
	v_add_f32_e32 v50, v50, v51
	v_add_f32_e32 v124, v126, v124
	v_add_f32_e32 v50, v52, v50
	v_add_f32_e32 v126, v128, v124
	v_add_f32_e32 v50, v114, v50
	v_add_f32_e32 v50, v126, v50
	ds_bpermute_b32 v51, v215, v50
	v_lshl_add_u64 v[124:125], v[134:135], 1, s[80:81]
	global_store_dwordx4 v[124:125], v[62:65], off
	s_nop 1
	v_permlane16_swap_b32_e32 v54, v58
	v_permlane16_swap_b32_e32 v55, v59
	v_permlane16_swap_b32_e32 v56, v60
	v_permlane16_swap_b32_e32 v57, v61
	v_permlane32_swap_b32_e32 v54, v58
	v_permlane32_swap_b32_e32 v55, v59
	v_permlane32_swap_b32_e32 v56, v60
	v_permlane32_swap_b32_e32 v57, v61
	v_sub_co_u32_e64 v232, s[98:99], v122, v189
	v_subbrev_co_u32_e64 v233, s[98:99], 0, v123, s[98:99]
	global_store_dwordx4 v[232:233], v[54:57], off offset:512
	global_store_dwordx4 v[232:233], v[58:61], off offset:576
	s_nop 1
	v_permlane32_swap_b32_e32 v54, v58
	v_permlane32_swap_b32_e32 v55, v59
	v_permlane32_swap_b32_e32 v56, v60
	v_permlane32_swap_b32_e32 v57, v61
	v_permlane16_swap_b32_e32 v54, v58
	v_permlane16_swap_b32_e32 v55, v59
	v_permlane16_swap_b32_e32 v56, v60
	v_permlane16_swap_b32_e32 v57, v61
	v_cvt_pk_bf16_f32 v52, v54, v55
	v_cvt_pk_bf16_f32 v53, v56, v57
	s_waitcnt lgkmcnt(0)
	v_add_f32_e32 v50, v50, v51
	ds_bpermute_b32 v51, v214, v50
	v_cvt_pk_bf16_f32 v54, v58, v59
	v_cvt_pk_bf16_f32 v55, v60, v61
	global_store_dwordx4 v[124:125], v[52:55], off offset:256
	s_and_saveexec_b64 s[22:23], vcc
	s_cbranch_execz .LBB0_1101
	v_lshlrev_b64 v[52:53], 6, v[164:165]
	v_lshl_add_u64 v[52:53], s[82:83], 0, v[52:53]
	v_lshl_add_u64 v[52:53], s[16:17], 2, v[52:53]
	s_lshl_b32 s34, s45, 2
	v_lshl_add_u64 v[52:53], v[52:53], 0, s[34:35]
	s_waitcnt lgkmcnt(0)
	v_add_f32_e32 v50, v50, v51
	global_store_dword v[52:53], v50, off
.LBB0_1101:
	s_or_b64 exec, exec, s[22:23]
	s_waitcnt lgkmcnt(0)
	v_lshlrev_b64 v[50:51], 10, v[162:163]
	s_waitcnt vmcnt(28)
	v_pk_add_f32 v[48:49], v[48:49], v[112:113]
	v_pk_add_f32 v[46:47], v[46:47], v[110:111]
	v_lshl_add_u64 v[50:51], v[50:51], 0, v[200:201]
	v_pk_mul_f32 v[54:55], v[48:49], v[48:49]
	v_pk_mul_f32 v[56:57], v[46:47], v[46:47]
	v_pk_add_f32 v[44:45], v[44:45], v[108:109]
	v_pk_add_f32 v[42:43], v[42:43], v[106:107]
	v_lshl_add_u64 v[52:53], v[50:51], 2, s[14:15]
	v_add_f32_e32 v56, v56, v57
	v_add_f32_e32 v54, v54, v55
	s_waitcnt vmcnt(26)
	v_pk_add_f32 v[40:41], v[40:41], v[104:105]
	v_pk_add_f32 v[38:39], v[38:39], v[102:103]
	s_nop 1
	v_permlane16_swap_b32_e32 v46, v42
	v_permlane16_swap_b32_e32 v47, v43
	v_permlane16_swap_b32_e32 v48, v44
	v_permlane16_swap_b32_e32 v49, v45
	v_permlane32_swap_b32_e32 v46, v42
	v_permlane32_swap_b32_e32 v47, v43
	v_permlane32_swap_b32_e32 v48, v44
	v_permlane32_swap_b32_e32 v49, v45
	v_sub_co_u32_e64 v232, s[98:99], v52, v189
	v_subbrev_co_u32_e64 v233, s[98:99], 0, v53, s[98:99]
	global_store_dwordx4 v[232:233], v[46:49], off
	global_store_dwordx4 v[232:233], v[42:45], off offset:64
	s_nop 1
	v_permlane32_swap_b32_e32 v46, v42
	v_permlane32_swap_b32_e32 v47, v43
	v_permlane32_swap_b32_e32 v48, v44
	v_permlane32_swap_b32_e32 v49, v45
	v_permlane16_swap_b32_e32 v46, v42
	v_permlane16_swap_b32_e32 v47, v43
	v_permlane16_swap_b32_e32 v48, v44
	v_permlane16_swap_b32_e32 v49, v45
	v_add_f32_e32 v58, v56, v54
	v_pk_mul_f32 v[54:55], v[44:45], v[44:45]
	v_pk_mul_f32 v[56:57], v[42:43], v[42:43]
	v_cvt_pk_bf16_f32 v46, v46, v47
	v_cvt_pk_bf16_f32 v47, v48, v49
	v_cvt_pk_bf16_f32 v48, v42, v43
	v_cvt_pk_bf16_f32 v49, v44, v45
	v_pk_add_f32 v[44:45], v[36:37], v[100:101]
	v_pk_add_f32 v[42:43], v[34:35], v[98:99]
	v_pk_mul_f32 v[34:35], v[40:41], v[40:41]
	v_pk_mul_f32 v[36:37], v[38:39], v[38:39]
	v_add_f32_e32 v34, v34, v35
	v_add_f32_e32 v36, v36, v37
	v_add_f32_e32 v54, v54, v55
	v_add_f32_e32 v55, v36, v34
	v_pk_mul_f32 v[34:35], v[44:45], v[44:45]
	v_pk_mul_f32 v[36:37], v[42:43], v[42:43]
	v_add_f32_e32 v56, v56, v57
	v_add_f32_e32 v36, v36, v37
	v_add_f32_e32 v34, v34, v35
	v_add_f32_e32 v54, v56, v54
	v_add_f32_e32 v34, v36, v34
	v_add_f32_e32 v54, v58, v54
	v_add_f32_e32 v34, v55, v34
	v_add_f32_e32 v34, v54, v34
	ds_bpermute_b32 v35, v215, v34
	v_lshl_add_u64 v[50:51], v[50:51], 1, s[80:81]
	global_store_dwordx4 v[50:51], v[46:49], off
	s_nop 1
	v_permlane16_swap_b32_e32 v38, v42
	v_permlane16_swap_b32_e32 v39, v43
	v_permlane16_swap_b32_e32 v40, v44
	v_permlane16_swap_b32_e32 v41, v45
	v_permlane32_swap_b32_e32 v38, v42
	v_permlane32_swap_b32_e32 v39, v43
	v_permlane32_swap_b32_e32 v40, v44
	v_permlane32_swap_b32_e32 v41, v45
	v_sub_co_u32_e64 v232, s[98:99], v52, v189
	v_subbrev_co_u32_e64 v233, s[98:99], 0, v53, s[98:99]
	global_store_dwordx4 v[232:233], v[38:41], off offset:512
	global_store_dwordx4 v[232:233], v[42:45], off offset:576
	s_nop 1
	v_permlane32_swap_b32_e32 v38, v42
	v_permlane32_swap_b32_e32 v39, v43
	v_permlane32_swap_b32_e32 v40, v44
	v_permlane32_swap_b32_e32 v41, v45
	v_permlane16_swap_b32_e32 v38, v42
	v_permlane16_swap_b32_e32 v39, v43
	v_permlane16_swap_b32_e32 v40, v44
	v_permlane16_swap_b32_e32 v41, v45
	v_cvt_pk_bf16_f32 v36, v38, v39
	v_cvt_pk_bf16_f32 v37, v40, v41
	s_waitcnt lgkmcnt(0)
	v_add_f32_e32 v34, v34, v35
	ds_bpermute_b32 v35, v214, v34
	v_cvt_pk_bf16_f32 v38, v42, v43
	v_cvt_pk_bf16_f32 v39, v44, v45
	global_store_dwordx4 v[50:51], v[36:39], off offset:256
	s_and_saveexec_b64 s[22:23], vcc
	s_cbranch_execz .LBB0_1103
	v_lshlrev_b64 v[36:37], 6, v[162:163]
	v_lshl_add_u64 v[36:37], s[82:83], 0, v[36:37]
	v_lshl_add_u64 v[36:37], s[16:17], 2, v[36:37]
	s_lshl_b32 s34, s45, 2
	v_lshl_add_u64 v[36:37], v[36:37], 0, s[34:35]
	s_waitcnt lgkmcnt(0)
	v_add_f32_e32 v34, v34, v35
	global_store_dword v[36:37], v34, off
.LBB0_1103:
	s_or_b64 exec, exec, s[22:23]
	s_waitcnt lgkmcnt(0)
	v_lshlrev_b64 v[34:35], 10, v[132:133]
	s_waitcnt vmcnt(18)
	v_pk_add_f32 v[32:33], v[32:33], v[96:97]
	v_pk_add_f32 v[30:31], v[30:31], v[94:95]
	v_lshl_add_u64 v[34:35], v[34:35], 0, v[200:201]
	v_pk_mul_f32 v[38:39], v[32:33], v[32:33]
	v_pk_mul_f32 v[40:41], v[30:31], v[30:31]
	v_pk_add_f32 v[28:29], v[28:29], v[92:93]
	v_pk_add_f32 v[26:27], v[26:27], v[90:91]
	v_lshl_add_u64 v[36:37], v[34:35], 2, s[14:15]
	v_add_f32_e32 v40, v40, v41
	v_add_f32_e32 v38, v38, v39
	s_waitcnt vmcnt(16)
	v_pk_add_f32 v[24:25], v[24:25], v[88:89]
	v_pk_add_f32 v[22:23], v[22:23], v[86:87]
	s_nop 1
	v_permlane16_swap_b32_e32 v30, v26
	v_permlane16_swap_b32_e32 v31, v27
	v_permlane16_swap_b32_e32 v32, v28
	v_permlane16_swap_b32_e32 v33, v29
	v_permlane32_swap_b32_e32 v30, v26
	v_permlane32_swap_b32_e32 v31, v27
	v_permlane32_swap_b32_e32 v32, v28
	v_permlane32_swap_b32_e32 v33, v29
	v_sub_co_u32_e64 v232, s[98:99], v36, v189
	v_subbrev_co_u32_e64 v233, s[98:99], 0, v37, s[98:99]
	global_store_dwordx4 v[232:233], v[30:33], off
	global_store_dwordx4 v[232:233], v[26:29], off offset:64
	s_nop 1
	v_permlane32_swap_b32_e32 v30, v26
	v_permlane32_swap_b32_e32 v31, v27
	v_permlane32_swap_b32_e32 v32, v28
	v_permlane32_swap_b32_e32 v33, v29
	v_permlane16_swap_b32_e32 v30, v26
	v_permlane16_swap_b32_e32 v31, v27
	v_permlane16_swap_b32_e32 v32, v28
	v_permlane16_swap_b32_e32 v33, v29
	v_add_f32_e32 v42, v40, v38
	v_pk_mul_f32 v[38:39], v[28:29], v[28:29]
	v_pk_mul_f32 v[40:41], v[26:27], v[26:27]
	v_cvt_pk_bf16_f32 v30, v30, v31
	v_cvt_pk_bf16_f32 v31, v32, v33
	v_cvt_pk_bf16_f32 v32, v26, v27
	v_cvt_pk_bf16_f32 v33, v28, v29
	v_pk_add_f32 v[28:29], v[20:21], v[84:85]
	v_pk_add_f32 v[26:27], v[18:19], v[82:83]
	v_pk_mul_f32 v[18:19], v[24:25], v[24:25]
	v_pk_mul_f32 v[20:21], v[22:23], v[22:23]
	v_add_f32_e32 v18, v18, v19
	v_add_f32_e32 v20, v20, v21
	v_add_f32_e32 v38, v38, v39
	v_add_f32_e32 v39, v20, v18
	v_pk_mul_f32 v[18:19], v[28:29], v[28:29]
	v_pk_mul_f32 v[20:21], v[26:27], v[26:27]
	v_add_f32_e32 v40, v40, v41
	v_add_f32_e32 v20, v20, v21
	v_add_f32_e32 v18, v18, v19
	v_add_f32_e32 v38, v40, v38
	v_add_f32_e32 v18, v20, v18
	v_add_f32_e32 v38, v42, v38
	v_add_f32_e32 v18, v39, v18
	v_add_f32_e32 v18, v38, v18
	ds_bpermute_b32 v19, v215, v18
	v_lshl_add_u64 v[34:35], v[34:35], 1, s[80:81]
	global_store_dwordx4 v[34:35], v[30:33], off
	s_nop 1
	v_permlane16_swap_b32_e32 v22, v26
	v_permlane16_swap_b32_e32 v23, v27
	v_permlane16_swap_b32_e32 v24, v28
	v_permlane16_swap_b32_e32 v25, v29
	v_permlane32_swap_b32_e32 v22, v26
	v_permlane32_swap_b32_e32 v23, v27
	v_permlane32_swap_b32_e32 v24, v28
	v_permlane32_swap_b32_e32 v25, v29
	v_sub_co_u32_e64 v232, s[98:99], v36, v189
	v_subbrev_co_u32_e64 v233, s[98:99], 0, v37, s[98:99]
	global_store_dwordx4 v[232:233], v[22:25], off offset:512
	global_store_dwordx4 v[232:233], v[26:29], off offset:576
	s_nop 1
	v_permlane32_swap_b32_e32 v22, v26
	v_permlane32_swap_b32_e32 v23, v27
	v_permlane32_swap_b32_e32 v24, v28
	v_permlane32_swap_b32_e32 v25, v29
	v_permlane16_swap_b32_e32 v22, v26
	v_permlane16_swap_b32_e32 v23, v27
	v_permlane16_swap_b32_e32 v24, v28
	v_permlane16_swap_b32_e32 v25, v29
	v_cvt_pk_bf16_f32 v20, v22, v23
	v_cvt_pk_bf16_f32 v21, v24, v25
	s_waitcnt lgkmcnt(0)
	v_add_f32_e32 v18, v18, v19
	ds_bpermute_b32 v19, v214, v18
	v_cvt_pk_bf16_f32 v22, v26, v27
	v_cvt_pk_bf16_f32 v23, v28, v29
	global_store_dwordx4 v[34:35], v[20:23], off offset:256
	s_and_saveexec_b64 s[22:23], vcc
	s_cbranch_execz .LBB0_1105
	v_lshlrev_b64 v[20:21], 6, v[132:133]
	v_lshl_add_u64 v[20:21], s[82:83], 0, v[20:21]
	v_lshl_add_u64 v[20:21], s[16:17], 2, v[20:21]
	s_lshl_b32 s34, s45, 2
	v_lshl_add_u64 v[20:21], v[20:21], 0, s[34:35]
	s_waitcnt lgkmcnt(0)
	v_add_f32_e32 v18, v18, v19
	global_store_dword v[20:21], v18, off
.LBB0_1105:
	s_or_b64 exec, exec, s[22:23]
	s_waitcnt lgkmcnt(0)
	v_lshlrev_b64 v[18:19], 10, v[130:131]
	s_waitcnt vmcnt(20)
	v_pk_add_f32 v[16:17], v[16:17], v[80:81]
	v_pk_add_f32 v[14:15], v[14:15], v[78:79]
	v_lshl_add_u64 v[18:19], v[18:19], 0, v[200:201]
	v_pk_mul_f32 v[22:23], v[16:17], v[16:17]
	v_pk_mul_f32 v[24:25], v[14:15], v[14:15]
	v_pk_add_f32 v[12:13], v[12:13], v[76:77]
	v_pk_add_f32 v[10:11], v[10:11], v[74:75]
	v_lshl_add_u64 v[20:21], v[18:19], 2, s[14:15]
	v_add_f32_e32 v24, v24, v25
	v_add_f32_e32 v22, v22, v23
	s_waitcnt vmcnt(18)
	v_pk_add_f32 v[8:9], v[8:9], v[72:73]
	v_pk_add_f32 v[6:7], v[6:7], v[70:71]
	s_nop 1
	v_permlane16_swap_b32_e32 v14, v10
	v_permlane16_swap_b32_e32 v15, v11
	v_permlane16_swap_b32_e32 v16, v12
	v_permlane16_swap_b32_e32 v17, v13
	v_permlane32_swap_b32_e32 v14, v10
	v_permlane32_swap_b32_e32 v15, v11
	v_permlane32_swap_b32_e32 v16, v12
	v_permlane32_swap_b32_e32 v17, v13
	v_sub_co_u32_e64 v232, s[98:99], v20, v189
	v_subbrev_co_u32_e64 v233, s[98:99], 0, v21, s[98:99]
	global_store_dwordx4 v[232:233], v[14:17], off
	global_store_dwordx4 v[232:233], v[10:13], off offset:64
	s_nop 1
	v_permlane32_swap_b32_e32 v14, v10
	v_permlane32_swap_b32_e32 v15, v11
	v_permlane32_swap_b32_e32 v16, v12
	v_permlane32_swap_b32_e32 v17, v13
	v_permlane16_swap_b32_e32 v14, v10
	v_permlane16_swap_b32_e32 v15, v11
	v_permlane16_swap_b32_e32 v16, v12
	v_permlane16_swap_b32_e32 v17, v13
	v_add_f32_e32 v26, v24, v22
	v_pk_mul_f32 v[22:23], v[12:13], v[12:13]
	v_pk_mul_f32 v[24:25], v[10:11], v[10:11]
	v_cvt_pk_bf16_f32 v14, v14, v15
	v_cvt_pk_bf16_f32 v15, v16, v17
	v_cvt_pk_bf16_f32 v16, v10, v11
	v_cvt_pk_bf16_f32 v17, v12, v13
	v_pk_add_f32 v[12:13], v[4:5], v[68:69]
	v_pk_add_f32 v[10:11], v[2:3], v[66:67]
	v_pk_mul_f32 v[2:3], v[8:9], v[8:9]
	v_pk_mul_f32 v[4:5], v[6:7], v[6:7]
	v_add_f32_e32 v2, v2, v3
	v_add_f32_e32 v4, v4, v5
	v_add_f32_e32 v22, v22, v23
	v_add_f32_e32 v23, v4, v2
	v_pk_mul_f32 v[2:3], v[12:13], v[12:13]
	v_pk_mul_f32 v[4:5], v[10:11], v[10:11]
	v_add_f32_e32 v24, v24, v25
	v_add_f32_e32 v4, v4, v5
	v_add_f32_e32 v2, v2, v3
	v_add_f32_e32 v22, v24, v22
	v_add_f32_e32 v2, v4, v2
	v_add_f32_e32 v22, v26, v22
	v_add_f32_e32 v2, v23, v2
	v_add_f32_e32 v2, v22, v2
	ds_bpermute_b32 v3, v215, v2
	v_lshl_add_u64 v[18:19], v[18:19], 1, s[80:81]
	global_store_dwordx4 v[18:19], v[14:17], off
	s_nop 1
	v_permlane16_swap_b32_e32 v6, v10
	v_permlane16_swap_b32_e32 v7, v11
	v_permlane16_swap_b32_e32 v8, v12
	v_permlane16_swap_b32_e32 v9, v13
	v_permlane32_swap_b32_e32 v6, v10
	v_permlane32_swap_b32_e32 v7, v11
	v_permlane32_swap_b32_e32 v8, v12
	v_permlane32_swap_b32_e32 v9, v13
	v_sub_co_u32_e64 v232, s[98:99], v20, v189
	v_subbrev_co_u32_e64 v233, s[98:99], 0, v21, s[98:99]
	global_store_dwordx4 v[232:233], v[6:9], off offset:512
	global_store_dwordx4 v[232:233], v[10:13], off offset:576
	s_nop 1
	v_permlane32_swap_b32_e32 v6, v10
	v_permlane32_swap_b32_e32 v7, v11
	v_permlane32_swap_b32_e32 v8, v12
	v_permlane32_swap_b32_e32 v9, v13
	v_permlane16_swap_b32_e32 v6, v10
	v_permlane16_swap_b32_e32 v7, v11
	v_permlane16_swap_b32_e32 v8, v12
	v_permlane16_swap_b32_e32 v9, v13
	v_cvt_pk_bf16_f32 v4, v6, v7
	v_cvt_pk_bf16_f32 v5, v8, v9
	s_waitcnt lgkmcnt(0)
	v_add_f32_e32 v2, v2, v3
	ds_bpermute_b32 v3, v214, v2
	v_cvt_pk_bf16_f32 v6, v10, v11
	v_cvt_pk_bf16_f32 v7, v12, v13
	global_store_dwordx4 v[18:19], v[4:7], off offset:256
	s_and_saveexec_b64 s[22:23], vcc
	s_cbranch_execz .LBB0_1078
	s_waitcnt lgkmcnt(0)
	v_add_f32_e32 v4, v2, v3
	v_lshlrev_b64 v[2:3], 6, v[130:131]
	v_lshl_add_u64 v[2:3], s[82:83], 0, v[2:3]
	v_lshl_add_u64 v[2:3], s[16:17], 2, v[2:3]
	s_lshl_b32 s34, s45, 2
	v_lshl_add_u64 v[2:3], v[2:3], 0, s[34:35]
	global_store_dword v[2:3], v4, off
	s_branch .LBB0_1078

.LBB0_1209:
	s_waitcnt lgkmcnt(0)
	v_lshl_add_u64 v[194:195], s[88:89], 0, v[154:155]
	s_add_i32 m0, s39, 0xc000
	ds_read_b128 v[158:161], v171
	ds_read_b128 v[162:165], v171 offset:1024
	ds_read_b128 v[166:169], v171 offset:2048
	ds_read_b128 v[172:175], v171 offset:3072
	ds_read_b128 v[176:179], v171 offset:4096
	ds_read_b128 v[180:183], v171 offset:5120
	ds_read_b128 v[184:187], v171 offset:6144
	ds_read_b128 v[190:193], v171 offset:7168
	global_load_lds_dwordx4 v[194:195], off
	s_add_i32 m0, s39, 0xe000
	v_lshl_add_u64 v[194:195], s[88:89], 0, v[156:157]
	global_load_lds_dwordx4 v[194:195], off
	s_waitcnt lgkmcnt(8)
	s_barrier
	s_waitcnt lgkmcnt(0)
	v_mfma_f32_16x16x32_bf16 v[126:129], v[130:133], v[158:161], v[126:129]
	v_mfma_f32_16x16x32_bf16 v[122:125], v[138:141], v[158:161], v[122:125]
	v_mfma_f32_16x16x32_bf16 v[110:113], v[130:133], v[166:169], v[110:113]
	v_mfma_f32_16x16x32_bf16 v[106:109], v[138:141], v[166:169], v[106:109]
	v_mfma_f32_16x16x32_bf16 v[94:97], v[130:133], v[176:179], v[94:97]
	v_mfma_f32_16x16x32_bf16 v[90:93], v[138:141], v[176:179], v[90:93]
	v_mfma_f32_16x16x32_bf16 v[78:81], v[130:133], v[184:187], v[78:81]
	v_mfma_f32_16x16x32_bf16 v[74:77], v[138:141], v[184:187], v[74:77]
	v_mfma_f32_16x16x32_bf16 v[126:129], v[134:137], v[162:165], v[126:129]
	v_mfma_f32_16x16x32_bf16 v[122:125], v[142:145], v[162:165], v[122:125]
	v_mfma_f32_16x16x32_bf16 v[110:113], v[134:137], v[172:175], v[110:113]
	v_mfma_f32_16x16x32_bf16 v[106:109], v[142:145], v[172:175], v[106:109]
	v_mfma_f32_16x16x32_bf16 v[94:97], v[134:137], v[180:183], v[94:97]
	v_mfma_f32_16x16x32_bf16 v[90:93], v[142:145], v[180:183], v[90:93]
	v_mfma_f32_16x16x32_bf16 v[78:81], v[134:137], v[190:193], v[78:81]
	v_mfma_f32_16x16x32_bf16 v[74:77], v[142:145], v[190:193], v[74:77]
	s_barrier
	s_add_i32 s87, 0, 0x14000
	s_add_i32 s94, s94, s38
	v_add_u32_e32 v0, s87, v170
	v_lshl_add_u64 v[210:211], s[90:91], 0, v[148:149]
	s_mov_b32 m0, s94
	ds_read_b128 v[194:197], v0
	ds_read_b128 v[198:201], v0 offset:1024
	ds_read_b128 v[202:205], v0 offset:2048
	ds_read_b128 v[206:209], v0 offset:3072
	global_load_lds_dwordx4 v[210:211], off
	s_add_i32 m0, s94, 0x2000
	v_lshl_add_u64 v[212:213], s[90:91], 0, v[152:153]
	global_load_lds_dwordx4 v[212:213], off
	s_barrier
	s_waitcnt lgkmcnt(0)
	v_mfma_f32_16x16x32_bf16 v[118:121], v[194:197], v[158:161], v[118:121]
	v_mfma_f32_16x16x32_bf16 v[114:117], v[202:205], v[158:161], v[114:117]
	v_mfma_f32_16x16x32_bf16 v[102:105], v[194:197], v[166:169], v[102:105]
	v_mfma_f32_16x16x32_bf16 v[98:101], v[202:205], v[166:169], v[98:101]
	v_mfma_f32_16x16x32_bf16 v[86:89], v[194:197], v[176:179], v[86:89]
	v_mfma_f32_16x16x32_bf16 v[82:85], v[202:205], v[176:179], v[82:85]
	v_mfma_f32_16x16x32_bf16 v[70:73], v[194:197], v[184:187], v[70:73]
	v_mfma_f32_16x16x32_bf16 v[66:69], v[202:205], v[184:187], v[66:69]
	v_mfma_f32_16x16x32_bf16 v[118:121], v[198:201], v[162:165], v[118:121]
	v_mfma_f32_16x16x32_bf16 v[114:117], v[206:209], v[162:165], v[114:117]
	v_mfma_f32_16x16x32_bf16 v[102:105], v[198:201], v[172:175], v[102:105]
	v_mfma_f32_16x16x32_bf16 v[98:101], v[206:209], v[172:175], v[98:101]
	v_mfma_f32_16x16x32_bf16 v[86:89], v[198:201], v[180:183], v[86:89]
	v_mfma_f32_16x16x32_bf16 v[82:85], v[206:209], v[180:183], v[82:85]
	v_mfma_f32_16x16x32_bf16 v[70:73], v[198:201], v[190:193], v[70:73]
	v_mfma_f32_16x16x32_bf16 v[66:69], v[206:209], v[190:193], v[66:69]
	s_mov_b32 m0, s39
	v_lshl_add_u64 v[214:215], s[92:93], 0, v[146:147]
	s_barrier
	ds_read_b128 v[158:161], v171 offset:16384
	ds_read_b128 v[162:165], v171 offset:17408
	ds_read_b128 v[166:169], v171 offset:18432
	ds_read_b128 v[172:175], v171 offset:19456
	ds_read_b128 v[176:179], v171 offset:20480
	ds_read_b128 v[180:183], v171 offset:21504
	ds_read_b128 v[184:187], v171 offset:22528
	ds_read_b128 v[190:193], v171 offset:23552
	global_load_lds_dwordx4 v[214:215], off
	s_mov_b32 m0, s42
	v_lshl_add_u64 v[216:217], s[92:93], 0, v[150:151]
	global_load_lds_dwordx4 v[216:217], off
	s_waitcnt vmcnt(10)
	s_barrier
	s_waitcnt lgkmcnt(0)
	v_mfma_f32_16x16x32_bf16 v[62:65], v[130:133], v[158:161], v[62:65]
	v_mfma_f32_16x16x32_bf16 v[58:61], v[138:141], v[158:161], v[58:61]
	v_mfma_f32_16x16x32_bf16 v[46:49], v[130:133], v[166:169], v[46:49]
	v_mfma_f32_16x16x32_bf16 v[42:45], v[138:141], v[166:169], v[42:45]
	v_mfma_f32_16x16x32_bf16 v[30:33], v[130:133], v[176:179], v[30:33]
	v_mfma_f32_16x16x32_bf16 v[26:29], v[138:141], v[176:179], v[26:29]
	v_mfma_f32_16x16x32_bf16 v[14:17], v[130:133], v[184:187], v[14:17]
	v_mfma_f32_16x16x32_bf16 v[10:13], v[138:141], v[184:187], v[10:13]
	v_mfma_f32_16x16x32_bf16 v[62:65], v[134:137], v[162:165], v[62:65]
	v_mfma_f32_16x16x32_bf16 v[58:61], v[142:145], v[162:165], v[58:61]
	v_mfma_f32_16x16x32_bf16 v[46:49], v[134:137], v[172:175], v[46:49]
	v_mfma_f32_16x16x32_bf16 v[42:45], v[142:145], v[172:175], v[42:45]
	v_mfma_f32_16x16x32_bf16 v[30:33], v[134:137], v[180:183], v[30:33]
	v_mfma_f32_16x16x32_bf16 v[26:29], v[142:145], v[180:183], v[26:29]
	v_mfma_f32_16x16x32_bf16 v[14:17], v[134:137], v[190:193], v[14:17]
	v_mfma_f32_16x16x32_bf16 v[10:13], v[142:145], v[190:193], v[10:13]
	s_barrier
	s_add_u32 s94, s90, 0x40000
	s_addc_u32 s95, s91, 0
	s_add_i32 s87, s87, s38
	s_mov_b32 m0, s87
	v_lshl_add_u64 v[130:131], s[94:95], 0, v[148:149]
	global_load_lds_dwordx4 v[130:131], off
	s_add_i32 m0, s87, 0x2000
	v_lshl_add_u64 v[130:131], s[94:95], 0, v[152:153]
	global_load_lds_dwordx4 v[130:131], off
	s_add_i32 s87, 0, 0x18000
	v_add_u32_e32 v0, s87, v170
	ds_read_b128 v[130:133], v0
	ds_read_b128 v[134:137], v0 offset:1024
	ds_read_b128 v[138:141], v0 offset:2048
	ds_read_b128 v[142:145], v0 offset:3072
	s_waitcnt vmcnt(6)
	s_barrier
	v_mfma_f32_16x16x32_bf16 v[54:57], v[194:197], v[158:161], v[54:57]
	v_mfma_f32_16x16x32_bf16 v[50:53], v[202:205], v[158:161], v[50:53]
	v_mfma_f32_16x16x32_bf16 v[38:41], v[194:197], v[166:169], v[38:41]
	v_mfma_f32_16x16x32_bf16 v[34:37], v[202:205], v[166:169], v[34:37]
	v_mfma_f32_16x16x32_bf16 v[22:25], v[194:197], v[176:179], v[22:25]
	v_mfma_f32_16x16x32_bf16 v[18:21], v[202:205], v[176:179], v[18:21]
	v_mfma_f32_16x16x32_bf16 v[6:9], v[194:197], v[184:187], v[6:9]
	v_mfma_f32_16x16x32_bf16 v[2:5], v[202:205], v[184:187], v[2:5]
	v_mfma_f32_16x16x32_bf16 v[54:57], v[198:201], v[162:165], v[54:57]
	v_mfma_f32_16x16x32_bf16 v[50:53], v[206:209], v[162:165], v[50:53]
	v_mfma_f32_16x16x32_bf16 v[38:41], v[198:201], v[172:175], v[38:41]
	v_mfma_f32_16x16x32_bf16 v[34:37], v[206:209], v[172:175], v[34:37]
	v_mfma_f32_16x16x32_bf16 v[22:25], v[198:201], v[180:183], v[22:25]
	v_mfma_f32_16x16x32_bf16 v[18:21], v[206:209], v[180:183], v[18:21]
	v_mfma_f32_16x16x32_bf16 v[6:9], v[198:201], v[190:193], v[6:9]
	v_mfma_f32_16x16x32_bf16 v[2:5], v[206:209], v[190:193], v[2:5]
	s_barrier
	s_add_u32 s92, s92, 0x40000
	s_addc_u32 s93, s93, 0
	s_mov_b32 m0, s43
	v_lshl_add_u64 v[194:195], s[92:93], 0, v[146:147]
	ds_read_b128 v[158:161], v171 offset:32768
	ds_read_b128 v[162:165], v171 offset:33792
	ds_read_b128 v[166:169], v171 offset:34816
	ds_read_b128 v[172:175], v171 offset:35840
	ds_read_b128 v[176:179], v171 offset:36864
	ds_read_b128 v[180:183], v171 offset:37888
	ds_read_b128 v[184:187], v171 offset:38912
	ds_read_b128 v[190:193], v171 offset:39936
	global_load_lds_dwordx4 v[194:195], off
	s_mov_b32 m0, s44
	v_lshl_add_u64 v[194:195], s[92:93], 0, v[150:151]
	global_load_lds_dwordx4 v[194:195], off
	s_waitcnt lgkmcnt(8)
	s_barrier
	s_waitcnt lgkmcnt(0)
	v_mfma_f32_16x16x32_bf16 v[126:129], v[130:133], v[158:161], v[126:129]
	v_mfma_f32_16x16x32_bf16 v[122:125], v[138:141], v[158:161], v[122:125]
	v_mfma_f32_16x16x32_bf16 v[110:113], v[130:133], v[166:169], v[110:113]
	v_mfma_f32_16x16x32_bf16 v[106:109], v[138:141], v[166:169], v[106:109]
	v_mfma_f32_16x16x32_bf16 v[94:97], v[130:133], v[176:179], v[94:97]
	v_mfma_f32_16x16x32_bf16 v[90:93], v[138:141], v[176:179], v[90:93]
	v_mfma_f32_16x16x32_bf16 v[78:81], v[130:133], v[184:187], v[78:81]
	v_mfma_f32_16x16x32_bf16 v[74:77], v[138:141], v[184:187], v[74:77]
	v_mfma_f32_16x16x32_bf16 v[126:129], v[134:137], v[162:165], v[126:129]
	v_mfma_f32_16x16x32_bf16 v[122:125], v[142:145], v[162:165], v[122:125]
	v_mfma_f32_16x16x32_bf16 v[110:113], v[134:137], v[172:175], v[110:113]
	v_mfma_f32_16x16x32_bf16 v[106:109], v[142:145], v[172:175], v[106:109]
	v_mfma_f32_16x16x32_bf16 v[94:97], v[134:137], v[180:183], v[94:97]
	v_mfma_f32_16x16x32_bf16 v[90:93], v[142:145], v[180:183], v[90:93]
	v_mfma_f32_16x16x32_bf16 v[78:81], v[134:137], v[190:193], v[78:81]
	v_mfma_f32_16x16x32_bf16 v[74:77], v[142:145], v[190:193], v[74:77]
	s_barrier
	s_add_i32 s92, 0, 0x1c000
	s_add_i32 s87, s87, s38
	v_add_u32_e32 v0, s92, v170
	v_lshl_add_u64 v[210:211], v[210:211], 0, s[40:41]
	s_mov_b32 m0, s87
	ds_read_b128 v[194:197], v0
	ds_read_b128 v[198:201], v0 offset:1024
	ds_read_b128 v[202:205], v0 offset:2048
	ds_read_b128 v[206:209], v0 offset:3072
	global_load_lds_dwordx4 v[210:211], off
	s_add_i32 m0, s87, 0x2000
	v_lshl_add_u64 v[210:211], v[212:213], 0, s[40:41]
	global_load_lds_dwordx4 v[210:211], off
	s_barrier
	s_waitcnt lgkmcnt(0)
	v_mfma_f32_16x16x32_bf16 v[118:121], v[194:197], v[158:161], v[118:121]
	v_mfma_f32_16x16x32_bf16 v[114:117], v[202:205], v[158:161], v[114:117]
	v_mfma_f32_16x16x32_bf16 v[102:105], v[194:197], v[166:169], v[102:105]
	v_mfma_f32_16x16x32_bf16 v[98:101], v[202:205], v[166:169], v[98:101]
	v_mfma_f32_16x16x32_bf16 v[86:89], v[194:197], v[176:179], v[86:89]
	v_mfma_f32_16x16x32_bf16 v[82:85], v[202:205], v[176:179], v[82:85]
	v_mfma_f32_16x16x32_bf16 v[70:73], v[194:197], v[184:187], v[70:73]
	v_mfma_f32_16x16x32_bf16 v[66:69], v[202:205], v[184:187], v[66:69]
	v_mfma_f32_16x16x32_bf16 v[118:121], v[198:201], v[162:165], v[118:121]
	v_mfma_f32_16x16x32_bf16 v[114:117], v[206:209], v[162:165], v[114:117]
	v_mfma_f32_16x16x32_bf16 v[102:105], v[198:201], v[172:175], v[102:105]
	v_mfma_f32_16x16x32_bf16 v[98:101], v[206:209], v[172:175], v[98:101]
	v_mfma_f32_16x16x32_bf16 v[86:89], v[198:201], v[180:183], v[86:89]
	v_mfma_f32_16x16x32_bf16 v[82:85], v[206:209], v[180:183], v[82:85]
	v_mfma_f32_16x16x32_bf16 v[70:73], v[198:201], v[190:193], v[70:73]
	v_mfma_f32_16x16x32_bf16 v[66:69], v[206:209], v[190:193], v[66:69]
	s_mov_b32 m0, s60
	v_lshl_add_u64 v[210:211], v[214:215], 0, s[40:41]
	s_barrier
	ds_read_b128 v[158:161], v171 offset:49152
	ds_read_b128 v[162:165], v171 offset:50176
	ds_read_b128 v[166:169], v171 offset:51200
	ds_read_b128 v[172:175], v171 offset:52224
	ds_read_b128 v[176:179], v171 offset:53248
	ds_read_b128 v[180:183], v171 offset:54272
	ds_read_b128 v[184:187], v171 offset:55296
	ds_read_b128 v[190:193], v171 offset:56320
	global_load_lds_dwordx4 v[210:211], off
	s_mov_b32 m0, s61
	v_lshl_add_u64 v[210:211], v[216:217], 0, s[40:41]
	global_load_lds_dwordx4 v[210:211], off
	s_waitcnt vmcnt(10)
	s_barrier
	s_waitcnt lgkmcnt(0)
	v_mfma_f32_16x16x32_bf16 v[62:65], v[130:133], v[158:161], v[62:65]
	v_mfma_f32_16x16x32_bf16 v[58:61], v[138:141], v[158:161], v[58:61]
	v_mfma_f32_16x16x32_bf16 v[46:49], v[130:133], v[166:169], v[46:49]
	v_mfma_f32_16x16x32_bf16 v[42:45], v[138:141], v[166:169], v[42:45]
	v_mfma_f32_16x16x32_bf16 v[30:33], v[130:133], v[176:179], v[30:33]
	v_mfma_f32_16x16x32_bf16 v[26:29], v[138:141], v[176:179], v[26:29]
	v_mfma_f32_16x16x32_bf16 v[14:17], v[130:133], v[184:187], v[14:17]
	v_mfma_f32_16x16x32_bf16 v[10:13], v[138:141], v[184:187], v[10:13]
	v_mfma_f32_16x16x32_bf16 v[62:65], v[134:137], v[162:165], v[62:65]
	v_mfma_f32_16x16x32_bf16 v[58:61], v[142:145], v[162:165], v[58:61]
	v_mfma_f32_16x16x32_bf16 v[46:49], v[134:137], v[172:175], v[46:49]
	v_mfma_f32_16x16x32_bf16 v[42:45], v[142:145], v[172:175], v[42:45]
	v_mfma_f32_16x16x32_bf16 v[30:33], v[134:137], v[180:183], v[30:33]
	v_mfma_f32_16x16x32_bf16 v[26:29], v[142:145], v[180:183], v[26:29]
	v_mfma_f32_16x16x32_bf16 v[14:17], v[134:137], v[190:193], v[14:17]
	v_mfma_f32_16x16x32_bf16 v[10:13], v[142:145], v[190:193], v[10:13]
	s_barrier
	s_add_u32 s90, s90, 0x40080
	s_addc_u32 s91, s91, 0
	s_add_i32 s87, s92, s38
	s_mov_b32 m0, s87
	v_lshl_add_u64 v[130:131], s[90:91], 0, v[148:149]
	global_load_lds_dwordx4 v[130:131], off
	s_add_i32 m0, s87, 0x2000
	v_lshl_add_u64 v[130:131], s[90:91], 0, v[152:153]
	global_load_lds_dwordx4 v[130:131], off
	s_add_i32 s94, 0, 0x10000
	v_add_u32_e32 v0, s94, v170
	ds_read_b128 v[130:133], v0
	ds_read_b128 v[134:137], v0 offset:1024
	ds_read_b128 v[138:141], v0 offset:2048
	ds_read_b128 v[142:145], v0 offset:3072
	s_waitcnt vmcnt(6)
	s_barrier
	v_mfma_f32_16x16x32_bf16 v[54:57], v[194:197], v[158:161], v[54:57]
	v_mfma_f32_16x16x32_bf16 v[50:53], v[202:205], v[158:161], v[50:53]
	v_mfma_f32_16x16x32_bf16 v[38:41], v[194:197], v[166:169], v[38:41]
	v_mfma_f32_16x16x32_bf16 v[34:37], v[202:205], v[166:169], v[34:37]
	v_mfma_f32_16x16x32_bf16 v[22:25], v[194:197], v[176:179], v[22:25]
	v_mfma_f32_16x16x32_bf16 v[18:21], v[202:205], v[176:179], v[18:21]
	v_mfma_f32_16x16x32_bf16 v[6:9], v[194:197], v[184:187], v[6:9]
	v_mfma_f32_16x16x32_bf16 v[2:5], v[202:205], v[184:187], v[2:5]
	v_mfma_f32_16x16x32_bf16 v[54:57], v[198:201], v[162:165], v[54:57]
	v_mfma_f32_16x16x32_bf16 v[50:53], v[206:209], v[162:165], v[50:53]
	v_mfma_f32_16x16x32_bf16 v[38:41], v[198:201], v[172:175], v[38:41]
	v_mfma_f32_16x16x32_bf16 v[34:37], v[206:209], v[172:175], v[34:37]
	v_mfma_f32_16x16x32_bf16 v[22:25], v[198:201], v[180:183], v[22:25]
	v_mfma_f32_16x16x32_bf16 v[18:21], v[206:209], v[180:183], v[18:21]
	v_mfma_f32_16x16x32_bf16 v[6:9], v[198:201], v[190:193], v[6:9]
	v_mfma_f32_16x16x32_bf16 v[2:5], v[206:209], v[190:193], v[2:5]
	s_add_i32 s85, s85, 2
	s_add_u32 s88, s88, 0x100
	s_addc_u32 s89, s89, 0
	s_add_u32 s34, s34, 0x100
	s_addc_u32 s79, s79, 0
	s_add_u32 s87, s88, 0xfffc0080
	s_addc_u32 s90, s89, -1
	s_cmp_eq_u32 s85, 12
	s_cselect_b32 s93, s13, s90
	s_cselect_b32 s92, s22, s87
	s_cselect_b32 s91, s7, s79
	s_cselect_b32 s90, s23, s34
	s_cmp_gt_u32 s85, 13
	s_barrier
	s_cbranch_scc0 .LBB0_1209
	v_bfe_u32 v189, v252, 4, 2
	v_lshlrev_b32_e32 v189, 4, v189
	s_waitcnt lgkmcnt(0)
	v_mov_b32_e32 v131, v252
	s_lshl_b32 s7, s86, 8
	v_and_b32_e32 v130, 63, v131
	v_or_b32_e32 v0, s72, v130
	v_lshrrev_b32_e32 v0, 1, v0
	v_and_or_b32 v132, v0, 63, s73
	v_add_u32_e32 v134, s7, v132
	v_ashrrev_i32_e32 v135, 31, v134
	v_and_b32_e32 v142, 1, v131
	v_lshlrev_b64 v[134:135], 6, v[134:135]
	v_lshl_add_u64 v[134:135], s[82:83], 0, v[134:135]
	v_lshlrev_b32_e32 v0, 5, v142
	v_lshl_add_u64 v[138:139], v[134:135], 0, v[0:1]
	global_load_dwordx4 v[134:137], v[138:139], off
	s_nop 0
	global_load_dwordx4 v[138:141], v[138:139], off offset:16
	v_lshlrev_b32_e32 v0, 2, v130
	v_cmp_eq_u32_e32 vcc, 0, v142
	s_waitcnt vmcnt(0)
	v_add_f32_e32 v133, v134, v135
	v_add_f32_e32 v134, v136, v137
	v_add_f32_e32 v135, v138, v139
	v_add_f32_e32 v136, v140, v141
	v_add_f32_e32 v133, v133, v134
	v_add_f32_e32 v134, v135, v136
	v_add_f32_e32 v133, v133, v134
	v_xor_b32_e32 v134, 4, v0
	ds_bpermute_b32 v134, v134, v133
	s_and_saveexec_b64 s[22:23], vcc
	s_cbranch_execz .LBB0_1212
	s_waitcnt lgkmcnt(0)
	v_add_f32_e32 v133, v133, v134
	v_fmamk_f32 v133, v133, 0x3a800000, v224
	s_mov_b32 s13, 0x800000
	v_mul_f32_e32 v134, 0x4b800000, v133
	v_cmp_gt_f32_e32 vcc, s13, v133
	v_lshl_add_u32 v132, v132, 2, 0
	v_add_u32_e32 v132, 0x20000, v132
	v_cndmask_b32_e32 v133, v133, v134, vcc
	v_rsq_f32_e32 v133, v133
	s_nop 0
	v_mul_f32_e32 v134, 0x45800000, v133
	v_cndmask_b32_e32 v133, v133, v134, vcc
	ds_write_b32 v132, v133
.LBB0_1212:
	s_or_b64 exec, exec, s[22:23]
	v_and_b32_e32 v136, 15, v131
	s_add_i32 s7, s7, s47
	v_or_b32_e32 v160, s7, v136
	s_lshl_b32 s7, s84, 8
	s_or_b32 s7, s7, s55
	v_lshrrev_b32_e32 v131, 1, v131
	v_and_or_b32 v158, v131, 24, s7
	v_ashrrev_i32_e32 v161, 31, v160
	v_ashrrev_i32_e32 v159, 31, v158
	v_lshlrev_b64 v[132:133], 10, v[160:161]
	v_lshl_add_u64 v[132:133], v[132:133], 0, v[158:159]
	v_lshlrev_b64 v[186:187], 1, v[132:133]
	s_waitcnt lgkmcnt(0)
	s_barrier
	s_waitcnt lgkmcnt(0)
	v_lshl_add_u64 v[134:135], s[24:25], 0, v[186:187]
	global_load_dwordx4 v[174:177], v[134:135], off
	v_lshl_add_u64 v[168:169], v[132:133], 2, s[4:5]
	global_load_dwordx4 v[178:181], v[168:169], off
	global_load_dwordx4 v[182:185], v[168:169], off offset:16
	v_or_b32_e32 v162, 16, v160
	v_ashrrev_i32_e32 v163, 31, v162
	v_cmp_gt_u32_e32 vcc, 16, v130
	v_lshlrev_b64 v[130:131], 10, v[162:163]
	v_lshl_add_u64 v[166:167], v[130:131], 0, v[158:159]
	v_or_b32_e32 v130, 0x100, v186
	v_mov_b32_e32 v131, v187
	v_lshl_add_u32 v173, v136, 2, s75
	v_lshl_add_u64 v[164:165], v[166:167], 2, s[4:5]
	v_lshl_add_u64 v[198:199], s[24:25], 0, v[130:131]
	ds_read_b32 v202, v173
	global_load_dwordx4 v[190:193], v[168:169], off offset:528
	global_load_dwordx4 v[194:197], v[168:169], off offset:512
	global_load_dwordx4 v[138:141], v[164:165], off offset:16
	global_load_dwordx4 v[142:145], v[164:165], off
	global_load_dwordx4 v[130:133], v[164:165], off offset:528
	global_load_dwordx4 v[134:137], v[164:165], off offset:512
	v_lshlrev_b64 v[204:205], 1, v[166:167]
	global_load_dwordx4 v[198:201], v[198:199], off
	v_lshl_add_u64 v[206:207], s[24:25], 0, v[204:205]
	v_or_b32_e32 v204, 0x100, v204
	s_waitcnt lgkmcnt(0)
	v_pk_mul_f32 v[128:129], v[128:129], v[202:203] op_sel_hi:[1,0]
	v_pk_mul_f32 v[126:127], v[126:127], v[202:203] op_sel_hi:[1,0]
	v_pk_mul_f32 v[124:125], v[124:125], v[202:203] op_sel_hi:[1,0]
	v_pk_mul_f32 v[122:123], v[122:123], v[202:203] op_sel_hi:[1,0]
	v_lshl_add_u64 v[204:205], s[24:25], 0, v[204:205]
	v_mul_f32_e32 v203, 0xbfb8aa3b, v126
	v_mul_f32_e32 v208, 0xbfb8aa3b, v122
	v_mul_f32_e32 v209, 0xbfb8aa3b, v127
	v_mul_f32_e32 v210, 0xbfb8aa3b, v123
	v_mul_f32_e32 v211, 0xbfb8aa3b, v128
	v_mul_f32_e32 v212, 0xbfb8aa3b, v124
	v_mul_f32_e32 v213, 0xbfb8aa3b, v129
	v_mul_f32_e32 v214, 0xbfb8aa3b, v125
	global_load_dwordx4 v[126:129], v[206:207], off
	global_load_dwordx4 v[122:125], v[204:205], off
	v_exp_f32_e32 v203, v203
	v_exp_f32_e32 v205, v209
	v_exp_f32_e32 v207, v211
	v_exp_f32_e32 v209, v213
	v_exp_f32_e32 v204, v208
	v_exp_f32_e32 v206, v210
	v_exp_f32_e32 v208, v212
	v_exp_f32_e32 v210, v214
	v_add_f32_e32 v203, 1.0, v203
	v_add_f32_e32 v205, 1.0, v205
	v_add_f32_e32 v213, 1.0, v207
	v_add_f32_e32 v209, 1.0, v209
	v_add_f32_e32 v211, 1.0, v204
	v_add_f32_e32 v212, 1.0, v206
	v_add_f32_e32 v214, 1.0, v208
	v_add_f32_e32 v215, 1.0, v210
	v_rcp_f32_e32 v204, v203
	v_rcp_f32_e32 v205, v205
	v_rcp_f32_e32 v208, v213
	v_rcp_f32_e32 v209, v209
	v_rcp_f32_e32 v206, v211
	v_rcp_f32_e32 v207, v212
	v_rcp_f32_e32 v210, v214
	v_rcp_f32_e32 v211, v215
	v_xor_b32_e32 v172, 64, v0
	v_xor_b32_e32 v0, 0x80, v0
	s_lshl_b32 s84, s84, 2
	s_ashr_i32 s85, s84, 31
	s_waitcnt vmcnt(11)
	v_lshlrev_b32_e32 v212, 16, v174
	v_and_b32_e32 v213, 0xffff0000, v174
	v_lshlrev_b32_e32 v174, 16, v175
	v_and_b32_e32 v175, 0xffff0000, v175
	v_lshlrev_b32_e32 v214, 16, v176
	v_and_b32_e32 v215, 0xffff0000, v176
	v_lshlrev_b32_e32 v216, 16, v177
	v_and_b32_e32 v217, 0xffff0000, v177
	s_waitcnt vmcnt(10)
	v_pk_fma_f32 v[176:177], v[208:209], v[174:175], v[180:181]
	v_pk_fma_f32 v[174:175], v[204:205], v[212:213], v[178:179]
	s_waitcnt vmcnt(9)
	v_pk_fma_f32 v[180:181], v[210:211], v[216:217], v[184:185]
	v_pk_fma_f32 v[178:179], v[206:207], v[214:215], v[182:183]
	v_pk_mul_f32 v[182:183], v[176:177], v[176:177]
	v_pk_mul_f32 v[184:185], v[174:175], v[174:175]
	v_add_f32_e32 v182, v182, v183
	v_add_f32_e32 v184, v184, v185
	v_add_f32_e32 v203, v184, v182
	v_pk_mul_f32 v[182:183], v[180:181], v[180:181]
	v_pk_mul_f32 v[184:185], v[178:179], v[178:179]
	v_add_f32_e32 v182, v182, v183
	v_add_f32_e32 v184, v184, v185
	v_add_f32_e32 v182, v184, v182
	v_add_f32_e32 v203, v203, v182
	v_pk_mul_f32 v[118:119], v[118:119], v[202:203] op_sel_hi:[1,0]
	v_pk_mul_f32 v[114:115], v[114:115], v[202:203] op_sel_hi:[1,0]
	v_mul_f32_e32 v118, 0xbfb8aa3b, v118
	v_mul_f32_e32 v114, 0xbfb8aa3b, v114
	s_nop 1
	v_permlane16_swap_b32_e32 v174, v178
	v_permlane16_swap_b32_e32 v175, v179
	v_permlane16_swap_b32_e32 v176, v180
	v_permlane16_swap_b32_e32 v177, v181
	v_permlane32_swap_b32_e32 v174, v178
	v_permlane32_swap_b32_e32 v175, v179
	v_permlane32_swap_b32_e32 v176, v180
	v_permlane32_swap_b32_e32 v177, v181
	v_sub_co_u32_e64 v232, s[98:99], v168, v189
	v_subbrev_co_u32_e64 v233, s[98:99], 0, v169, s[98:99]
	global_store_dwordx4 v[232:233], v[174:177], off
	global_store_dwordx4 v[232:233], v[178:181], off offset:64
	s_nop 1
	v_permlane32_swap_b32_e32 v174, v178
	v_permlane32_swap_b32_e32 v175, v179
	v_permlane32_swap_b32_e32 v176, v180
	v_permlane32_swap_b32_e32 v177, v181
	v_permlane16_swap_b32_e32 v174, v178
	v_permlane16_swap_b32_e32 v175, v179
	v_permlane16_swap_b32_e32 v176, v180
	v_permlane16_swap_b32_e32 v177, v181
	v_exp_f32_e32 v118, v118
	v_cvt_pk_bf16_f32 v174, v174, v175
	v_cvt_pk_bf16_f32 v175, v176, v177
	v_cvt_pk_bf16_f32 v177, v180, v181
	v_exp_f32_e32 v180, v114
	v_mul_f32_e32 v119, 0xbfb8aa3b, v119
	v_mul_f32_e32 v115, 0xbfb8aa3b, v115
	v_add_f32_e32 v114, 1.0, v118
	v_add_f32_e32 v118, 1.0, v180
	v_exp_f32_e32 v119, v119
	v_exp_f32_e32 v180, v115
	v_pk_mul_f32 v[120:121], v[120:121], v[202:203] op_sel_hi:[1,0]
	v_pk_mul_f32 v[116:117], v[116:117], v[202:203] op_sel_hi:[1,0]
	v_mul_f32_e32 v120, 0xbfb8aa3b, v120
	v_mul_f32_e32 v116, 0xbfb8aa3b, v116
	v_add_f32_e32 v115, 1.0, v119
	v_add_f32_e32 v119, 1.0, v180
	v_exp_f32_e32 v120, v120
	v_exp_f32_e32 v180, v116
	v_mul_f32_e32 v121, 0xbfb8aa3b, v121
	v_exp_f32_e32 v121, v121
	v_mul_f32_e32 v117, 0xbfb8aa3b, v117
	v_add_f32_e32 v116, 1.0, v120
	v_add_f32_e32 v120, 1.0, v180
	v_exp_f32_e32 v180, v117
	v_add_f32_e32 v117, 1.0, v121
	v_rcp_f32_e32 v114, v114
	v_rcp_f32_e32 v115, v115
	v_rcp_f32_e32 v116, v116
	v_rcp_f32_e32 v117, v117
	v_add_f32_e32 v121, 1.0, v180
	v_rcp_f32_e32 v118, v118
	v_rcp_f32_e32 v119, v119
	v_rcp_f32_e32 v120, v120
	v_rcp_f32_e32 v121, v121
	s_waitcnt vmcnt(4)
	v_lshlrev_b32_e32 v180, 16, v198
	v_and_b32_e32 v181, 0xffff0000, v198
	v_lshlrev_b32_e32 v182, 16, v199
	v_and_b32_e32 v183, 0xffff0000, v199
	v_pk_fma_f32 v[116:117], v[116:117], v[182:183], v[196:197]
	v_pk_fma_f32 v[114:115], v[114:115], v[180:181], v[194:195]
	v_cvt_pk_bf16_f32 v176, v178, v179
	v_lshl_add_u64 v[178:179], s[8:9], 0, v[186:187]
	v_lshlrev_b32_e32 v184, 16, v200
	v_and_b32_e32 v185, 0xffff0000, v200
	v_lshlrev_b32_e32 v186, 16, v201
	v_and_b32_e32 v187, 0xffff0000, v201
	v_pk_mul_f32 v[180:181], v[116:117], v[116:117]
	v_pk_mul_f32 v[182:183], v[114:115], v[114:115]
	v_pk_fma_f32 v[120:121], v[120:121], v[186:187], v[192:193]
	v_pk_fma_f32 v[118:119], v[118:119], v[184:185], v[190:191]
	v_add_f32_e32 v182, v182, v183
	v_add_f32_e32 v180, v180, v181
	v_add_f32_e32 v184, v182, v180
	v_pk_mul_f32 v[180:181], v[120:121], v[120:121]
	v_pk_mul_f32 v[182:183], v[118:119], v[118:119]
	v_add_f32_e32 v180, v180, v181
	v_add_f32_e32 v182, v182, v183
	v_add_f32_e32 v180, v182, v180
	v_add_f32_e32 v180, v184, v180
	v_add_f32_e32 v180, v203, v180
	ds_bpermute_b32 v181, v172, v180
	global_store_dwordx4 v[178:179], v[174:177], off
	s_nop 1
	v_permlane16_swap_b32_e32 v114, v118
	v_permlane16_swap_b32_e32 v115, v119
	v_permlane16_swap_b32_e32 v116, v120
	v_permlane16_swap_b32_e32 v117, v121
	v_permlane32_swap_b32_e32 v114, v118
	v_permlane32_swap_b32_e32 v115, v119
	v_permlane32_swap_b32_e32 v116, v120
	v_permlane32_swap_b32_e32 v117, v121
	v_sub_co_u32_e64 v232, s[98:99], v168, v189
	v_subbrev_co_u32_e64 v233, s[98:99], 0, v169, s[98:99]
	global_store_dwordx4 v[232:233], v[114:117], off offset:512
	global_store_dwordx4 v[232:233], v[118:121], off offset:576
	s_nop 1
	v_permlane32_swap_b32_e32 v114, v118
	v_permlane32_swap_b32_e32 v115, v119
	v_permlane32_swap_b32_e32 v116, v120
	v_permlane32_swap_b32_e32 v117, v121
	v_permlane16_swap_b32_e32 v114, v118
	v_permlane16_swap_b32_e32 v115, v119
	v_permlane16_swap_b32_e32 v116, v120
	v_permlane16_swap_b32_e32 v117, v121
	v_cvt_pk_bf16_f32 v174, v114, v115
	v_cvt_pk_bf16_f32 v175, v116, v117
	v_cvt_pk_bf16_f32 v176, v118, v119
	s_waitcnt lgkmcnt(0)
	v_add_f32_e32 v114, v180, v181
	ds_bpermute_b32 v115, v0, v114
	v_cvt_pk_bf16_f32 v177, v120, v121
	global_store_dwordx4 v[178:179], v[174:177], off offset:256
	s_and_saveexec_b64 s[22:23], vcc
	s_cbranch_execz .LBB0_1214
	v_lshlrev_b64 v[116:117], 6, v[160:161]
	v_lshl_add_u64 v[116:117], s[10:11], 0, v[116:117]
	v_lshl_add_u64 v[116:117], s[84:85], 2, v[116:117]
	s_lshl_b32 s34, s45, 2
	v_lshl_add_u64 v[116:117], v[116:117], 0, s[34:35]
	s_waitcnt lgkmcnt(0)
	v_add_f32_e32 v114, v114, v115
	global_store_dword v[116:117], v114, off
.LBB0_1214:
	s_or_b64 exec, exec, s[22:23]
	ds_read_b32 v114, v173 offset:64
	s_waitcnt vmcnt(7)
	v_and_b32_e32 v117, 0xffff0000, v126
	v_lshlrev_b32_e32 v118, 16, v127
	v_and_b32_e32 v119, 0xffff0000, v127
	v_and_b32_e32 v127, 0xffff0000, v129
	s_waitcnt lgkmcnt(0)
	v_pk_mul_f32 v[110:111], v[110:111], v[114:115] op_sel_hi:[1,0]
	v_pk_mul_f32 v[106:107], v[106:107], v[114:115] op_sel_hi:[1,0]
	v_mul_f32_e32 v110, 0xbfb8aa3b, v110
	v_mul_f32_e32 v106, 0xbfb8aa3b, v106
	v_exp_f32_e32 v110, v110
	v_exp_f32_e32 v106, v106
	v_pk_mul_f32 v[112:113], v[112:113], v[114:115] op_sel_hi:[1,0]
	v_pk_mul_f32 v[108:109], v[108:109], v[114:115] op_sel_hi:[1,0]
	v_mul_f32_e32 v111, 0xbfb8aa3b, v111
	v_add_f32_e32 v110, 1.0, v110
	v_add_f32_e32 v115, 1.0, v106
	v_mul_f32_e32 v112, 0xbfb8aa3b, v112
	v_mul_f32_e32 v108, 0xbfb8aa3b, v108
	v_mul_f32_e32 v113, 0xbfb8aa3b, v113
	v_rcp_f32_e32 v106, v110
	v_exp_f32_e32 v111, v111
	v_rcp_f32_e32 v110, v115
	v_exp_f32_e32 v112, v112
	v_exp_f32_e32 v115, v108
	v_exp_f32_e32 v113, v113
	v_mul_f32_e32 v107, 0xbfb8aa3b, v107
	v_mul_f32_e32 v109, 0xbfb8aa3b, v109
	v_exp_f32_e32 v116, v107
	v_add_f32_e32 v107, 1.0, v111
	v_add_f32_e32 v108, 1.0, v112
	v_add_f32_e32 v112, 1.0, v115
	v_exp_f32_e32 v115, v109
	v_add_f32_e32 v109, 1.0, v113
	v_rcp_f32_e32 v107, v107
	v_rcp_f32_e32 v108, v108
	v_rcp_f32_e32 v109, v109
	v_add_f32_e32 v111, 1.0, v116
	v_lshlrev_b32_e32 v116, 16, v126
	v_add_f32_e32 v113, 1.0, v115
	v_pk_fma_f32 v[108:109], v[108:109], v[118:119], v[144:145]
	v_pk_fma_f32 v[106:107], v[106:107], v[116:117], v[142:143]
	v_rcp_f32_e32 v112, v112
	v_rcp_f32_e32 v113, v113
	v_pk_mul_f32 v[116:117], v[108:109], v[108:109]
	v_pk_mul_f32 v[118:119], v[106:107], v[106:107]
	v_rcp_f32_e32 v111, v111
	v_add_f32_e32 v115, v118, v119
	v_add_f32_e32 v116, v116, v117
	v_add_f32_e32 v115, v115, v116
	v_lshlrev_b32_e32 v126, 16, v129
	v_pk_mul_f32 v[102:103], v[102:103], v[114:115] op_sel_hi:[1,0]
	v_pk_mul_f32 v[98:99], v[98:99], v[114:115] op_sel_hi:[1,0]
	v_lshlrev_b32_e32 v120, 16, v128
	v_and_b32_e32 v121, 0xffff0000, v128
	v_pk_fma_f32 v[112:113], v[112:113], v[126:127], v[140:141]
	v_mul_f32_e32 v102, 0xbfb8aa3b, v102
	v_mul_f32_e32 v98, 0xbfb8aa3b, v98
	v_pk_fma_f32 v[110:111], v[110:111], v[120:121], v[138:139]
	s_nop 1
	v_permlane16_swap_b32_e32 v106, v110
	v_permlane16_swap_b32_e32 v107, v111
	v_permlane16_swap_b32_e32 v108, v112
	v_permlane16_swap_b32_e32 v109, v113
	v_permlane32_swap_b32_e32 v106, v110
	v_permlane32_swap_b32_e32 v107, v111
	v_permlane32_swap_b32_e32 v108, v112
	v_permlane32_swap_b32_e32 v109, v113
	v_sub_co_u32_e64 v232, s[98:99], v164, v189
	v_subbrev_co_u32_e64 v233, s[98:99], 0, v165, s[98:99]
	global_store_dwordx4 v[232:233], v[106:109], off
	global_store_dwordx4 v[232:233], v[110:113], off offset:64
	s_nop 1
	v_permlane32_swap_b32_e32 v106, v110
	v_permlane32_swap_b32_e32 v107, v111
	v_permlane32_swap_b32_e32 v108, v112
	v_permlane32_swap_b32_e32 v109, v113
	v_permlane16_swap_b32_e32 v106, v110
	v_permlane16_swap_b32_e32 v107, v111
	v_permlane16_swap_b32_e32 v108, v112
	v_permlane16_swap_b32_e32 v109, v113
	v_pk_mul_f32 v[116:117], v[112:113], v[112:113]
	v_cvt_pk_bf16_f32 v106, v106, v107
	v_cvt_pk_bf16_f32 v107, v108, v109
	v_cvt_pk_bf16_f32 v109, v112, v113
	v_exp_f32_e32 v102, v102
	v_exp_f32_e32 v112, v98
	v_mul_f32_e32 v103, 0xbfb8aa3b, v103
	v_mul_f32_e32 v99, 0xbfb8aa3b, v99
	v_add_f32_e32 v98, 1.0, v102
	v_add_f32_e32 v102, 1.0, v112
	v_exp_f32_e32 v103, v103
	v_exp_f32_e32 v112, v99
	v_pk_mul_f32 v[104:105], v[104:105], v[114:115] op_sel_hi:[1,0]
	v_pk_mul_f32 v[100:101], v[100:101], v[114:115] op_sel_hi:[1,0]
	v_mul_f32_e32 v104, 0xbfb8aa3b, v104
	v_mul_f32_e32 v100, 0xbfb8aa3b, v100
	v_add_f32_e32 v99, 1.0, v103
	v_add_f32_e32 v103, 1.0, v112
	v_exp_f32_e32 v104, v104
	v_exp_f32_e32 v112, v100
	v_mul_f32_e32 v105, 0xbfb8aa3b, v105
	v_exp_f32_e32 v105, v105
	v_mul_f32_e32 v101, 0xbfb8aa3b, v101
	v_add_f32_e32 v100, 1.0, v104
	v_add_f32_e32 v104, 1.0, v112
	v_exp_f32_e32 v112, v101
	v_add_f32_e32 v101, 1.0, v105
	v_pk_mul_f32 v[118:119], v[110:111], v[110:111]
	v_rcp_f32_e32 v98, v98
	v_rcp_f32_e32 v99, v99
	v_rcp_f32_e32 v100, v100
	v_rcp_f32_e32 v101, v101
	v_add_f32_e32 v118, v118, v119
	v_add_f32_e32 v116, v116, v117
	v_add_f32_e32 v105, 1.0, v112
	v_add_f32_e32 v116, v118, v116
	v_rcp_f32_e32 v102, v102
	v_rcp_f32_e32 v103, v103
	v_rcp_f32_e32 v104, v104
	v_rcp_f32_e32 v105, v105
	v_add_f32_e32 v120, v115, v116
	s_waitcnt vmcnt(8)
	v_lshlrev_b32_e32 v112, 16, v122
	v_and_b32_e32 v113, 0xffff0000, v122
	v_lshlrev_b32_e32 v114, 16, v123
	v_and_b32_e32 v115, 0xffff0000, v123
	v_pk_fma_f32 v[100:101], v[100:101], v[114:115], v[136:137]
	v_pk_fma_f32 v[98:99], v[98:99], v[112:113], v[134:135]
	v_lshlrev_b32_e32 v116, 16, v124
	v_and_b32_e32 v117, 0xffff0000, v124
	v_lshlrev_b32_e32 v118, 16, v125
	v_and_b32_e32 v119, 0xffff0000, v125
	v_pk_mul_f32 v[112:113], v[100:101], v[100:101]
	v_pk_mul_f32 v[114:115], v[98:99], v[98:99]
	v_pk_fma_f32 v[104:105], v[104:105], v[118:119], v[132:133]
	v_pk_fma_f32 v[102:103], v[102:103], v[116:117], v[130:131]
	v_add_f32_e32 v114, v114, v115
	v_add_f32_e32 v112, v112, v113
	v_add_f32_e32 v116, v114, v112
	v_pk_mul_f32 v[112:113], v[104:105], v[104:105]
	v_pk_mul_f32 v[114:115], v[102:103], v[102:103]
	v_add_f32_e32 v112, v112, v113
	v_add_f32_e32 v114, v114, v115
	v_add_f32_e32 v112, v114, v112
	v_add_f32_e32 v112, v116, v112
	v_add_f32_e32 v112, v120, v112
	ds_bpermute_b32 v113, v172, v112
	v_cvt_pk_bf16_f32 v108, v110, v111
	v_lshl_add_u64 v[110:111], v[166:167], 1, s[8:9]
	global_store_dwordx4 v[110:111], v[106:109], off
	s_nop 1
	v_permlane16_swap_b32_e32 v98, v102
	v_permlane16_swap_b32_e32 v99, v103
	v_permlane16_swap_b32_e32 v100, v104
	v_permlane16_swap_b32_e32 v101, v105
	v_permlane32_swap_b32_e32 v98, v102
	v_permlane32_swap_b32_e32 v99, v103
	v_permlane32_swap_b32_e32 v100, v104
	v_permlane32_swap_b32_e32 v101, v105
	v_sub_co_u32_e64 v232, s[98:99], v164, v189
	v_subbrev_co_u32_e64 v233, s[98:99], 0, v165, s[98:99]
	global_store_dwordx4 v[232:233], v[98:101], off offset:512
	global_store_dwordx4 v[232:233], v[102:105], off offset:576
	s_nop 1
	v_permlane32_swap_b32_e32 v98, v102
	v_permlane32_swap_b32_e32 v99, v103
	v_permlane32_swap_b32_e32 v100, v104
	v_permlane32_swap_b32_e32 v101, v105
	v_permlane16_swap_b32_e32 v98, v102
	v_permlane16_swap_b32_e32 v99, v103
	v_permlane16_swap_b32_e32 v100, v104
	v_permlane16_swap_b32_e32 v101, v105
	v_cvt_pk_bf16_f32 v106, v98, v99
	s_waitcnt lgkmcnt(0)
	v_add_f32_e32 v98, v112, v113
	ds_bpermute_b32 v99, v0, v98
	v_cvt_pk_bf16_f32 v107, v100, v101
	v_cvt_pk_bf16_f32 v108, v102, v103
	v_cvt_pk_bf16_f32 v109, v104, v105
	global_store_dwordx4 v[110:111], v[106:109], off offset:256
	s_and_saveexec_b64 s[22:23], vcc
	s_cbranch_execz .LBB0_1216
	s_waitcnt lgkmcnt(0)
	v_add_f32_e32 v100, v98, v99
	v_lshlrev_b64 v[98:99], 6, v[162:163]
	v_lshl_add_u64 v[98:99], s[10:11], 0, v[98:99]
	v_lshl_add_u64 v[98:99], s[84:85], 2, v[98:99]
	s_lshl_b32 s34, s45, 2
	v_lshl_add_u64 v[98:99], v[98:99], 0, s[34:35]
	global_store_dword v[98:99], v100, off
.LBB0_1216:
	s_or_b64 exec, exec, s[22:23]
	v_or_b32_e32 v120, 32, v160
	v_ashrrev_i32_e32 v121, 31, v120
	s_waitcnt lgkmcnt(0)
	v_lshlrev_b64 v[98:99], 10, v[120:121]
	v_lshl_add_u64 v[98:99], v[98:99], 0, v[158:159]
	v_lshlrev_b64 v[144:145], 1, v[98:99]
	v_lshl_add_u64 v[100:101], s[24:25], 0, v[144:145]
	global_load_dwordx4 v[124:127], v[100:101], off
	v_lshl_add_u64 v[122:123], v[98:99], 2, s[4:5]
	global_load_dwordx4 v[128:131], v[122:123], off
	global_load_dwordx4 v[132:135], v[122:123], off offset:16
	v_or_b32_e32 v114, 48, v160
	ds_read_b32 v166, v173 offset:128
	v_ashrrev_i32_e32 v115, 31, v114
	v_lshlrev_b64 v[98:99], 10, v[114:115]
	v_lshl_add_u64 v[118:119], v[98:99], 0, v[158:159]
	v_lshlrev_b64 v[162:163], 1, v[118:119]
	v_or_b32_e32 v164, 0x100, v144
	v_mov_b32_e32 v165, v145
	v_lshl_add_u64 v[116:117], v[118:119], 2, s[4:5]
	global_load_dwordx4 v[136:139], v[122:123], off offset:528
	global_load_dwordx4 v[140:143], v[122:123], off offset:512
	v_lshl_add_u64 v[168:169], s[24:25], 0, v[162:163]
	v_or_b32_e32 v162, 0x100, v162
	s_waitcnt lgkmcnt(0)
	v_pk_mul_f32 v[96:97], v[96:97], v[166:167] op_sel_hi:[1,0]
	v_pk_mul_f32 v[94:95], v[94:95], v[166:167] op_sel_hi:[1,0]
	v_pk_mul_f32 v[92:93], v[92:93], v[166:167] op_sel_hi:[1,0]
	v_pk_mul_f32 v[90:91], v[90:91], v[166:167] op_sel_hi:[1,0]
	v_lshl_add_u64 v[164:165], s[24:25], 0, v[164:165]
	global_load_dwordx4 v[106:109], v[116:117], off offset:16
	global_load_dwordx4 v[110:113], v[116:117], off
	global_load_dwordx4 v[98:101], v[116:117], off offset:528
	global_load_dwordx4 v[102:105], v[116:117], off offset:512
	v_lshl_add_u64 v[174:175], s[24:25], 0, v[162:163]
	v_mul_f32_e32 v161, 0xbfb8aa3b, v94
	v_mul_f32_e32 v167, 0xbfb8aa3b, v90
	v_mul_f32_e32 v176, 0xbfb8aa3b, v95
	v_mul_f32_e32 v177, 0xbfb8aa3b, v91
	v_mul_f32_e32 v178, 0xbfb8aa3b, v96
	v_mul_f32_e32 v179, 0xbfb8aa3b, v92
	v_mul_f32_e32 v180, 0xbfb8aa3b, v97
	v_mul_f32_e32 v181, 0xbfb8aa3b, v93
	global_load_dwordx4 v[162:165], v[164:165], off
	s_nop 0
	global_load_dwordx4 v[94:97], v[168:169], off
	global_load_dwordx4 v[90:93], v[174:175], off
	v_exp_f32_e32 v161, v161
	v_exp_f32_e32 v168, v176
	v_exp_f32_e32 v169, v177
	v_exp_f32_e32 v174, v178
	v_exp_f32_e32 v175, v179
	v_exp_f32_e32 v176, v180
	v_exp_f32_e32 v177, v181
	v_exp_f32_e32 v167, v167
	v_add_f32_e32 v161, 1.0, v161
	v_add_f32_e32 v178, 1.0, v168
	v_add_f32_e32 v179, 1.0, v169
	v_add_f32_e32 v180, 1.0, v174
	v_add_f32_e32 v181, 1.0, v175
	v_add_f32_e32 v182, 1.0, v176
	v_add_f32_e32 v183, 1.0, v177
	v_add_f32_e32 v167, 1.0, v167
	v_rcp_f32_e32 v168, v161
	v_rcp_f32_e32 v169, v178
	v_rcp_f32_e32 v175, v179
	v_rcp_f32_e32 v176, v180
	v_rcp_f32_e32 v178, v181
	v_rcp_f32_e32 v177, v182
	v_rcp_f32_e32 v179, v183
	v_rcp_f32_e32 v174, v167
	v_pk_mul_f32 v[86:87], v[86:87], v[166:167] op_sel_hi:[1,0]
	v_pk_mul_f32 v[82:83], v[82:83], v[166:167] op_sel_hi:[1,0]
	v_mul_f32_e32 v86, 0xbfb8aa3b, v86
	v_mul_f32_e32 v82, 0xbfb8aa3b, v82
	v_exp_f32_e32 v86, v86
	v_mul_f32_e32 v87, 0xbfb8aa3b, v87
	v_mul_f32_e32 v83, 0xbfb8aa3b, v83
	v_exp_f32_e32 v87, v87
	v_pk_mul_f32 v[88:89], v[88:89], v[166:167] op_sel_hi:[1,0]
	v_pk_mul_f32 v[84:85], v[84:85], v[166:167] op_sel_hi:[1,0]
	v_mul_f32_e32 v88, 0xbfb8aa3b, v88
	v_mul_f32_e32 v84, 0xbfb8aa3b, v84
	v_exp_f32_e32 v88, v88
	v_mul_f32_e32 v89, 0xbfb8aa3b, v89
	v_exp_f32_e32 v89, v89
	v_mul_f32_e32 v85, 0xbfb8aa3b, v85
	s_waitcnt vmcnt(11)
	v_lshlrev_b32_e32 v180, 16, v124
	v_and_b32_e32 v181, 0xffff0000, v124
	v_lshlrev_b32_e32 v124, 16, v125
	v_and_b32_e32 v125, 0xffff0000, v125
	v_lshlrev_b32_e32 v184, 16, v127
	v_and_b32_e32 v185, 0xffff0000, v127
	v_lshlrev_b32_e32 v182, 16, v126
	v_and_b32_e32 v183, 0xffff0000, v126
	s_waitcnt vmcnt(10)
	v_pk_fma_f32 v[126:127], v[176:177], v[124:125], v[130:131]
	v_pk_fma_f32 v[124:125], v[168:169], v[180:181], v[128:129]
	s_waitcnt vmcnt(9)
	v_pk_fma_f32 v[130:131], v[178:179], v[184:185], v[134:135]
	v_pk_fma_f32 v[128:129], v[174:175], v[182:183], v[132:133]
	s_nop 1
	v_permlane16_swap_b32_e32 v124, v128
	v_permlane16_swap_b32_e32 v125, v129
	v_permlane16_swap_b32_e32 v126, v130
	v_permlane16_swap_b32_e32 v127, v131
	v_permlane32_swap_b32_e32 v124, v128
	v_permlane32_swap_b32_e32 v125, v129
	v_permlane32_swap_b32_e32 v126, v130
	v_permlane32_swap_b32_e32 v127, v131
	v_sub_co_u32_e64 v232, s[98:99], v122, v189
	v_subbrev_co_u32_e64 v233, s[98:99], 0, v123, s[98:99]
	global_store_dwordx4 v[232:233], v[124:127], off
	global_store_dwordx4 v[232:233], v[128:131], off offset:64
	s_nop 1
	v_permlane32_swap_b32_e32 v124, v128
	v_permlane32_swap_b32_e32 v125, v129
	v_permlane32_swap_b32_e32 v126, v130
	v_permlane32_swap_b32_e32 v127, v131
	v_permlane16_swap_b32_e32 v124, v128
	v_permlane16_swap_b32_e32 v125, v129
	v_permlane16_swap_b32_e32 v126, v130
	v_permlane16_swap_b32_e32 v127, v131
	v_pk_mul_f32 v[132:133], v[126:127], v[126:127]
	v_pk_mul_f32 v[134:135], v[124:125], v[124:125]
	v_pk_mul_f32 v[168:169], v[130:131], v[130:131]
	v_cvt_pk_bf16_f32 v124, v124, v125
	v_cvt_pk_bf16_f32 v125, v126, v127
	v_cvt_pk_bf16_f32 v127, v130, v131
	v_exp_f32_e32 v130, v82
	v_add_f32_e32 v82, 1.0, v86
	v_pk_mul_f32 v[174:175], v[128:129], v[128:129]
	v_rcp_f32_e32 v82, v82
	v_add_f32_e32 v86, 1.0, v130
	v_exp_f32_e32 v130, v83
	v_add_f32_e32 v83, 1.0, v87
	v_rcp_f32_e32 v83, v83
	v_add_f32_e32 v134, v134, v135
	v_add_f32_e32 v87, 1.0, v130
	v_exp_f32_e32 v130, v84
	v_add_f32_e32 v84, 1.0, v88
	v_rcp_f32_e32 v84, v84
	v_add_f32_e32 v132, v132, v133
	v_add_f32_e32 v88, 1.0, v130
	v_exp_f32_e32 v130, v85
	v_add_f32_e32 v85, 1.0, v89
	v_rcp_f32_e32 v85, v85
	v_add_f32_e32 v133, v174, v175
	v_add_f32_e32 v135, v168, v169
	v_add_f32_e32 v89, 1.0, v130
	v_add_f32_e32 v132, v134, v132
	v_add_f32_e32 v133, v133, v135
	v_rcp_f32_e32 v86, v86
	v_rcp_f32_e32 v87, v87
	v_rcp_f32_e32 v88, v88
	v_rcp_f32_e32 v89, v89
	v_add_f32_e32 v161, v132, v133
	s_waitcnt vmcnt(4)
	v_lshlrev_b32_e32 v130, 16, v162
	v_and_b32_e32 v131, 0xffff0000, v162
	v_lshlrev_b32_e32 v132, 16, v163
	v_and_b32_e32 v133, 0xffff0000, v163
	v_pk_fma_f32 v[84:85], v[84:85], v[132:133], v[142:143]
	v_pk_fma_f32 v[82:83], v[82:83], v[130:131], v[140:141]
	v_cvt_pk_bf16_f32 v126, v128, v129
	v_lshl_add_u64 v[128:129], s[8:9], 0, v[144:145]
	v_lshlrev_b32_e32 v134, 16, v164
	v_and_b32_e32 v135, 0xffff0000, v164
	v_lshlrev_b32_e32 v144, 16, v165
	v_and_b32_e32 v145, 0xffff0000, v165
	v_pk_mul_f32 v[130:131], v[84:85], v[84:85]
	v_pk_mul_f32 v[132:133], v[82:83], v[82:83]
	v_pk_fma_f32 v[88:89], v[88:89], v[144:145], v[138:139]
	v_pk_fma_f32 v[86:87], v[86:87], v[134:135], v[136:137]
	v_add_f32_e32 v132, v132, v133
	v_add_f32_e32 v130, v130, v131
	v_add_f32_e32 v134, v132, v130
	v_pk_mul_f32 v[130:131], v[88:89], v[88:89]
	v_pk_mul_f32 v[132:133], v[86:87], v[86:87]
	v_add_f32_e32 v130, v130, v131
	v_add_f32_e32 v132, v132, v133
	v_add_f32_e32 v130, v132, v130
	v_add_f32_e32 v130, v134, v130
	v_add_f32_e32 v130, v161, v130
	ds_bpermute_b32 v131, v172, v130
	global_store_dwordx4 v[128:129], v[124:127], off
	s_nop 1
	v_permlane16_swap_b32_e32 v82, v86
	v_permlane16_swap_b32_e32 v83, v87
	v_permlane16_swap_b32_e32 v84, v88
	v_permlane16_swap_b32_e32 v85, v89
	v_permlane32_swap_b32_e32 v82, v86
	v_permlane32_swap_b32_e32 v83, v87
	v_permlane32_swap_b32_e32 v84, v88
	v_permlane32_swap_b32_e32 v85, v89
	v_sub_co_u32_e64 v232, s[98:99], v122, v189
	v_subbrev_co_u32_e64 v233, s[98:99], 0, v123, s[98:99]
	global_store_dwordx4 v[232:233], v[82:85], off offset:512
	global_store_dwordx4 v[232:233], v[86:89], off offset:576
	s_nop 1
	v_permlane32_swap_b32_e32 v82, v86
	v_permlane32_swap_b32_e32 v83, v87
	v_permlane32_swap_b32_e32 v84, v88
	v_permlane32_swap_b32_e32 v85, v89
	v_permlane16_swap_b32_e32 v82, v86
	v_permlane16_swap_b32_e32 v83, v87
	v_permlane16_swap_b32_e32 v84, v88
	v_permlane16_swap_b32_e32 v85, v89
	v_cvt_pk_bf16_f32 v122, v82, v83
	v_cvt_pk_bf16_f32 v123, v84, v85
	v_cvt_pk_bf16_f32 v124, v86, v87
	s_waitcnt lgkmcnt(0)
	v_add_f32_e32 v82, v130, v131
	ds_bpermute_b32 v83, v0, v82
	v_cvt_pk_bf16_f32 v125, v88, v89
	global_store_dwordx4 v[128:129], v[122:125], off offset:256
	s_and_saveexec_b64 s[22:23], vcc
	s_cbranch_execz .LBB0_1218
	v_lshlrev_b64 v[84:85], 6, v[120:121]
	v_lshl_add_u64 v[84:85], s[10:11], 0, v[84:85]
	v_lshl_add_u64 v[84:85], s[84:85], 2, v[84:85]
	s_lshl_b32 s34, s45, 2
	v_lshl_add_u64 v[84:85], v[84:85], 0, s[34:35]
	s_waitcnt lgkmcnt(0)
	v_add_f32_e32 v82, v82, v83
	global_store_dword v[84:85], v82, off
.LBB0_1218:
	s_or_b64 exec, exec, s[22:23]
	ds_read_b32 v82, v173 offset:192
	s_waitcnt vmcnt(7)
	v_and_b32_e32 v85, 0xffff0000, v94
	v_lshlrev_b32_e32 v86, 16, v95
	v_and_b32_e32 v87, 0xffff0000, v95
	v_and_b32_e32 v95, 0xffff0000, v97
	s_waitcnt lgkmcnt(0)
	v_pk_mul_f32 v[78:79], v[78:79], v[82:83] op_sel_hi:[1,0]
	v_pk_mul_f32 v[74:75], v[74:75], v[82:83] op_sel_hi:[1,0]
	v_mul_f32_e32 v78, 0xbfb8aa3b, v78
	v_mul_f32_e32 v74, 0xbfb8aa3b, v74
	v_exp_f32_e32 v78, v78
	v_exp_f32_e32 v74, v74
	v_pk_mul_f32 v[80:81], v[80:81], v[82:83] op_sel_hi:[1,0]
	v_pk_mul_f32 v[76:77], v[76:77], v[82:83] op_sel_hi:[1,0]
	v_mul_f32_e32 v79, 0xbfb8aa3b, v79
	v_add_f32_e32 v78, 1.0, v78
	v_add_f32_e32 v83, 1.0, v74
	v_mul_f32_e32 v80, 0xbfb8aa3b, v80
	v_mul_f32_e32 v76, 0xbfb8aa3b, v76
	v_mul_f32_e32 v81, 0xbfb8aa3b, v81
	v_rcp_f32_e32 v74, v78
	v_exp_f32_e32 v79, v79
	v_rcp_f32_e32 v78, v83
	v_exp_f32_e32 v80, v80
	v_exp_f32_e32 v83, v76
	v_exp_f32_e32 v81, v81
	v_mul_f32_e32 v75, 0xbfb8aa3b, v75
	v_mul_f32_e32 v77, 0xbfb8aa3b, v77
	v_exp_f32_e32 v84, v75
	v_add_f32_e32 v75, 1.0, v79
	v_add_f32_e32 v76, 1.0, v80
	v_add_f32_e32 v80, 1.0, v83
	v_exp_f32_e32 v83, v77
	v_add_f32_e32 v77, 1.0, v81
	v_rcp_f32_e32 v75, v75
	v_rcp_f32_e32 v76, v76
	v_rcp_f32_e32 v77, v77
	v_add_f32_e32 v79, 1.0, v84
	v_lshlrev_b32_e32 v84, 16, v94
	v_add_f32_e32 v81, 1.0, v83
	v_pk_fma_f32 v[76:77], v[76:77], v[86:87], v[112:113]
	v_pk_fma_f32 v[74:75], v[74:75], v[84:85], v[110:111]
	v_rcp_f32_e32 v80, v80
	v_rcp_f32_e32 v81, v81
	v_pk_mul_f32 v[84:85], v[76:77], v[76:77]
	v_pk_mul_f32 v[86:87], v[74:75], v[74:75]
	v_rcp_f32_e32 v79, v79
	v_add_f32_e32 v83, v86, v87
	v_add_f32_e32 v84, v84, v85
	v_add_f32_e32 v83, v83, v84
	v_lshlrev_b32_e32 v94, 16, v97
	v_pk_mul_f32 v[70:71], v[70:71], v[82:83] op_sel_hi:[1,0]
	v_pk_mul_f32 v[66:67], v[66:67], v[82:83] op_sel_hi:[1,0]
	v_lshlrev_b32_e32 v88, 16, v96
	v_and_b32_e32 v89, 0xffff0000, v96
	v_pk_fma_f32 v[80:81], v[80:81], v[94:95], v[108:109]
	v_mul_f32_e32 v70, 0xbfb8aa3b, v70
	v_mul_f32_e32 v66, 0xbfb8aa3b, v66
	v_pk_fma_f32 v[78:79], v[78:79], v[88:89], v[106:107]
	s_nop 1
	v_permlane16_swap_b32_e32 v74, v78
	v_permlane16_swap_b32_e32 v75, v79
	v_permlane16_swap_b32_e32 v76, v80
	v_permlane16_swap_b32_e32 v77, v81
	v_permlane32_swap_b32_e32 v74, v78
	v_permlane32_swap_b32_e32 v75, v79
	v_permlane32_swap_b32_e32 v76, v80
	v_permlane32_swap_b32_e32 v77, v81
	v_sub_co_u32_e64 v232, s[98:99], v116, v189
	v_subbrev_co_u32_e64 v233, s[98:99], 0, v117, s[98:99]
	global_store_dwordx4 v[232:233], v[74:77], off
	global_store_dwordx4 v[232:233], v[78:81], off offset:64
	s_nop 1
	v_permlane32_swap_b32_e32 v74, v78
	v_permlane32_swap_b32_e32 v75, v79
	v_permlane32_swap_b32_e32 v76, v80
	v_permlane32_swap_b32_e32 v77, v81
	v_permlane16_swap_b32_e32 v74, v78
	v_permlane16_swap_b32_e32 v75, v79
	v_permlane16_swap_b32_e32 v76, v80
	v_permlane16_swap_b32_e32 v77, v81
	v_pk_mul_f32 v[84:85], v[80:81], v[80:81]
	v_cvt_pk_bf16_f32 v74, v74, v75
	v_cvt_pk_bf16_f32 v75, v76, v77
	v_cvt_pk_bf16_f32 v77, v80, v81
	v_exp_f32_e32 v70, v70
	v_exp_f32_e32 v80, v66
	v_mul_f32_e32 v71, 0xbfb8aa3b, v71
	v_mul_f32_e32 v67, 0xbfb8aa3b, v67
	v_add_f32_e32 v66, 1.0, v70
	v_add_f32_e32 v70, 1.0, v80
	v_exp_f32_e32 v71, v71
	v_exp_f32_e32 v80, v67
	v_pk_mul_f32 v[72:73], v[72:73], v[82:83] op_sel_hi:[1,0]
	v_pk_mul_f32 v[68:69], v[68:69], v[82:83] op_sel_hi:[1,0]
	v_mul_f32_e32 v72, 0xbfb8aa3b, v72
	v_mul_f32_e32 v68, 0xbfb8aa3b, v68
	v_add_f32_e32 v67, 1.0, v71
	v_add_f32_e32 v71, 1.0, v80
	v_exp_f32_e32 v72, v72
	v_exp_f32_e32 v80, v68
	v_mul_f32_e32 v73, 0xbfb8aa3b, v73
	v_exp_f32_e32 v73, v73
	v_mul_f32_e32 v69, 0xbfb8aa3b, v69
	v_add_f32_e32 v68, 1.0, v72
	v_add_f32_e32 v72, 1.0, v80
	v_exp_f32_e32 v80, v69
	v_add_f32_e32 v69, 1.0, v73
	v_pk_mul_f32 v[86:87], v[78:79], v[78:79]
	v_rcp_f32_e32 v66, v66
	v_rcp_f32_e32 v67, v67
	v_rcp_f32_e32 v68, v68
	v_rcp_f32_e32 v69, v69
	v_add_f32_e32 v86, v86, v87
	v_add_f32_e32 v84, v84, v85
	v_add_f32_e32 v73, 1.0, v80
	v_add_f32_e32 v84, v86, v84
	v_rcp_f32_e32 v70, v70
	v_rcp_f32_e32 v71, v71
	v_rcp_f32_e32 v72, v72
	v_rcp_f32_e32 v73, v73
	v_add_f32_e32 v88, v83, v84
	s_waitcnt vmcnt(8)
	v_lshlrev_b32_e32 v80, 16, v90
	v_and_b32_e32 v81, 0xffff0000, v90
	v_lshlrev_b32_e32 v82, 16, v91
	v_and_b32_e32 v83, 0xffff0000, v91
	v_pk_fma_f32 v[68:69], v[68:69], v[82:83], v[104:105]
	v_pk_fma_f32 v[66:67], v[66:67], v[80:81], v[102:103]
	v_lshlrev_b32_e32 v84, 16, v92
	v_and_b32_e32 v85, 0xffff0000, v92
	v_lshlrev_b32_e32 v86, 16, v93
	v_and_b32_e32 v87, 0xffff0000, v93
	v_pk_mul_f32 v[80:81], v[68:69], v[68:69]
	v_pk_mul_f32 v[82:83], v[66:67], v[66:67]
	v_pk_fma_f32 v[72:73], v[72:73], v[86:87], v[100:101]
	v_pk_fma_f32 v[70:71], v[70:71], v[84:85], v[98:99]
	v_add_f32_e32 v82, v82, v83
	v_add_f32_e32 v80, v80, v81
	v_add_f32_e32 v84, v82, v80
	v_pk_mul_f32 v[80:81], v[72:73], v[72:73]
	v_pk_mul_f32 v[82:83], v[70:71], v[70:71]
	v_add_f32_e32 v80, v80, v81
	v_add_f32_e32 v82, v82, v83
	v_add_f32_e32 v80, v82, v80
	v_add_f32_e32 v80, v84, v80
	v_add_f32_e32 v80, v88, v80
	ds_bpermute_b32 v81, v172, v80
	v_cvt_pk_bf16_f32 v76, v78, v79
	v_lshl_add_u64 v[78:79], v[118:119], 1, s[8:9]
	global_store_dwordx4 v[78:79], v[74:77], off
	s_nop 1
	v_permlane16_swap_b32_e32 v66, v70
	v_permlane16_swap_b32_e32 v67, v71
	v_permlane16_swap_b32_e32 v68, v72
	v_permlane16_swap_b32_e32 v69, v73
	v_permlane32_swap_b32_e32 v66, v70
	v_permlane32_swap_b32_e32 v67, v71
	v_permlane32_swap_b32_e32 v68, v72
	v_permlane32_swap_b32_e32 v69, v73
	v_sub_co_u32_e64 v232, s[98:99], v116, v189
	v_subbrev_co_u32_e64 v233, s[98:99], 0, v117, s[98:99]
	global_store_dwordx4 v[232:233], v[66:69], off offset:512
	global_store_dwordx4 v[232:233], v[70:73], off offset:576
	s_nop 1
	v_permlane32_swap_b32_e32 v66, v70
	v_permlane32_swap_b32_e32 v67, v71
	v_permlane32_swap_b32_e32 v68, v72
	v_permlane32_swap_b32_e32 v69, v73
	v_permlane16_swap_b32_e32 v66, v70
	v_permlane16_swap_b32_e32 v67, v71
	v_permlane16_swap_b32_e32 v68, v72
	v_permlane16_swap_b32_e32 v69, v73
	v_cvt_pk_bf16_f32 v74, v66, v67
	s_waitcnt lgkmcnt(0)
	v_add_f32_e32 v66, v80, v81
	ds_bpermute_b32 v67, v0, v66
	v_cvt_pk_bf16_f32 v75, v68, v69
	v_cvt_pk_bf16_f32 v76, v70, v71
	v_cvt_pk_bf16_f32 v77, v72, v73
	global_store_dwordx4 v[78:79], v[74:77], off offset:256
	s_and_saveexec_b64 s[22:23], vcc
	s_cbranch_execz .LBB0_1220
	s_waitcnt lgkmcnt(0)
	v_add_f32_e32 v68, v66, v67
	v_lshlrev_b64 v[66:67], 6, v[114:115]
	v_lshl_add_u64 v[66:67], s[10:11], 0, v[66:67]
	v_lshl_add_u64 v[66:67], s[84:85], 2, v[66:67]
	s_lshl_b32 s34, s45, 2
	v_lshl_add_u64 v[66:67], v[66:67], 0, s[34:35]
	global_store_dword v[66:67], v68, off
.LBB0_1220:
	s_or_b64 exec, exec, s[22:23]
	v_add_u32_e32 v88, 0x80, v160
	v_ashrrev_i32_e32 v89, 31, v88
	s_waitcnt lgkmcnt(0)
	v_lshlrev_b64 v[66:67], 10, v[88:89]
	v_lshl_add_u64 v[66:67], v[66:67], 0, v[158:159]
	v_lshlrev_b64 v[116:117], 1, v[66:67]
	v_lshl_add_u64 v[68:69], s[24:25], 0, v[116:117]
	global_load_dwordx4 v[92:95], v[68:69], off
	v_lshl_add_u64 v[90:91], v[66:67], 2, s[4:5]
	global_load_dwordx4 v[96:99], v[90:91], off
	global_load_dwordx4 v[100:103], v[90:91], off offset:16
	v_add_u32_e32 v82, 0x90, v160
	ds_read_b32 v118, v173 offset:512
	v_ashrrev_i32_e32 v83, 31, v82
	v_lshlrev_b64 v[66:67], 10, v[82:83]
	v_lshl_add_u64 v[86:87], v[66:67], 0, v[158:159]
	v_lshlrev_b64 v[112:113], 1, v[86:87]
	v_or_b32_e32 v114, 0x100, v116
	v_mov_b32_e32 v115, v117
	v_lshl_add_u64 v[84:85], v[86:87], 2, s[4:5]
	global_load_dwordx4 v[104:107], v[90:91], off offset:528
	global_load_dwordx4 v[108:111], v[90:91], off offset:512
	v_lshl_add_u64 v[120:121], s[24:25], 0, v[112:113]
	v_or_b32_e32 v112, 0x100, v112
	s_waitcnt lgkmcnt(0)
	v_pk_mul_f32 v[64:65], v[64:65], v[118:119] op_sel_hi:[1,0]
	v_pk_mul_f32 v[62:63], v[62:63], v[118:119] op_sel_hi:[1,0]
	v_pk_mul_f32 v[60:61], v[60:61], v[118:119] op_sel_hi:[1,0]
	v_pk_mul_f32 v[58:59], v[58:59], v[118:119] op_sel_hi:[1,0]
	v_lshl_add_u64 v[114:115], s[24:25], 0, v[114:115]
	global_load_dwordx4 v[74:77], v[84:85], off offset:16
	global_load_dwordx4 v[78:81], v[84:85], off
	global_load_dwordx4 v[66:69], v[84:85], off offset:528
	global_load_dwordx4 v[70:73], v[84:85], off offset:512
	v_lshl_add_u64 v[122:123], s[24:25], 0, v[112:113]
	v_mul_f32_e32 v119, 0xbfb8aa3b, v62
	v_mul_f32_e32 v124, 0xbfb8aa3b, v58
	v_mul_f32_e32 v125, 0xbfb8aa3b, v63
	v_mul_f32_e32 v126, 0xbfb8aa3b, v59
	v_mul_f32_e32 v127, 0xbfb8aa3b, v64
	v_mul_f32_e32 v128, 0xbfb8aa3b, v60
	v_mul_f32_e32 v129, 0xbfb8aa3b, v65
	v_mul_f32_e32 v130, 0xbfb8aa3b, v61
	global_load_dwordx4 v[112:115], v[114:115], off
	s_nop 0
	global_load_dwordx4 v[62:65], v[120:121], off
	global_load_dwordx4 v[58:61], v[122:123], off
	v_exp_f32_e32 v119, v119
	v_exp_f32_e32 v120, v124
	v_exp_f32_e32 v121, v125
	v_exp_f32_e32 v122, v126
	v_exp_f32_e32 v123, v127
	v_exp_f32_e32 v124, v128
	v_exp_f32_e32 v125, v129
	v_exp_f32_e32 v126, v130
	v_add_f32_e32 v119, 1.0, v119
	v_add_f32_e32 v127, 1.0, v120
	v_add_f32_e32 v121, 1.0, v121
	v_add_f32_e32 v128, 1.0, v122
	v_add_f32_e32 v129, 1.0, v123
	v_add_f32_e32 v130, 1.0, v124
	v_add_f32_e32 v125, 1.0, v125
	v_add_f32_e32 v131, 1.0, v126
	v_rcp_f32_e32 v120, v119
	v_rcp_f32_e32 v122, v127
	v_rcp_f32_e32 v121, v121
	v_rcp_f32_e32 v123, v128
	v_rcp_f32_e32 v124, v129
	v_rcp_f32_e32 v126, v130
	v_rcp_f32_e32 v125, v125
	v_rcp_f32_e32 v127, v131
	s_waitcnt vmcnt(11)
	v_lshlrev_b32_e32 v128, 16, v92
	v_and_b32_e32 v129, 0xffff0000, v92
	v_lshlrev_b32_e32 v92, 16, v93
	v_and_b32_e32 v93, 0xffff0000, v93
	v_lshlrev_b32_e32 v130, 16, v94
	v_and_b32_e32 v131, 0xffff0000, v94
	v_lshlrev_b32_e32 v132, 16, v95
	v_and_b32_e32 v133, 0xffff0000, v95
	s_waitcnt vmcnt(10)
	v_pk_fma_f32 v[94:95], v[124:125], v[92:93], v[98:99]
	v_pk_fma_f32 v[92:93], v[120:121], v[128:129], v[96:97]
	s_waitcnt vmcnt(9)
	v_pk_fma_f32 v[98:99], v[126:127], v[132:133], v[102:103]
	v_pk_fma_f32 v[96:97], v[122:123], v[130:131], v[100:101]
	v_pk_mul_f32 v[100:101], v[94:95], v[94:95]
	v_pk_mul_f32 v[102:103], v[92:93], v[92:93]
	v_pk_mul_f32 v[120:121], v[98:99], v[98:99]
	v_pk_mul_f32 v[122:123], v[96:97], v[96:97]
	v_add_f32_e32 v102, v102, v103
	v_add_f32_e32 v100, v100, v101
	v_add_f32_e32 v101, v122, v123
	v_add_f32_e32 v103, v120, v121
	v_add_f32_e32 v100, v102, v100
	v_add_f32_e32 v101, v101, v103
	v_add_f32_e32 v119, v100, v101
	v_pk_mul_f32 v[54:55], v[54:55], v[118:119] op_sel_hi:[1,0]
	v_pk_mul_f32 v[50:51], v[50:51], v[118:119] op_sel_hi:[1,0]
	v_mul_f32_e32 v54, 0xbfb8aa3b, v54
	v_mul_f32_e32 v50, 0xbfb8aa3b, v50
	s_nop 1
	v_permlane16_swap_b32_e32 v92, v96
	v_permlane16_swap_b32_e32 v93, v97
	v_permlane16_swap_b32_e32 v94, v98
	v_permlane16_swap_b32_e32 v95, v99
	v_permlane32_swap_b32_e32 v92, v96
	v_permlane32_swap_b32_e32 v93, v97
	v_permlane32_swap_b32_e32 v94, v98
	v_permlane32_swap_b32_e32 v95, v99
	v_sub_co_u32_e64 v232, s[98:99], v90, v189
	v_subbrev_co_u32_e64 v233, s[98:99], 0, v91, s[98:99]
	global_store_dwordx4 v[232:233], v[92:95], off
	global_store_dwordx4 v[232:233], v[96:99], off offset:64
	s_nop 1
	v_permlane32_swap_b32_e32 v92, v96
	v_permlane32_swap_b32_e32 v93, v97
	v_permlane32_swap_b32_e32 v94, v98
	v_permlane32_swap_b32_e32 v95, v99
	v_permlane16_swap_b32_e32 v92, v96
	v_permlane16_swap_b32_e32 v93, v97
	v_permlane16_swap_b32_e32 v94, v98
	v_permlane16_swap_b32_e32 v95, v99
	v_exp_f32_e32 v54, v54
	v_cvt_pk_bf16_f32 v92, v92, v93
	v_cvt_pk_bf16_f32 v93, v94, v95
	v_cvt_pk_bf16_f32 v95, v98, v99
	v_exp_f32_e32 v98, v50
	v_mul_f32_e32 v55, 0xbfb8aa3b, v55
	v_mul_f32_e32 v51, 0xbfb8aa3b, v51
	v_add_f32_e32 v50, 1.0, v54
	v_add_f32_e32 v54, 1.0, v98
	v_exp_f32_e32 v55, v55
	v_exp_f32_e32 v98, v51
	v_pk_mul_f32 v[56:57], v[56:57], v[118:119] op_sel_hi:[1,0]
	v_pk_mul_f32 v[52:53], v[52:53], v[118:119] op_sel_hi:[1,0]
	v_mul_f32_e32 v56, 0xbfb8aa3b, v56
	v_mul_f32_e32 v52, 0xbfb8aa3b, v52
	v_add_f32_e32 v51, 1.0, v55
	v_add_f32_e32 v55, 1.0, v98
	v_exp_f32_e32 v56, v56
	v_exp_f32_e32 v98, v52
	v_mul_f32_e32 v57, 0xbfb8aa3b, v57
	v_exp_f32_e32 v57, v57
	v_mul_f32_e32 v53, 0xbfb8aa3b, v53
	v_add_f32_e32 v52, 1.0, v56
	v_add_f32_e32 v56, 1.0, v98
	v_exp_f32_e32 v98, v53
	v_add_f32_e32 v53, 1.0, v57
	v_rcp_f32_e32 v50, v50
	v_rcp_f32_e32 v51, v51
	v_rcp_f32_e32 v52, v52
	v_rcp_f32_e32 v53, v53
	v_add_f32_e32 v57, 1.0, v98
	v_rcp_f32_e32 v54, v54
	v_rcp_f32_e32 v55, v55
	v_rcp_f32_e32 v56, v56
	v_rcp_f32_e32 v57, v57
	s_waitcnt vmcnt(4)
	v_lshlrev_b32_e32 v98, 16, v112
	v_and_b32_e32 v99, 0xffff0000, v112
	v_lshlrev_b32_e32 v100, 16, v113
	v_and_b32_e32 v101, 0xffff0000, v113
	v_pk_fma_f32 v[52:53], v[52:53], v[100:101], v[110:111]
	v_pk_fma_f32 v[50:51], v[50:51], v[98:99], v[108:109]
	v_lshlrev_b32_e32 v102, 16, v114
	v_and_b32_e32 v103, 0xffff0000, v114
	v_lshlrev_b32_e32 v112, 16, v115
	v_and_b32_e32 v113, 0xffff0000, v115
	v_pk_mul_f32 v[98:99], v[52:53], v[52:53]
	v_pk_mul_f32 v[100:101], v[50:51], v[50:51]
	v_pk_fma_f32 v[56:57], v[56:57], v[112:113], v[106:107]
	v_pk_fma_f32 v[54:55], v[54:55], v[102:103], v[104:105]
	v_add_f32_e32 v100, v100, v101
	v_add_f32_e32 v98, v98, v99
	v_add_f32_e32 v102, v100, v98
	v_pk_mul_f32 v[98:99], v[56:57], v[56:57]
	v_pk_mul_f32 v[100:101], v[54:55], v[54:55]
	v_add_f32_e32 v98, v98, v99
	v_add_f32_e32 v100, v100, v101
	v_add_f32_e32 v98, v100, v98
	v_add_f32_e32 v98, v102, v98
	v_add_f32_e32 v98, v119, v98
	ds_bpermute_b32 v99, v172, v98
	v_cvt_pk_bf16_f32 v94, v96, v97
	v_lshl_add_u64 v[96:97], s[8:9], 0, v[116:117]
	global_store_dwordx4 v[96:97], v[92:95], off
	s_nop 1
	v_permlane16_swap_b32_e32 v50, v54
	v_permlane16_swap_b32_e32 v51, v55
	v_permlane16_swap_b32_e32 v52, v56
	v_permlane16_swap_b32_e32 v53, v57
	v_permlane32_swap_b32_e32 v50, v54
	v_permlane32_swap_b32_e32 v51, v55
	v_permlane32_swap_b32_e32 v52, v56
	v_permlane32_swap_b32_e32 v53, v57
	v_sub_co_u32_e64 v232, s[98:99], v90, v189
	v_subbrev_co_u32_e64 v233, s[98:99], 0, v91, s[98:99]
	global_store_dwordx4 v[232:233], v[50:53], off offset:512
	global_store_dwordx4 v[232:233], v[54:57], off offset:576
	s_nop 1
	v_permlane32_swap_b32_e32 v50, v54
	v_permlane32_swap_b32_e32 v51, v55
	v_permlane32_swap_b32_e32 v52, v56
	v_permlane32_swap_b32_e32 v53, v57
	v_permlane16_swap_b32_e32 v50, v54
	v_permlane16_swap_b32_e32 v51, v55
	v_permlane16_swap_b32_e32 v52, v56
	v_permlane16_swap_b32_e32 v53, v57
	v_cvt_pk_bf16_f32 v90, v50, v51
	s_waitcnt lgkmcnt(0)
	v_add_f32_e32 v50, v98, v99
	ds_bpermute_b32 v51, v0, v50
	v_cvt_pk_bf16_f32 v91, v52, v53
	v_cvt_pk_bf16_f32 v92, v54, v55
	v_cvt_pk_bf16_f32 v93, v56, v57
	global_store_dwordx4 v[96:97], v[90:93], off offset:256
	s_and_saveexec_b64 s[22:23], vcc
	s_cbranch_execz .LBB0_1222
	v_lshlrev_b64 v[52:53], 6, v[88:89]
	v_lshl_add_u64 v[52:53], s[10:11], 0, v[52:53]
	v_lshl_add_u64 v[52:53], s[84:85], 2, v[52:53]
	s_lshl_b32 s34, s45, 2
	v_lshl_add_u64 v[52:53], v[52:53], 0, s[34:35]
	s_waitcnt lgkmcnt(0)
	v_add_f32_e32 v50, v50, v51
	global_store_dword v[52:53], v50, off
.LBB0_1222:
	s_or_b64 exec, exec, s[22:23]
	ds_read_b32 v50, v173 offset:576
	s_waitcnt vmcnt(7)
	v_and_b32_e32 v53, 0xffff0000, v62
	v_lshlrev_b32_e32 v54, 16, v63
	v_and_b32_e32 v55, 0xffff0000, v63
	v_and_b32_e32 v63, 0xffff0000, v65
	s_waitcnt lgkmcnt(0)
	v_pk_mul_f32 v[46:47], v[46:47], v[50:51] op_sel_hi:[1,0]
	v_pk_mul_f32 v[42:43], v[42:43], v[50:51] op_sel_hi:[1,0]
	v_mul_f32_e32 v46, 0xbfb8aa3b, v46
	v_mul_f32_e32 v42, 0xbfb8aa3b, v42
	v_exp_f32_e32 v46, v46
	v_exp_f32_e32 v42, v42
	v_pk_mul_f32 v[48:49], v[48:49], v[50:51] op_sel_hi:[1,0]
	v_pk_mul_f32 v[44:45], v[44:45], v[50:51] op_sel_hi:[1,0]
	v_mul_f32_e32 v47, 0xbfb8aa3b, v47
	v_add_f32_e32 v46, 1.0, v46
	v_add_f32_e32 v51, 1.0, v42
	v_mul_f32_e32 v48, 0xbfb8aa3b, v48
	v_mul_f32_e32 v44, 0xbfb8aa3b, v44
	v_mul_f32_e32 v49, 0xbfb8aa3b, v49
	v_rcp_f32_e32 v42, v46
	v_exp_f32_e32 v47, v47
	v_rcp_f32_e32 v46, v51
	v_exp_f32_e32 v48, v48
	v_exp_f32_e32 v51, v44
	v_exp_f32_e32 v49, v49
	v_mul_f32_e32 v43, 0xbfb8aa3b, v43
	v_mul_f32_e32 v45, 0xbfb8aa3b, v45
	v_exp_f32_e32 v52, v43
	v_add_f32_e32 v43, 1.0, v47
	v_add_f32_e32 v44, 1.0, v48
	v_add_f32_e32 v48, 1.0, v51
	v_exp_f32_e32 v51, v45
	v_add_f32_e32 v45, 1.0, v49
	v_rcp_f32_e32 v43, v43
	v_rcp_f32_e32 v44, v44
	v_rcp_f32_e32 v45, v45
	v_add_f32_e32 v47, 1.0, v52
	v_lshlrev_b32_e32 v52, 16, v62
	v_add_f32_e32 v49, 1.0, v51
	v_pk_fma_f32 v[44:45], v[44:45], v[54:55], v[80:81]
	v_pk_fma_f32 v[42:43], v[42:43], v[52:53], v[78:79]
	v_rcp_f32_e32 v48, v48
	v_rcp_f32_e32 v49, v49
	v_pk_mul_f32 v[52:53], v[44:45], v[44:45]
	v_pk_mul_f32 v[54:55], v[42:43], v[42:43]
	v_rcp_f32_e32 v47, v47
	v_add_f32_e32 v51, v54, v55
	v_add_f32_e32 v52, v52, v53
	v_add_f32_e32 v51, v51, v52
	v_lshlrev_b32_e32 v62, 16, v65
	v_pk_mul_f32 v[38:39], v[38:39], v[50:51] op_sel_hi:[1,0]
	v_pk_mul_f32 v[34:35], v[34:35], v[50:51] op_sel_hi:[1,0]
	v_lshlrev_b32_e32 v56, 16, v64
	v_and_b32_e32 v57, 0xffff0000, v64
	v_pk_fma_f32 v[48:49], v[48:49], v[62:63], v[76:77]
	v_mul_f32_e32 v38, 0xbfb8aa3b, v38
	v_mul_f32_e32 v34, 0xbfb8aa3b, v34
	v_pk_fma_f32 v[46:47], v[46:47], v[56:57], v[74:75]
	s_nop 1
	v_permlane16_swap_b32_e32 v42, v46
	v_permlane16_swap_b32_e32 v43, v47
	v_permlane16_swap_b32_e32 v44, v48
	v_permlane16_swap_b32_e32 v45, v49
	v_permlane32_swap_b32_e32 v42, v46
	v_permlane32_swap_b32_e32 v43, v47
	v_permlane32_swap_b32_e32 v44, v48
	v_permlane32_swap_b32_e32 v45, v49
	v_sub_co_u32_e64 v232, s[98:99], v84, v189
	v_subbrev_co_u32_e64 v233, s[98:99], 0, v85, s[98:99]
	global_store_dwordx4 v[232:233], v[42:45], off
	global_store_dwordx4 v[232:233], v[46:49], off offset:64
	s_nop 1
	v_permlane32_swap_b32_e32 v42, v46
	v_permlane32_swap_b32_e32 v43, v47
	v_permlane32_swap_b32_e32 v44, v48
	v_permlane32_swap_b32_e32 v45, v49
	v_permlane16_swap_b32_e32 v42, v46
	v_permlane16_swap_b32_e32 v43, v47
	v_permlane16_swap_b32_e32 v44, v48
	v_permlane16_swap_b32_e32 v45, v49
	v_pk_mul_f32 v[52:53], v[48:49], v[48:49]
	v_cvt_pk_bf16_f32 v42, v42, v43
	v_cvt_pk_bf16_f32 v43, v44, v45
	v_cvt_pk_bf16_f32 v45, v48, v49
	v_exp_f32_e32 v38, v38
	v_exp_f32_e32 v48, v34
	v_mul_f32_e32 v39, 0xbfb8aa3b, v39
	v_mul_f32_e32 v35, 0xbfb8aa3b, v35
	v_add_f32_e32 v34, 1.0, v38
	v_add_f32_e32 v38, 1.0, v48
	v_exp_f32_e32 v39, v39
	v_exp_f32_e32 v48, v35
	v_pk_mul_f32 v[40:41], v[40:41], v[50:51] op_sel_hi:[1,0]
	v_pk_mul_f32 v[36:37], v[36:37], v[50:51] op_sel_hi:[1,0]
	v_mul_f32_e32 v40, 0xbfb8aa3b, v40
	v_mul_f32_e32 v36, 0xbfb8aa3b, v36
	v_add_f32_e32 v35, 1.0, v39
	v_add_f32_e32 v39, 1.0, v48
	v_exp_f32_e32 v40, v40
	v_exp_f32_e32 v48, v36
	v_mul_f32_e32 v41, 0xbfb8aa3b, v41
	v_exp_f32_e32 v41, v41
	v_mul_f32_e32 v37, 0xbfb8aa3b, v37
	v_add_f32_e32 v36, 1.0, v40
	v_add_f32_e32 v40, 1.0, v48
	v_exp_f32_e32 v48, v37
	v_add_f32_e32 v37, 1.0, v41
	v_pk_mul_f32 v[54:55], v[46:47], v[46:47]
	v_rcp_f32_e32 v34, v34
	v_rcp_f32_e32 v35, v35
	v_rcp_f32_e32 v36, v36
	v_rcp_f32_e32 v37, v37
	v_add_f32_e32 v54, v54, v55
	v_add_f32_e32 v52, v52, v53
	v_add_f32_e32 v41, 1.0, v48
	v_add_f32_e32 v52, v54, v52
	v_rcp_f32_e32 v38, v38
	v_rcp_f32_e32 v39, v39
	v_rcp_f32_e32 v40, v40
	v_rcp_f32_e32 v41, v41
	v_add_f32_e32 v56, v51, v52
	s_waitcnt vmcnt(8)
	v_lshlrev_b32_e32 v48, 16, v58
	v_and_b32_e32 v49, 0xffff0000, v58
	v_lshlrev_b32_e32 v50, 16, v59
	v_and_b32_e32 v51, 0xffff0000, v59
	v_pk_fma_f32 v[36:37], v[36:37], v[50:51], v[72:73]
	v_pk_fma_f32 v[34:35], v[34:35], v[48:49], v[70:71]
	v_lshlrev_b32_e32 v52, 16, v60
	v_and_b32_e32 v53, 0xffff0000, v60
	v_lshlrev_b32_e32 v54, 16, v61
	v_and_b32_e32 v55, 0xffff0000, v61
	v_pk_mul_f32 v[48:49], v[36:37], v[36:37]
	v_pk_mul_f32 v[50:51], v[34:35], v[34:35]
	v_pk_fma_f32 v[40:41], v[40:41], v[54:55], v[68:69]
	v_pk_fma_f32 v[38:39], v[38:39], v[52:53], v[66:67]
	v_add_f32_e32 v50, v50, v51
	v_add_f32_e32 v48, v48, v49
	v_add_f32_e32 v52, v50, v48
	v_pk_mul_f32 v[48:49], v[40:41], v[40:41]
	v_pk_mul_f32 v[50:51], v[38:39], v[38:39]
	v_add_f32_e32 v48, v48, v49
	v_add_f32_e32 v50, v50, v51
	v_add_f32_e32 v48, v50, v48
	v_add_f32_e32 v48, v52, v48
	v_add_f32_e32 v48, v56, v48
	ds_bpermute_b32 v49, v172, v48
	v_cvt_pk_bf16_f32 v44, v46, v47
	v_lshl_add_u64 v[46:47], v[86:87], 1, s[8:9]
	global_store_dwordx4 v[46:47], v[42:45], off
	s_nop 1
	v_permlane16_swap_b32_e32 v34, v38
	v_permlane16_swap_b32_e32 v35, v39
	v_permlane16_swap_b32_e32 v36, v40
	v_permlane16_swap_b32_e32 v37, v41
	v_permlane32_swap_b32_e32 v34, v38
	v_permlane32_swap_b32_e32 v35, v39
	v_permlane32_swap_b32_e32 v36, v40
	v_permlane32_swap_b32_e32 v37, v41
	v_sub_co_u32_e64 v232, s[98:99], v84, v189
	v_subbrev_co_u32_e64 v233, s[98:99], 0, v85, s[98:99]
	global_store_dwordx4 v[232:233], v[34:37], off offset:512
	global_store_dwordx4 v[232:233], v[38:41], off offset:576
	s_nop 1
	v_permlane32_swap_b32_e32 v34, v38
	v_permlane32_swap_b32_e32 v35, v39
	v_permlane32_swap_b32_e32 v36, v40
	v_permlane32_swap_b32_e32 v37, v41
	v_permlane16_swap_b32_e32 v34, v38
	v_permlane16_swap_b32_e32 v35, v39
	v_permlane16_swap_b32_e32 v36, v40
	v_permlane16_swap_b32_e32 v37, v41
	v_cvt_pk_bf16_f32 v42, v34, v35
	s_waitcnt lgkmcnt(0)
	v_add_f32_e32 v34, v48, v49
	ds_bpermute_b32 v35, v0, v34
	v_cvt_pk_bf16_f32 v43, v36, v37
	v_cvt_pk_bf16_f32 v44, v38, v39
	v_cvt_pk_bf16_f32 v45, v40, v41
	global_store_dwordx4 v[46:47], v[42:45], off offset:256
	s_and_saveexec_b64 s[22:23], vcc
	s_cbranch_execz .LBB0_1224
	s_waitcnt lgkmcnt(0)
	v_add_f32_e32 v36, v34, v35
	v_lshlrev_b64 v[34:35], 6, v[82:83]
	v_lshl_add_u64 v[34:35], s[10:11], 0, v[34:35]
	v_lshl_add_u64 v[34:35], s[84:85], 2, v[34:35]
	s_lshl_b32 s34, s45, 2
	v_lshl_add_u64 v[34:35], v[34:35], 0, s[34:35]
	global_store_dword v[34:35], v36, off
.LBB0_1224:
	s_or_b64 exec, exec, s[22:23]
	v_add_u32_e32 v56, 0xa0, v160
	v_ashrrev_i32_e32 v57, 31, v56
	s_waitcnt lgkmcnt(0)
	v_lshlrev_b64 v[34:35], 10, v[56:57]
	v_lshl_add_u64 v[34:35], v[34:35], 0, v[158:159]
	v_lshlrev_b64 v[84:85], 1, v[34:35]
	v_lshl_add_u64 v[36:37], s[24:25], 0, v[84:85]
	global_load_dwordx4 v[60:63], v[36:37], off
	v_lshl_add_u64 v[58:59], v[34:35], 2, s[4:5]
	global_load_dwordx4 v[64:67], v[58:59], off
	global_load_dwordx4 v[68:71], v[58:59], off offset:16
	v_add_u32_e32 v50, 0xb0, v160
	ds_read_b32 v86, v173 offset:640
	v_ashrrev_i32_e32 v51, 31, v50
	v_lshlrev_b64 v[34:35], 10, v[50:51]
	v_lshl_add_u64 v[54:55], v[34:35], 0, v[158:159]
	v_lshlrev_b64 v[80:81], 1, v[54:55]
	v_or_b32_e32 v82, 0x100, v84
	v_mov_b32_e32 v83, v85
	v_lshl_add_u64 v[52:53], v[54:55], 2, s[4:5]
	global_load_dwordx4 v[72:75], v[58:59], off offset:528
	global_load_dwordx4 v[76:79], v[58:59], off offset:512
	v_lshl_add_u64 v[88:89], s[24:25], 0, v[80:81]
	v_or_b32_e32 v80, 0x100, v80
	s_waitcnt lgkmcnt(0)
	v_pk_mul_f32 v[32:33], v[32:33], v[86:87] op_sel_hi:[1,0]
	v_pk_mul_f32 v[30:31], v[30:31], v[86:87] op_sel_hi:[1,0]
	v_pk_mul_f32 v[28:29], v[28:29], v[86:87] op_sel_hi:[1,0]
	v_pk_mul_f32 v[26:27], v[26:27], v[86:87] op_sel_hi:[1,0]
	v_lshl_add_u64 v[82:83], s[24:25], 0, v[82:83]
	global_load_dwordx4 v[42:45], v[52:53], off offset:16
	global_load_dwordx4 v[46:49], v[52:53], off
	global_load_dwordx4 v[34:37], v[52:53], off offset:528
	global_load_dwordx4 v[38:41], v[52:53], off offset:512
	v_lshl_add_u64 v[90:91], s[24:25], 0, v[80:81]
	v_mul_f32_e32 v87, 0xbfb8aa3b, v30
	v_mul_f32_e32 v92, 0xbfb8aa3b, v26
	v_mul_f32_e32 v93, 0xbfb8aa3b, v31
	v_mul_f32_e32 v94, 0xbfb8aa3b, v27
	v_mul_f32_e32 v95, 0xbfb8aa3b, v32
	v_mul_f32_e32 v96, 0xbfb8aa3b, v28
	v_mul_f32_e32 v97, 0xbfb8aa3b, v33
	v_mul_f32_e32 v98, 0xbfb8aa3b, v29
	global_load_dwordx4 v[80:83], v[82:83], off
	s_nop 0
	global_load_dwordx4 v[30:33], v[88:89], off
	global_load_dwordx4 v[26:29], v[90:91], off
	v_exp_f32_e32 v87, v87
	v_exp_f32_e32 v88, v92
	v_exp_f32_e32 v89, v93
	v_exp_f32_e32 v90, v94
	v_exp_f32_e32 v91, v95
	v_exp_f32_e32 v92, v96
	v_exp_f32_e32 v93, v97
	v_exp_f32_e32 v94, v98
	v_add_f32_e32 v87, 1.0, v87
	v_add_f32_e32 v95, 1.0, v88
	v_add_f32_e32 v89, 1.0, v89
	v_add_f32_e32 v96, 1.0, v90
	v_add_f32_e32 v97, 1.0, v91
	v_add_f32_e32 v98, 1.0, v92
	v_add_f32_e32 v93, 1.0, v93
	v_add_f32_e32 v99, 1.0, v94
	v_rcp_f32_e32 v88, v87
	v_rcp_f32_e32 v90, v95
	v_rcp_f32_e32 v89, v89
	v_rcp_f32_e32 v91, v96
	v_rcp_f32_e32 v92, v97
	v_rcp_f32_e32 v94, v98
	v_rcp_f32_e32 v93, v93
	v_rcp_f32_e32 v95, v99
	s_waitcnt vmcnt(11)
	v_lshlrev_b32_e32 v96, 16, v60
	v_and_b32_e32 v97, 0xffff0000, v60
	v_lshlrev_b32_e32 v60, 16, v61
	v_and_b32_e32 v61, 0xffff0000, v61
	v_lshlrev_b32_e32 v98, 16, v62
	v_and_b32_e32 v99, 0xffff0000, v62
	v_lshlrev_b32_e32 v100, 16, v63
	v_and_b32_e32 v101, 0xffff0000, v63
	s_waitcnt vmcnt(10)
	v_pk_fma_f32 v[62:63], v[92:93], v[60:61], v[66:67]
	v_pk_fma_f32 v[60:61], v[88:89], v[96:97], v[64:65]
	s_waitcnt vmcnt(9)
	v_pk_fma_f32 v[66:67], v[94:95], v[100:101], v[70:71]
	v_pk_fma_f32 v[64:65], v[90:91], v[98:99], v[68:69]
	v_pk_mul_f32 v[68:69], v[62:63], v[62:63]
	v_pk_mul_f32 v[70:71], v[60:61], v[60:61]
	v_pk_mul_f32 v[88:89], v[66:67], v[66:67]
	v_pk_mul_f32 v[90:91], v[64:65], v[64:65]
	v_add_f32_e32 v70, v70, v71
	v_add_f32_e32 v68, v68, v69
	v_add_f32_e32 v69, v90, v91
	v_add_f32_e32 v71, v88, v89
	v_add_f32_e32 v68, v70, v68
	v_add_f32_e32 v69, v69, v71
	v_add_f32_e32 v87, v68, v69
	v_pk_mul_f32 v[22:23], v[22:23], v[86:87] op_sel_hi:[1,0]
	v_pk_mul_f32 v[18:19], v[18:19], v[86:87] op_sel_hi:[1,0]
	v_mul_f32_e32 v22, 0xbfb8aa3b, v22
	v_mul_f32_e32 v18, 0xbfb8aa3b, v18
	s_nop 1
	v_permlane16_swap_b32_e32 v60, v64
	v_permlane16_swap_b32_e32 v61, v65
	v_permlane16_swap_b32_e32 v62, v66
	v_permlane16_swap_b32_e32 v63, v67
	v_permlane32_swap_b32_e32 v60, v64
	v_permlane32_swap_b32_e32 v61, v65
	v_permlane32_swap_b32_e32 v62, v66
	v_permlane32_swap_b32_e32 v63, v67
	v_sub_co_u32_e64 v232, s[98:99], v58, v189
	v_subbrev_co_u32_e64 v233, s[98:99], 0, v59, s[98:99]
	global_store_dwordx4 v[232:233], v[60:63], off
	global_store_dwordx4 v[232:233], v[64:67], off offset:64
	s_nop 1
	v_permlane32_swap_b32_e32 v60, v64
	v_permlane32_swap_b32_e32 v61, v65
	v_permlane32_swap_b32_e32 v62, v66
	v_permlane32_swap_b32_e32 v63, v67
	v_permlane16_swap_b32_e32 v60, v64
	v_permlane16_swap_b32_e32 v61, v65
	v_permlane16_swap_b32_e32 v62, v66
	v_permlane16_swap_b32_e32 v63, v67
	v_exp_f32_e32 v22, v22
	v_cvt_pk_bf16_f32 v60, v60, v61
	v_cvt_pk_bf16_f32 v61, v62, v63
	v_cvt_pk_bf16_f32 v63, v66, v67
	v_exp_f32_e32 v66, v18
	v_mul_f32_e32 v23, 0xbfb8aa3b, v23
	v_mul_f32_e32 v19, 0xbfb8aa3b, v19
	v_add_f32_e32 v18, 1.0, v22
	v_add_f32_e32 v22, 1.0, v66
	v_exp_f32_e32 v23, v23
	v_exp_f32_e32 v66, v19
	v_pk_mul_f32 v[24:25], v[24:25], v[86:87] op_sel_hi:[1,0]
	v_pk_mul_f32 v[20:21], v[20:21], v[86:87] op_sel_hi:[1,0]
	v_mul_f32_e32 v24, 0xbfb8aa3b, v24
	v_mul_f32_e32 v20, 0xbfb8aa3b, v20
	v_add_f32_e32 v19, 1.0, v23
	v_add_f32_e32 v23, 1.0, v66
	v_exp_f32_e32 v24, v24
	v_exp_f32_e32 v66, v20
	v_mul_f32_e32 v25, 0xbfb8aa3b, v25
	v_exp_f32_e32 v25, v25
	v_mul_f32_e32 v21, 0xbfb8aa3b, v21
	v_add_f32_e32 v20, 1.0, v24
	v_add_f32_e32 v24, 1.0, v66
	v_exp_f32_e32 v66, v21
	v_add_f32_e32 v21, 1.0, v25
	v_rcp_f32_e32 v18, v18
	v_rcp_f32_e32 v19, v19
	v_rcp_f32_e32 v20, v20
	v_rcp_f32_e32 v21, v21
	v_add_f32_e32 v25, 1.0, v66
	v_rcp_f32_e32 v22, v22
	v_rcp_f32_e32 v23, v23
	v_rcp_f32_e32 v24, v24
	v_rcp_f32_e32 v25, v25
	s_waitcnt vmcnt(4)
	v_lshlrev_b32_e32 v66, 16, v80
	v_and_b32_e32 v67, 0xffff0000, v80
	v_lshlrev_b32_e32 v68, 16, v81
	v_and_b32_e32 v69, 0xffff0000, v81
	v_pk_fma_f32 v[20:21], v[20:21], v[68:69], v[78:79]
	v_pk_fma_f32 v[18:19], v[18:19], v[66:67], v[76:77]
	v_lshlrev_b32_e32 v70, 16, v82
	v_and_b32_e32 v71, 0xffff0000, v82
	v_lshlrev_b32_e32 v80, 16, v83
	v_and_b32_e32 v81, 0xffff0000, v83
	v_pk_mul_f32 v[66:67], v[20:21], v[20:21]
	v_pk_mul_f32 v[68:69], v[18:19], v[18:19]
	v_pk_fma_f32 v[24:25], v[24:25], v[80:81], v[74:75]
	v_pk_fma_f32 v[22:23], v[22:23], v[70:71], v[72:73]
	v_add_f32_e32 v68, v68, v69
	v_add_f32_e32 v66, v66, v67
	v_add_f32_e32 v70, v68, v66
	v_pk_mul_f32 v[66:67], v[24:25], v[24:25]
	v_pk_mul_f32 v[68:69], v[22:23], v[22:23]
	v_add_f32_e32 v66, v66, v67
	v_add_f32_e32 v68, v68, v69
	v_add_f32_e32 v66, v68, v66
	v_add_f32_e32 v66, v70, v66
	v_add_f32_e32 v66, v87, v66
	ds_bpermute_b32 v67, v172, v66
	v_cvt_pk_bf16_f32 v62, v64, v65
	v_lshl_add_u64 v[64:65], s[8:9], 0, v[84:85]
	global_store_dwordx4 v[64:65], v[60:63], off
	s_nop 1
	v_permlane16_swap_b32_e32 v18, v22
	v_permlane16_swap_b32_e32 v19, v23
	v_permlane16_swap_b32_e32 v20, v24
	v_permlane16_swap_b32_e32 v21, v25
	v_permlane32_swap_b32_e32 v18, v22
	v_permlane32_swap_b32_e32 v19, v23
	v_permlane32_swap_b32_e32 v20, v24
	v_permlane32_swap_b32_e32 v21, v25
	v_sub_co_u32_e64 v232, s[98:99], v58, v189
	v_subbrev_co_u32_e64 v233, s[98:99], 0, v59, s[98:99]
	global_store_dwordx4 v[232:233], v[18:21], off offset:512
	global_store_dwordx4 v[232:233], v[22:25], off offset:576
	s_nop 1
	v_permlane32_swap_b32_e32 v18, v22
	v_permlane32_swap_b32_e32 v19, v23
	v_permlane32_swap_b32_e32 v20, v24
	v_permlane32_swap_b32_e32 v21, v25
	v_permlane16_swap_b32_e32 v18, v22
	v_permlane16_swap_b32_e32 v19, v23
	v_permlane16_swap_b32_e32 v20, v24
	v_permlane16_swap_b32_e32 v21, v25
	v_cvt_pk_bf16_f32 v58, v18, v19
	s_waitcnt lgkmcnt(0)
	v_add_f32_e32 v18, v66, v67
	ds_bpermute_b32 v19, v0, v18
	v_cvt_pk_bf16_f32 v59, v20, v21
	v_cvt_pk_bf16_f32 v60, v22, v23
	v_cvt_pk_bf16_f32 v61, v24, v25
	global_store_dwordx4 v[64:65], v[58:61], off offset:256
	s_and_saveexec_b64 s[22:23], vcc
	s_cbranch_execz .LBB0_1226
	v_lshlrev_b64 v[20:21], 6, v[56:57]
	v_lshl_add_u64 v[20:21], s[10:11], 0, v[20:21]
	v_lshl_add_u64 v[20:21], s[84:85], 2, v[20:21]
	s_lshl_b32 s34, s45, 2
	v_lshl_add_u64 v[20:21], v[20:21], 0, s[34:35]
	s_waitcnt lgkmcnt(0)
	v_add_f32_e32 v18, v18, v19
	global_store_dword v[20:21], v18, off
.LBB0_1226:
	s_or_b64 exec, exec, s[22:23]
	ds_read_b32 v18, v173 offset:704
	s_waitcnt vmcnt(7)
	v_and_b32_e32 v21, 0xffff0000, v30
	v_lshlrev_b32_e32 v22, 16, v31
	v_and_b32_e32 v23, 0xffff0000, v31
	v_and_b32_e32 v31, 0xffff0000, v33
	s_waitcnt lgkmcnt(0)
	v_pk_mul_f32 v[14:15], v[14:15], v[18:19] op_sel_hi:[1,0]
	v_pk_mul_f32 v[10:11], v[10:11], v[18:19] op_sel_hi:[1,0]
	v_mul_f32_e32 v14, 0xbfb8aa3b, v14
	v_mul_f32_e32 v10, 0xbfb8aa3b, v10
	v_exp_f32_e32 v14, v14
	v_exp_f32_e32 v10, v10
	v_pk_mul_f32 v[16:17], v[16:17], v[18:19] op_sel_hi:[1,0]
	v_pk_mul_f32 v[12:13], v[12:13], v[18:19] op_sel_hi:[1,0]
	v_mul_f32_e32 v15, 0xbfb8aa3b, v15
	v_add_f32_e32 v14, 1.0, v14
	v_add_f32_e32 v19, 1.0, v10
	v_mul_f32_e32 v16, 0xbfb8aa3b, v16
	v_mul_f32_e32 v12, 0xbfb8aa3b, v12
	v_mul_f32_e32 v17, 0xbfb8aa3b, v17
	v_rcp_f32_e32 v10, v14
	v_exp_f32_e32 v15, v15
	v_rcp_f32_e32 v14, v19
	v_exp_f32_e32 v16, v16
	v_exp_f32_e32 v19, v12
	v_exp_f32_e32 v17, v17
	v_mul_f32_e32 v11, 0xbfb8aa3b, v11
	v_mul_f32_e32 v13, 0xbfb8aa3b, v13
	v_exp_f32_e32 v20, v11
	v_add_f32_e32 v11, 1.0, v15
	v_add_f32_e32 v12, 1.0, v16
	v_add_f32_e32 v16, 1.0, v19
	v_exp_f32_e32 v19, v13
	v_add_f32_e32 v13, 1.0, v17
	v_rcp_f32_e32 v11, v11
	v_rcp_f32_e32 v12, v12
	v_rcp_f32_e32 v13, v13
	v_add_f32_e32 v15, 1.0, v20
	v_lshlrev_b32_e32 v20, 16, v30
	v_add_f32_e32 v17, 1.0, v19
	v_pk_fma_f32 v[12:13], v[12:13], v[22:23], v[48:49]
	v_pk_fma_f32 v[10:11], v[10:11], v[20:21], v[46:47]
	v_rcp_f32_e32 v16, v16
	v_rcp_f32_e32 v17, v17
	v_pk_mul_f32 v[20:21], v[12:13], v[12:13]
	v_pk_mul_f32 v[22:23], v[10:11], v[10:11]
	v_rcp_f32_e32 v15, v15
	v_add_f32_e32 v19, v22, v23
	v_add_f32_e32 v20, v20, v21
	v_add_f32_e32 v19, v19, v20
	v_lshlrev_b32_e32 v30, 16, v33
	v_pk_mul_f32 v[6:7], v[6:7], v[18:19] op_sel_hi:[1,0]
	v_pk_mul_f32 v[2:3], v[2:3], v[18:19] op_sel_hi:[1,0]
	v_lshlrev_b32_e32 v24, 16, v32
	v_and_b32_e32 v25, 0xffff0000, v32
	v_pk_fma_f32 v[16:17], v[16:17], v[30:31], v[44:45]
	v_mul_f32_e32 v6, 0xbfb8aa3b, v6
	v_mul_f32_e32 v2, 0xbfb8aa3b, v2
	v_pk_fma_f32 v[14:15], v[14:15], v[24:25], v[42:43]
	s_nop 1
	v_permlane16_swap_b32_e32 v10, v14
	v_permlane16_swap_b32_e32 v11, v15
	v_permlane16_swap_b32_e32 v12, v16
	v_permlane16_swap_b32_e32 v13, v17
	v_permlane32_swap_b32_e32 v10, v14
	v_permlane32_swap_b32_e32 v11, v15
	v_permlane32_swap_b32_e32 v12, v16
	v_permlane32_swap_b32_e32 v13, v17
	v_sub_co_u32_e64 v232, s[98:99], v52, v189
	v_subbrev_co_u32_e64 v233, s[98:99], 0, v53, s[98:99]
	global_store_dwordx4 v[232:233], v[10:13], off
	global_store_dwordx4 v[232:233], v[14:17], off offset:64
	s_nop 1
	v_permlane32_swap_b32_e32 v10, v14
	v_permlane32_swap_b32_e32 v11, v15
	v_permlane32_swap_b32_e32 v12, v16
	v_permlane32_swap_b32_e32 v13, v17
	v_permlane16_swap_b32_e32 v10, v14
	v_permlane16_swap_b32_e32 v11, v15
	v_permlane16_swap_b32_e32 v12, v16
	v_permlane16_swap_b32_e32 v13, v17
	v_pk_mul_f32 v[20:21], v[16:17], v[16:17]
	v_cvt_pk_bf16_f32 v10, v10, v11
	v_cvt_pk_bf16_f32 v11, v12, v13
	v_cvt_pk_bf16_f32 v13, v16, v17
	v_exp_f32_e32 v6, v6
	v_exp_f32_e32 v16, v2
	v_mul_f32_e32 v7, 0xbfb8aa3b, v7
	v_mul_f32_e32 v3, 0xbfb8aa3b, v3
	v_add_f32_e32 v2, 1.0, v6
	v_add_f32_e32 v6, 1.0, v16
	v_exp_f32_e32 v7, v7
	v_exp_f32_e32 v16, v3
	v_pk_mul_f32 v[8:9], v[8:9], v[18:19] op_sel_hi:[1,0]
	v_pk_mul_f32 v[4:5], v[4:5], v[18:19] op_sel_hi:[1,0]
	v_mul_f32_e32 v8, 0xbfb8aa3b, v8
	v_mul_f32_e32 v4, 0xbfb8aa3b, v4
	v_add_f32_e32 v3, 1.0, v7
	v_add_f32_e32 v7, 1.0, v16
	v_exp_f32_e32 v8, v8
	v_exp_f32_e32 v16, v4
	v_mul_f32_e32 v9, 0xbfb8aa3b, v9
	v_exp_f32_e32 v9, v9
	v_mul_f32_e32 v5, 0xbfb8aa3b, v5
	v_add_f32_e32 v4, 1.0, v8
	v_add_f32_e32 v8, 1.0, v16
	v_exp_f32_e32 v16, v5
	v_add_f32_e32 v5, 1.0, v9
	v_pk_mul_f32 v[22:23], v[14:15], v[14:15]
	v_rcp_f32_e32 v2, v2
	v_rcp_f32_e32 v3, v3
	v_rcp_f32_e32 v4, v4
	v_rcp_f32_e32 v5, v5
	v_add_f32_e32 v22, v22, v23
	v_add_f32_e32 v20, v20, v21
	v_add_f32_e32 v9, 1.0, v16
	v_add_f32_e32 v20, v22, v20
	v_rcp_f32_e32 v6, v6
	v_rcp_f32_e32 v7, v7
	v_rcp_f32_e32 v8, v8
	v_rcp_f32_e32 v9, v9
	v_add_f32_e32 v24, v19, v20
	s_waitcnt vmcnt(8)
	v_lshlrev_b32_e32 v16, 16, v26
	v_and_b32_e32 v17, 0xffff0000, v26
	v_lshlrev_b32_e32 v18, 16, v27
	v_and_b32_e32 v19, 0xffff0000, v27
	v_pk_fma_f32 v[4:5], v[4:5], v[18:19], v[40:41]
	v_pk_fma_f32 v[2:3], v[2:3], v[16:17], v[38:39]
	v_lshlrev_b32_e32 v20, 16, v28
	v_and_b32_e32 v21, 0xffff0000, v28
	v_lshlrev_b32_e32 v22, 16, v29
	v_and_b32_e32 v23, 0xffff0000, v29
	v_pk_mul_f32 v[16:17], v[4:5], v[4:5]
	v_pk_mul_f32 v[18:19], v[2:3], v[2:3]
	v_pk_fma_f32 v[8:9], v[8:9], v[22:23], v[36:37]
	v_pk_fma_f32 v[6:7], v[6:7], v[20:21], v[34:35]
	v_add_f32_e32 v18, v18, v19
	v_add_f32_e32 v16, v16, v17
	v_add_f32_e32 v20, v18, v16
	v_pk_mul_f32 v[16:17], v[8:9], v[8:9]
	v_pk_mul_f32 v[18:19], v[6:7], v[6:7]
	v_add_f32_e32 v16, v16, v17
	v_add_f32_e32 v18, v18, v19
	v_add_f32_e32 v16, v18, v16
	v_add_f32_e32 v16, v20, v16
	v_add_f32_e32 v16, v24, v16
	ds_bpermute_b32 v17, v172, v16
	v_cvt_pk_bf16_f32 v12, v14, v15
	v_lshl_add_u64 v[14:15], v[54:55], 1, s[8:9]
	global_store_dwordx4 v[14:15], v[10:13], off
	s_nop 1
	v_permlane16_swap_b32_e32 v2, v6
	v_permlane16_swap_b32_e32 v3, v7
	v_permlane16_swap_b32_e32 v4, v8
	v_permlane16_swap_b32_e32 v5, v9
	v_permlane32_swap_b32_e32 v2, v6
	v_permlane32_swap_b32_e32 v3, v7
	v_permlane32_swap_b32_e32 v4, v8
	v_permlane32_swap_b32_e32 v5, v9
	v_sub_co_u32_e64 v232, s[98:99], v52, v189
	v_subbrev_co_u32_e64 v233, s[98:99], 0, v53, s[98:99]
	global_store_dwordx4 v[232:233], v[2:5], off offset:512
	global_store_dwordx4 v[232:233], v[6:9], off offset:576
	s_nop 1
	v_permlane32_swap_b32_e32 v2, v6
	v_permlane32_swap_b32_e32 v3, v7
	v_permlane32_swap_b32_e32 v4, v8
	v_permlane32_swap_b32_e32 v5, v9
	v_permlane16_swap_b32_e32 v2, v6
	v_permlane16_swap_b32_e32 v3, v7
	v_permlane16_swap_b32_e32 v4, v8
	v_permlane16_swap_b32_e32 v5, v9
	v_cvt_pk_bf16_f32 v10, v2, v3
	s_waitcnt lgkmcnt(0)
	v_add_f32_e32 v2, v16, v17
	ds_bpermute_b32 v0, v0, v2
	v_cvt_pk_bf16_f32 v11, v4, v5
	v_cvt_pk_bf16_f32 v12, v6, v7
	v_cvt_pk_bf16_f32 v13, v8, v9
	global_store_dwordx4 v[14:15], v[10:13], off offset:256
	s_and_saveexec_b64 s[22:23], vcc
	s_cbranch_execz .LBB0_1201
	s_waitcnt lgkmcnt(0)
	v_add_f32_e32 v0, v2, v0
	v_lshlrev_b64 v[2:3], 6, v[50:51]
	v_lshl_add_u64 v[2:3], s[10:11], 0, v[2:3]
	v_lshl_add_u64 v[2:3], s[84:85], 2, v[2:3]
	s_lshl_b32 s34, s45, 2
	v_lshl_add_u64 v[2:3], v[2:3], 0, s[34:35]
	global_store_dword v[2:3], v0, off
	s_branch .LBB0_1201
